# Whole NSA inner loop body hand-written: compressed branch rewritten (S^T form, far groups without table lookups, DPP head-sum for importance), on top of the top-k and block-loop rewrites
# speedup vs baseline: 1.0452x; 1.0174x over previous
; #define LAS __attribute__((address_space(3)))
; __device__ __forceinline__ void nsa_quad_pre(int bg, int quad, const bf16_t* Q, const bf16_t* KV, const bf16_t* KCMP, const bf16_t* VCMPT, const float* GN, bf16_t* ONSA, ...
;     const int r16 = lane & 15, q4 = lane >> 4, b = bg >> 2, g = bg & 3, t0 = quad * 4;
;     const unsigned koff = (unsigned)(r16 * 64 + q4 * 8) * 2u, voffS = (unsigned)(r16 * SEQ + q4 * 8) * 2u, voffC = (unsigned)(r16 * 512 + q4 * 8) * 2u;
;     const char* KWb = (const char*)(KV + 4 * (size_t)MTOK * 256 + (size_t)bg * SEQ * 64); const char* VWb = (const char*)(KV + 5 * (size_t)MTOK * 256 + (size_t)bg * 64 * SEQ);
;     const char* KCb = (const char*)(KCMP + (size_t)bg * 512 * 64); const char* VCb = (const char*)(VCMPT + (size_t)bg * 64 * 512);
;     ...
;     const size_t qoff = (size_t)(b * SEQ + t0 + (r16 & 3)) * 1024 + (g * 4 + (r16 >> 2)) * 64 + q4 * 8;
;     { const bf16x8 a0 = *(const bf16x8*)(Q + qoff), a1 = *(const bf16x8*)(Q + qoff + 32); *(LAS bf16x8*)(qfw + lane * 8) = a0; *(LAS bf16x8*)(qfw + 512 + lane * 8) = a1; }
;     const LAS bf16_t* qf = qfw + lane * 8;
;     const LAS float* bt = btab + q4 * 1028;
;     const f32x4 z4 = {0.f, 0.f, 0.f, 0.f};
;     KFrag KF; VFrag VF; f32x4 sc[4];
;     const int w_lo = (t0 - 511 > 0 ? t0 - 511 : 0) >> 6, w_hi = t0 >> 6;
;     f32x4 oc[4] = {z4, z4, z4, z4};
;     const int tl = t0 + 3, nvmax = tl >= 31 ? ((tl - 31) >> 4) + 1 : 0, ngr = (nvmax + 63) >> 6;
;     if (ngr > 0) {
;         float ls[4] = {0.f, 0.f, 0.f, 0.f};
;         load_k(KF, KP_C(0));
;         for (int gr = 0; gr < ngr; ++gr) {
;             qk_scores(KF, qf, sc);
;             load_k(KF, KP_C(gr + 1 < ngr ? gr + 1 : 0));
;             cmp_sm1(sc, gr, t0, bt, ls, r16);
.LBB0_738:
	s_lshl_b32 s1, s3, 5
	s_sub_i32 s14, s1, s91
	s_and_b32 s0, s3, 1
	s_add_i32 s14, s14, 31
	s_add_i32 s1, s1, s91
	s_cmp_eq_u32 s0, 0
	s_cselect_b32 s18, s1, s14
	v_and_b32_e32 v232, 15, v184
	v_lshrrev_b32_e32 v233, 4, v184
	v_and_b32_e32 v234, 3, v232
	v_lshrrev_b32_e32 v235, 2, v232
	v_mul_u32_u24_e32 v173, 0x1010, v235
	ds_read_b32 v225, v173 offset:4096
	v_mov_b32_e32 v252, 0xf149f2ca
	v_lshl_add_u32 v253, v235, 3, v234
	v_lshlrev_b32_e32 v0, 4, v233
	v_lshl_add_u32 v174, v253, 7, v0
	v_add_u32_e32 v175, 0x1000, v174
	v_lshl_add_u32 v176, v232, 10, v0
	v_add_u32_e32 v177, 0x4000, v176
	v_add_u32_e32 v178, 0x8000, v176
	v_add_u32_e32 v179, 0xc000, v176
	v_lshlrev_b32_e32 v98, 7, v233
	v_sub_u32_e32 v172, v234, v98
	v_add_u32_e32 v172, 0xffffffe1, v172
	s_lshl_b32 s0, s80, 10
	s_add_i32 s0, s0, 56384
	v_lshlrev_b32_e32 v215, 11, v234
	v_lshl_add_u32 v215, v233, 5, v215
	v_add_u32_e32 v215, s0, v215
	s_lshl_b32 s0, s18, 6
	s_add_i32 s0, s0, s97
	s_add_i32 s0, s0, s80
	v_add_u32_e32 v253, s0, v234
	s_and_b32 s1, s88, 3
	s_lshl_b32 s1, s1, 2
	v_add_u32_e32 v98, s1, v235
	v_lshlrev_b32_e32 v98, 7, v98
	v_lshl_add_u32 v98, v253, 11, v98
	v_lshl_add_u32 v98, v233, 4, v98
	v_add_u32_e32 v99, 0x2000, v98
	s_add_u32 s70, s30, 0x29900000
	s_addc_u32 s71, s31, 0
	global_load_dwordx4 v[34:37], v98, s[70:71] offset:0
	global_load_dwordx4 v[38:41], v98, s[70:71] offset:64
	global_load_dwordx4 v[42:45], v99, s[70:71] offset:0
	global_load_dwordx4 v[46:49], v99, s[70:71] offset:64
	s_waitcnt lgkmcnt(0)
	s_lshr_b32 s15, s97, 13
	s_lshl_b32 s15, s15, 2
	s_and_b32 s1, s88, 3
	s_or_b32 s15, s15, s1
	s_lshl_b32 s15, s15, 16
	s_add_u32 s66, s30, 0x38110000
	s_addc_u32 s67, s31, 0
	s_add_u32 s66, s66, s15
	s_addc_u32 s67, s67, 0
	s_add_u32 s68, s30, 0x38210000
	s_addc_u32 s69, s31, 0
	s_add_u32 s68, s68, s15
	s_addc_u32 s69, s69, 0
	s_lshl_b32 s47, s18, 6
	s_add_i32 s47, s47, s80
	v_mov_b32_e32 v2, 0
	v_mov_b32_e32 v3, 0
	v_mov_b32_e32 v4, 0
	v_mov_b32_e32 v5, 0
	v_mov_b32_e32 v6, 0
	v_mov_b32_e32 v7, 0
	v_mov_b32_e32 v8, 0
	v_mov_b32_e32 v9, 0
	v_mov_b32_e32 v10, 0
	v_mov_b32_e32 v11, 0
	v_mov_b32_e32 v12, 0
	v_mov_b32_e32 v13, 0
	v_mov_b32_e32 v14, 0
	v_mov_b32_e32 v15, 0
	v_mov_b32_e32 v16, 0
	v_mov_b32_e32 v17, 0
	s_sub_i32 s0, s47, 28
	s_ashr_i32 s0, s0, 4
	s_add_i32 s0, s0, 64
	s_ashr_i32 s53, s0, 6
	s_cmp_gt_i32 s47, 27
	s_cselect_b32 s53, s53, 0
	s_cmp_lt_i32 s53, 1
	s_cbranch_scc1 .Lcmp_none_q0
	s_sub_i32 s0, s47, 2063
	s_ashr_i32 s52, s0, 10
	s_add_i32 s52, s52, 1
	s_max_i32 s52, s52, 0
	s_min_i32 s52, s52, s53
	v_add_u32_e32 v99, s47, v172
	v_and_b32_e32 v98, 15, v184
	v_mov_b32_e32 v170, 0
	s_mov_b32 s57, 0
	s_lshl_b32 s0, s57, 13
	s_add_u32 s70, s66, s0
	s_addc_u32 s71, s67, 0
	global_load_dwordx4 v[50:53], v174, s[70:71] offset:0
	global_load_dwordx4 v[54:57], v174, s[70:71] offset:64
	global_load_dwordx4 v[58:61], v174, s[70:71] offset:512
	global_load_dwordx4 v[62:65], v174, s[70:71] offset:576
	global_load_dwordx4 v[66:69], v175, s[70:71] offset:0
	global_load_dwordx4 v[70:73], v175, s[70:71] offset:64
	global_load_dwordx4 v[74:77], v175, s[70:71] offset:512
	global_load_dwordx4 v[78:81], v175, s[70:71] offset:576
	s_mov_b32 s57, 0
.Lcmp_top_q0p1:
	s_nop 1
	s_cmp_lt_i32 s57, s52
	s_cbranch_scc0 .Lcmp_gen_q0p1
	s_waitcnt vmcnt(0)
	v_mov_b32_e32 v228, v225
	v_mov_b32_e32 v229, v225
	v_mov_b32_e32 v230, v225
	v_mov_b32_e32 v231, v225
	s_nop 1
	v_mfma_f32_16x16x32_bf16 v[18:21], v[50:53], v[34:37], v[228:231]
	v_mfma_f32_16x16x32_bf16 v[18:21], v[54:57], v[38:41], v[18:21]
	v_mfma_f32_16x16x32_bf16 v[22:25], v[58:61], v[34:37], v[228:231]
	v_mfma_f32_16x16x32_bf16 v[22:25], v[62:65], v[38:41], v[22:25]
	v_mfma_f32_16x16x32_bf16 v[26:29], v[66:69], v[34:37], v[228:231]
	v_mfma_f32_16x16x32_bf16 v[26:29], v[70:73], v[38:41], v[26:29]
	v_mfma_f32_16x16x32_bf16 v[30:33], v[74:77], v[34:37], v[228:231]
	v_mfma_f32_16x16x32_bf16 v[30:33], v[78:81], v[38:41], v[30:33]
	s_add_i32 s1, s57, 1
	s_cmp_lt_i32 s1, s53
	s_cselect_b32 s1, s1, 0
	s_lshl_b32 s0, s1, 13
	s_add_u32 s70, s66, s0
	s_addc_u32 s71, s67, 0
	global_load_dwordx4 v[50:53], v174, s[70:71] offset:0
	global_load_dwordx4 v[54:57], v174, s[70:71] offset:64
	global_load_dwordx4 v[58:61], v174, s[70:71] offset:512
	global_load_dwordx4 v[62:65], v174, s[70:71] offset:576
	global_load_dwordx4 v[66:69], v175, s[70:71] offset:0
	global_load_dwordx4 v[70:73], v175, s[70:71] offset:64
	global_load_dwordx4 v[74:77], v175, s[70:71] offset:512
	global_load_dwordx4 v[78:81], v175, s[70:71] offset:576
	v_exp_f32_e32 v18, v18
	v_exp_f32_e32 v19, v19
	v_exp_f32_e32 v20, v20
	v_exp_f32_e32 v21, v21
	v_exp_f32_e32 v22, v22
	v_exp_f32_e32 v23, v23
	v_exp_f32_e32 v24, v24
	v_exp_f32_e32 v25, v25
	v_exp_f32_e32 v26, v26
	v_exp_f32_e32 v27, v27
	v_exp_f32_e32 v28, v28
	v_exp_f32_e32 v29, v29
	v_exp_f32_e32 v30, v30
	v_exp_f32_e32 v31, v31
	v_exp_f32_e32 v32, v32
	v_exp_f32_e32 v33, v33
	v_add_f32_e32 v170, v170, v18
	v_add_f32_e32 v170, v170, v19
	v_add_f32_e32 v170, v170, v20
	v_add_f32_e32 v170, v170, v21
	v_add_f32_e32 v170, v170, v22
	v_add_f32_e32 v170, v170, v23
	v_add_f32_e32 v170, v170, v24
	v_add_f32_e32 v170, v170, v25
	v_add_f32_e32 v170, v170, v26
	v_add_f32_e32 v170, v170, v27
	v_add_f32_e32 v170, v170, v28
	v_add_f32_e32 v170, v170, v29
	v_add_f32_e32 v170, v170, v30
	v_add_f32_e32 v170, v170, v31
	v_add_f32_e32 v170, v170, v32
	v_add_f32_e32 v170, v170, v33
	s_branch .Lcmp_nx_q0p1
; #define LAS __attribute__((address_space(3)))
; __device__ __forceinline__ float ex2(float x) { return __builtin_amdgcn_exp2f(x); }
; __device__ __forceinline__ void cmp_sm1(const f32x4 (&sc)[4], int gr, int t0, const LAS float* bt, float (&ls)[4], int r16) {
; #pragma unroll
;     for (int cc = 0; cc < 4; ++cc) {
;         const int cend = (gr * 64 + cc * 16 + r16) * 16 + 31;
; #pragma unroll
;         for (int i = 0; i < 4; ++i) { const int dist = t0 + i - cend; ls[i] += dist >= 0 ? ex2(sc[cc][i] + bt[clampd(dist)]) : 0.f; }
;     }
; __device__ __forceinline__ void nsa_quad_pre(int bg, int quad, const bf16_t* Q, const bf16_t* KV, const bf16_t* KCMP, const bf16_t* VCMPT, const float* GN, bf16_t* ONSA, ...
;     ...
;         for (int gr = 0; gr < ngr; ++gr) {
;             qk_scores(KF, qf, sc);
;             load_k(KF, KP_C(gr + 1 < ngr ? gr + 1 : 0));
;             cmp_sm1(sc, gr, t0, bt, ls, r16);
;         }
.Lcmp_gen_q0p1:
	s_nop 1
	s_waitcnt vmcnt(0)
	v_mfma_f32_16x16x32_bf16 v[18:21], v[50:53], v[34:37], 0
	v_mfma_f32_16x16x32_bf16 v[18:21], v[54:57], v[38:41], v[18:21]
	v_mfma_f32_16x16x32_bf16 v[22:25], v[58:61], v[34:37], 0
	v_mfma_f32_16x16x32_bf16 v[22:25], v[62:65], v[38:41], v[22:25]
	v_mfma_f32_16x16x32_bf16 v[26:29], v[66:69], v[34:37], 0
	v_mfma_f32_16x16x32_bf16 v[26:29], v[70:73], v[38:41], v[26:29]
	v_mfma_f32_16x16x32_bf16 v[30:33], v[74:77], v[34:37], 0
	v_mfma_f32_16x16x32_bf16 v[30:33], v[78:81], v[38:41], v[30:33]
	s_add_i32 s1, s57, 1
	s_cmp_lt_i32 s1, s53
	s_cselect_b32 s1, s1, 0
	s_lshl_b32 s0, s1, 13
	s_add_u32 s70, s66, s0
	s_addc_u32 s71, s67, 0
	global_load_dwordx4 v[50:53], v174, s[70:71] offset:0
	global_load_dwordx4 v[54:57], v174, s[70:71] offset:64
	global_load_dwordx4 v[58:61], v174, s[70:71] offset:512
	global_load_dwordx4 v[62:65], v174, s[70:71] offset:576
	global_load_dwordx4 v[66:69], v175, s[70:71] offset:0
	global_load_dwordx4 v[70:73], v175, s[70:71] offset:64
	global_load_dwordx4 v[74:77], v175, s[70:71] offset:512
	global_load_dwordx4 v[78:81], v175, s[70:71] offset:576
	s_lshl_b32 s0, s57, 10
	v_subrev_u32_e32 v224, s0, v99
	v_add_u32_e32 v232, 0x0, v224
	v_min_u32_e32 v232, 0x400, v232
	v_lshl_add_u32 v232, v232, 2, v173
	ds_read_b32 v216, v232
	v_add_u32_e32 v232, 0xfffffff0, v224
	v_min_u32_e32 v232, 0x400, v232
	v_lshl_add_u32 v232, v232, 2, v173
	ds_read_b32 v217, v232
	v_add_u32_e32 v232, 0xffffffe0, v224
	v_min_u32_e32 v232, 0x400, v232
	v_lshl_add_u32 v232, v232, 2, v173
	ds_read_b32 v218, v232
	v_add_u32_e32 v232, 0xffffffd0, v224
	v_min_u32_e32 v232, 0x400, v232
	v_lshl_add_u32 v232, v232, 2, v173
	ds_read_b32 v219, v232
	v_add_u32_e32 v232, 0xffffffc0, v224
	v_min_u32_e32 v232, 0x400, v232
	v_lshl_add_u32 v232, v232, 2, v173
	ds_read_b32 v220, v232
	v_add_u32_e32 v232, 0xffffffb0, v224
	v_min_u32_e32 v232, 0x400, v232
	v_lshl_add_u32 v232, v232, 2, v173
	ds_read_b32 v221, v232
	v_add_u32_e32 v232, 0xffffffa0, v224
	v_min_u32_e32 v232, 0x400, v232
	v_lshl_add_u32 v232, v232, 2, v173
	ds_read_b32 v222, v232
	v_add_u32_e32 v232, 0xffffff90, v224
	v_min_u32_e32 v232, 0x400, v232
	v_lshl_add_u32 v232, v232, 2, v173
	ds_read_b32 v223, v232
	s_waitcnt lgkmcnt(7)
	v_add_u32_e32 v232, 0x0, v224
	v_cmp_le_i32_e32 vcc, 0, v232
	s_nop 1
	v_cndmask_b32_e32 v216, v252, v216, vcc
	v_add_f32_e32 v18, v18, v216
	s_waitcnt lgkmcnt(6)
	v_add_u32_e32 v232, 0xfffffff0, v224
	v_cmp_le_i32_e32 vcc, 0, v232
	s_nop 1
	v_cndmask_b32_e32 v217, v252, v217, vcc
	v_add_f32_e32 v19, v19, v217
	s_waitcnt lgkmcnt(5)
	v_add_u32_e32 v232, 0xffffffe0, v224
	v_cmp_le_i32_e32 vcc, 0, v232
	s_nop 1
	v_cndmask_b32_e32 v218, v252, v218, vcc
	v_add_f32_e32 v20, v20, v218
	s_waitcnt lgkmcnt(4)
	v_add_u32_e32 v232, 0xffffffd0, v224
	v_cmp_le_i32_e32 vcc, 0, v232
	s_nop 1
	v_cndmask_b32_e32 v219, v252, v219, vcc
	v_add_f32_e32 v21, v21, v219
	s_waitcnt lgkmcnt(3)
	v_add_u32_e32 v232, 0xffffffc0, v224
	v_cmp_le_i32_e32 vcc, 0, v232
	s_nop 1
	v_cndmask_b32_e32 v220, v252, v220, vcc
	v_add_f32_e32 v22, v22, v220
	s_waitcnt lgkmcnt(2)
	v_add_u32_e32 v232, 0xffffffb0, v224
	v_cmp_le_i32_e32 vcc, 0, v232
	s_nop 1
	v_cndmask_b32_e32 v221, v252, v221, vcc
	v_add_f32_e32 v23, v23, v221
	s_waitcnt lgkmcnt(1)
	v_add_u32_e32 v232, 0xffffffa0, v224
	v_cmp_le_i32_e32 vcc, 0, v232
	s_nop 1
	v_cndmask_b32_e32 v222, v252, v222, vcc
	v_add_f32_e32 v24, v24, v222
	s_waitcnt lgkmcnt(0)
	v_add_u32_e32 v232, 0xffffff90, v224
	v_cmp_le_i32_e32 vcc, 0, v232
	s_nop 1
	v_cndmask_b32_e32 v223, v252, v223, vcc
	v_add_f32_e32 v25, v25, v223
	v_add_u32_e32 v232, 0xfffffe00, v224
	v_min_u32_e32 v232, 0x400, v232
	v_lshl_add_u32 v232, v232, 2, v173
	ds_read_b32 v216, v232
	v_add_u32_e32 v232, 0xfffffdf0, v224
	v_min_u32_e32 v232, 0x400, v232
	v_lshl_add_u32 v232, v232, 2, v173
	ds_read_b32 v217, v232
	v_add_u32_e32 v232, 0xfffffde0, v224
	v_min_u32_e32 v232, 0x400, v232
	v_lshl_add_u32 v232, v232, 2, v173
	ds_read_b32 v218, v232
	v_add_u32_e32 v232, 0xfffffdd0, v224
	v_min_u32_e32 v232, 0x400, v232
	v_lshl_add_u32 v232, v232, 2, v173
	ds_read_b32 v219, v232
	v_add_u32_e32 v232, 0xfffffdc0, v224
	v_min_u32_e32 v232, 0x400, v232
	v_lshl_add_u32 v232, v232, 2, v173
	ds_read_b32 v220, v232
	v_add_u32_e32 v232, 0xfffffdb0, v224
	v_min_u32_e32 v232, 0x400, v232
	v_lshl_add_u32 v232, v232, 2, v173
	ds_read_b32 v221, v232
	v_add_u32_e32 v232, 0xfffffda0, v224
	v_min_u32_e32 v232, 0x400, v232
	v_lshl_add_u32 v232, v232, 2, v173
	ds_read_b32 v222, v232
	v_add_u32_e32 v232, 0xfffffd90, v224
	v_min_u32_e32 v232, 0x400, v232
	v_lshl_add_u32 v232, v232, 2, v173
	ds_read_b32 v223, v232
	s_waitcnt lgkmcnt(7)
	v_add_u32_e32 v232, 0xfffffe00, v224
	v_cmp_le_i32_e32 vcc, 0, v232
	s_nop 1
	v_cndmask_b32_e32 v216, v252, v216, vcc
	v_add_f32_e32 v26, v26, v216
	s_waitcnt lgkmcnt(6)
	v_add_u32_e32 v232, 0xfffffdf0, v224
	v_cmp_le_i32_e32 vcc, 0, v232
	s_nop 1
	v_cndmask_b32_e32 v217, v252, v217, vcc
	v_add_f32_e32 v27, v27, v217
	s_waitcnt lgkmcnt(5)
	v_add_u32_e32 v232, 0xfffffde0, v224
	v_cmp_le_i32_e32 vcc, 0, v232
	s_nop 1
	v_cndmask_b32_e32 v218, v252, v218, vcc
	v_add_f32_e32 v28, v28, v218
	s_waitcnt lgkmcnt(4)
	v_add_u32_e32 v232, 0xfffffdd0, v224
	v_cmp_le_i32_e32 vcc, 0, v232
	s_nop 1
	v_cndmask_b32_e32 v219, v252, v219, vcc
	v_add_f32_e32 v29, v29, v219
	s_waitcnt lgkmcnt(3)
	v_add_u32_e32 v232, 0xfffffdc0, v224
	v_cmp_le_i32_e32 vcc, 0, v232
	s_nop 1
	v_cndmask_b32_e32 v220, v252, v220, vcc
	v_add_f32_e32 v30, v30, v220
	s_waitcnt lgkmcnt(2)
	v_add_u32_e32 v232, 0xfffffdb0, v224
	v_cmp_le_i32_e32 vcc, 0, v232
	s_nop 1
	v_cndmask_b32_e32 v221, v252, v221, vcc
	v_add_f32_e32 v31, v31, v221
	s_waitcnt lgkmcnt(1)
	v_add_u32_e32 v232, 0xfffffda0, v224
	v_cmp_le_i32_e32 vcc, 0, v232
	s_nop 1
	v_cndmask_b32_e32 v222, v252, v222, vcc
	v_add_f32_e32 v32, v32, v222
	s_waitcnt lgkmcnt(0)
	v_add_u32_e32 v232, 0xfffffd90, v224
	v_cmp_le_i32_e32 vcc, 0, v232
	s_nop 1
	v_cndmask_b32_e32 v223, v252, v223, vcc
	v_add_f32_e32 v33, v33, v223
	v_exp_f32_e32 v18, v18
	v_exp_f32_e32 v19, v19
	v_exp_f32_e32 v20, v20
	v_exp_f32_e32 v21, v21
	v_exp_f32_e32 v22, v22
	v_exp_f32_e32 v23, v23
	v_exp_f32_e32 v24, v24
	v_exp_f32_e32 v25, v25
	v_exp_f32_e32 v26, v26
	v_exp_f32_e32 v27, v27
	v_exp_f32_e32 v28, v28
	v_exp_f32_e32 v29, v29
	v_exp_f32_e32 v30, v30
	v_exp_f32_e32 v31, v31
	v_exp_f32_e32 v32, v32
	v_exp_f32_e32 v33, v33
	v_add_f32_e32 v170, v170, v18
	v_add_f32_e32 v170, v170, v19
	v_add_f32_e32 v170, v170, v20
	v_add_f32_e32 v170, v170, v21
	v_add_f32_e32 v170, v170, v22
	v_add_f32_e32 v170, v170, v23
	v_add_f32_e32 v170, v170, v24
	v_add_f32_e32 v170, v170, v25
	v_add_f32_e32 v170, v170, v26
	v_add_f32_e32 v170, v170, v27
	v_add_f32_e32 v170, v170, v28
	v_add_f32_e32 v170, v170, v29
	v_add_f32_e32 v170, v170, v30
	v_add_f32_e32 v170, v170, v31
	v_add_f32_e32 v170, v170, v32
	v_add_f32_e32 v170, v170, v33
; #define LAS __attribute__((address_space(3)))
; __device__ __forceinline__ bf16_t tobf(float x) { return (bf16_t)pk2(x, 0.f); }
; __device__ __forceinline__ float red16(float v) { v += __shfl_xor(v, 1); v += __shfl_xor(v, 2); v += __shfl_xor(v, 4); v += __shfl_xor(v, 8); return v; }
; __device__ __forceinline__ float ex2(float x) { return __builtin_amdgcn_exp2f(x); }
; __device__ __forceinline__ void cmp_sm2(const f32x4 (&sc)[4], int gr, int t0, const LAS float* bt, const float (&inv)[4], LAS bf16_t* Pb, LAS float* psum, int r16, int q4) {
; #pragma unroll
;     for (int cc = 0; cc < 4; ++cc) {
;         const int kk = gr * 64 + cc * 16 + r16, cend = kk * 16 + 31;
; #pragma unroll
;         for (int i = 0; i < 4; ++i) { const int dist = t0 + i - cend; float p = dist >= 0 ? ex2(sc[cc][i] + bt[clampd(dist)]) * inv[i] : 0.f;
;             Pb[(4 * q4 + i) * 72 + cc * 16 + r16] = tobf(p); p += __shfl_xor(p, 16); p += __shfl_xor(p, 32); if (q4 == 0) psum[i * 512 + kk] = p; }
;     }
; __device__ __forceinline__ void nsa_quad_pre(int bg, int quad, const bf16_t* Q, const bf16_t* KV, const bf16_t* KCMP, const bf16_t* VCMPT, const float* GN, bf16_t* ONSA, ...
;     ...
;         float inv[4];
; #pragma unroll
;         for (int i = 0; i < 4; ++i) { const float l = red16(ls[i]); inv[i] = l > 0.f ? 1.f / l : 0.f; }
;         for (int gr = 0; gr < ngr; ++gr) {
;             const bool more = gr + 1 < ngr;
;             qk_scores(KF, qf, sc);
;             if (more) load_k(KF, KP_C(gr + 1));
;             cmp_sm2(sc, gr, t0, bt, inv, Pb, psum, r16, q4);
;             pv_step(VF, oc, Pb, r16, q4);
;             if (more) load_v(VF, VP_C(gr + 1));
.Lcmp_nx_q0p1:
	s_nop 1
	s_add_i32 s57, s57, 1
	s_cmp_lt_i32 s57, s53
	s_cbranch_scc1 .Lcmp_top_q0p1
	v_xor_b32_e32 v232, 16, v184
	v_lshlrev_b32_e32 v232, 2, v232
	v_xor_b32_e32 v233, 32, v184
	v_lshlrev_b32_e32 v233, 2, v233
	ds_bpermute_b32 v234, v232, v170
	s_waitcnt lgkmcnt(0)
	v_add_f32_e32 v170, v170, v234
	ds_bpermute_b32 v234, v233, v170
	s_waitcnt lgkmcnt(0)
	v_add_f32_e32 v170, v170, v234
	v_mov_b32_e32 v0, 1.0
	v_div_scale_f32 v232, s[20:21], v170, v170, v0
	v_rcp_f32_e32 v233, v232
	v_div_scale_f32 v234, vcc, v0, v170, v0
	v_fma_f32 v235, -v232, v233, 1.0
	v_fmac_f32_e32 v233, v235, v233
	v_mul_f32_e32 v235, v234, v233
	v_fma_f32 v253, -v232, v235, v234
	v_fmac_f32_e32 v235, v253, v233
	v_fma_f32 v232, -v232, v235, v234
	s_nop 1
	v_div_fmas_f32 v232, v232, v233, v235
	v_div_fixup_f32 v171, v232, v170, v0
	v_cmp_lt_f32_e32 vcc, 0, v170
	s_nop 1
	v_cndmask_b32_e32 v171, 0, v171, vcc
	s_mov_b32 s57, 0
.Lcmp_top_q0p2:
	s_nop 1
	s_cmp_lt_i32 s57, s52
	s_cbranch_scc0 .Lcmp_gen_q0p2
	s_lshl_b32 s0, s57, 7
	s_add_u32 s14, s68, s0
	s_addc_u32 s15, s69, 0
	global_load_dwordx4 v[82:85], v176, s[14:15] offset:0
	global_load_dwordx4 v[86:89], v176, s[14:15] offset:64
	global_load_dwordx4 v[90:93], v177, s[14:15] offset:0
	global_load_dwordx4 v[94:97], v177, s[14:15] offset:64
	global_load_dwordx4 v[236:239], v178, s[14:15] offset:0
	global_load_dwordx4 v[240:243], v178, s[14:15] offset:64
	global_load_dwordx4 v[244:247], v179, s[14:15] offset:0
	global_load_dwordx4 v[248:251], v179, s[14:15] offset:64
	s_waitcnt vmcnt(8)
	v_mov_b32_e32 v228, v225
	v_mov_b32_e32 v229, v225
	v_mov_b32_e32 v230, v225
	v_mov_b32_e32 v231, v225
	s_nop 1
	v_mfma_f32_16x16x32_bf16 v[18:21], v[50:53], v[34:37], v[228:231]
	v_mfma_f32_16x16x32_bf16 v[18:21], v[54:57], v[38:41], v[18:21]
	v_mfma_f32_16x16x32_bf16 v[22:25], v[58:61], v[34:37], v[228:231]
	v_mfma_f32_16x16x32_bf16 v[22:25], v[62:65], v[38:41], v[22:25]
	v_mfma_f32_16x16x32_bf16 v[26:29], v[66:69], v[34:37], v[228:231]
	v_mfma_f32_16x16x32_bf16 v[26:29], v[70:73], v[38:41], v[26:29]
	v_mfma_f32_16x16x32_bf16 v[30:33], v[74:77], v[34:37], v[228:231]
	v_mfma_f32_16x16x32_bf16 v[30:33], v[78:81], v[38:41], v[30:33]
	s_nop 1
	v_exp_f32_e32 v18, v18
	v_exp_f32_e32 v19, v19
	v_exp_f32_e32 v20, v20
	v_exp_f32_e32 v21, v21
	v_exp_f32_e32 v22, v22
	v_exp_f32_e32 v23, v23
	v_exp_f32_e32 v24, v24
	v_exp_f32_e32 v25, v25
	v_exp_f32_e32 v26, v26
	v_exp_f32_e32 v27, v27
	v_exp_f32_e32 v28, v28
	v_exp_f32_e32 v29, v29
	v_exp_f32_e32 v30, v30
	v_exp_f32_e32 v31, v31
	v_exp_f32_e32 v32, v32
	v_exp_f32_e32 v33, v33
	v_mul_f32_e32 v18, v18, v171
	v_mul_f32_e32 v19, v19, v171
	v_mul_f32_e32 v20, v20, v171
	v_mul_f32_e32 v21, v21, v171
	v_mul_f32_e32 v22, v22, v171
	v_mul_f32_e32 v23, v23, v171
	v_mul_f32_e32 v24, v24, v171
	v_mul_f32_e32 v25, v25, v171
	v_mul_f32_e32 v26, v26, v171
	v_mul_f32_e32 v27, v27, v171
	v_mul_f32_e32 v28, v28, v171
	v_mul_f32_e32 v29, v29, v171
	v_mul_f32_e32 v30, v30, v171
	v_mul_f32_e32 v31, v31, v171
	v_mul_f32_e32 v32, v32, v171
	v_mul_f32_e32 v33, v33, v171
	v_add_f32_dpp v50, v18, v18 row_shr:4 row_mask:0xf bank_mask:0xf
	v_add_f32_dpp v51, v19, v19 row_shr:4 row_mask:0xf bank_mask:0xf
	v_add_f32_dpp v52, v20, v20 row_shr:4 row_mask:0xf bank_mask:0xf
	v_add_f32_dpp v53, v21, v21 row_shr:4 row_mask:0xf bank_mask:0xf
	v_add_f32_dpp v54, v22, v22 row_shr:4 row_mask:0xf bank_mask:0xf
	v_add_f32_dpp v55, v23, v23 row_shr:4 row_mask:0xf bank_mask:0xf
	v_add_f32_dpp v56, v24, v24 row_shr:4 row_mask:0xf bank_mask:0xf
	v_add_f32_dpp v57, v25, v25 row_shr:4 row_mask:0xf bank_mask:0xf
	v_add_f32_dpp v58, v26, v26 row_shr:4 row_mask:0xf bank_mask:0xf
	v_add_f32_dpp v59, v27, v27 row_shr:4 row_mask:0xf bank_mask:0xf
	v_add_f32_dpp v60, v28, v28 row_shr:4 row_mask:0xf bank_mask:0xf
	v_add_f32_dpp v61, v29, v29 row_shr:4 row_mask:0xf bank_mask:0xf
	v_add_f32_dpp v62, v30, v30 row_shr:4 row_mask:0xf bank_mask:0xf
	v_add_f32_dpp v63, v31, v31 row_shr:4 row_mask:0xf bank_mask:0xf
	v_add_f32_dpp v64, v32, v32 row_shr:4 row_mask:0xf bank_mask:0xf
	v_add_f32_dpp v65, v33, v33 row_shr:4 row_mask:0xf bank_mask:0xf
	v_add_f32_dpp v50, v50, v50 row_shr:8 row_mask:0xf bank_mask:0xf
	v_add_f32_dpp v51, v51, v51 row_shr:8 row_mask:0xf bank_mask:0xf
	v_add_f32_dpp v52, v52, v52 row_shr:8 row_mask:0xf bank_mask:0xf
	v_add_f32_dpp v53, v53, v53 row_shr:8 row_mask:0xf bank_mask:0xf
	v_add_f32_dpp v54, v54, v54 row_shr:8 row_mask:0xf bank_mask:0xf
	v_add_f32_dpp v55, v55, v55 row_shr:8 row_mask:0xf bank_mask:0xf
	v_add_f32_dpp v56, v56, v56 row_shr:8 row_mask:0xf bank_mask:0xf
	v_add_f32_dpp v57, v57, v57 row_shr:8 row_mask:0xf bank_mask:0xf
	v_add_f32_dpp v58, v58, v58 row_shr:8 row_mask:0xf bank_mask:0xf
	v_add_f32_dpp v59, v59, v59 row_shr:8 row_mask:0xf bank_mask:0xf
	v_add_f32_dpp v60, v60, v60 row_shr:8 row_mask:0xf bank_mask:0xf
	v_add_f32_dpp v61, v61, v61 row_shr:8 row_mask:0xf bank_mask:0xf
	v_add_f32_dpp v62, v62, v62 row_shr:8 row_mask:0xf bank_mask:0xf
	v_add_f32_dpp v63, v63, v63 row_shr:8 row_mask:0xf bank_mask:0xf
	v_add_f32_dpp v64, v64, v64 row_shr:8 row_mask:0xf bank_mask:0xf
	v_add_f32_dpp v65, v65, v65 row_shr:8 row_mask:0xf bank_mask:0xf
	s_lshl_b32 s0, s57, 8
	v_add_u32_e32 v232, s0, v215
	v_cmp_lt_u32_e32 vcc, 11, v98
	s_nop 0
	s_and_saveexec_b64 s[20:21], vcc
	ds_write_b128 v232, v[50:53] offset:0
	ds_write_b128 v232, v[54:57] offset:16
	ds_write_b128 v232, v[58:61] offset:128
	ds_write_b128 v232, v[62:65] offset:144
	s_or_b64 exec, exec, s[20:21]
	v_cvt_pk_bf16_f32 v216, v18, v19
	v_cvt_pk_bf16_f32 v217, v20, v21
	v_cvt_pk_bf16_f32 v218, v22, v23
	v_cvt_pk_bf16_f32 v219, v24, v25
	v_cvt_pk_bf16_f32 v220, v26, v27
	v_cvt_pk_bf16_f32 v221, v28, v29
	v_cvt_pk_bf16_f32 v222, v30, v31
	v_cvt_pk_bf16_f32 v223, v32, v33
	s_add_i32 s1, s57, 1
	s_cmp_lt_i32 s1, s53
	s_cbranch_scc0 .Lcmp_nok_q0p2f
	s_waitcnt lgkmcnt(0)
	s_lshl_b32 s0, s1, 13
	s_add_u32 s70, s66, s0
	s_addc_u32 s71, s67, 0
	global_load_dwordx4 v[50:53], v174, s[70:71] offset:0
	global_load_dwordx4 v[54:57], v174, s[70:71] offset:64
	global_load_dwordx4 v[58:61], v174, s[70:71] offset:512
	global_load_dwordx4 v[62:65], v174, s[70:71] offset:576
	global_load_dwordx4 v[66:69], v175, s[70:71] offset:0
	global_load_dwordx4 v[70:73], v175, s[70:71] offset:64
	global_load_dwordx4 v[74:77], v175, s[70:71] offset:512
	global_load_dwordx4 v[78:81], v175, s[70:71] offset:576
	s_waitcnt vmcnt(8)
	s_branch .Lcmp_kj_q0p2f
; #define LAS __attribute__((address_space(3)))
; __device__ __forceinline__ bf16_t tobf(float x) { return (bf16_t)pk2(x, 0.f); }
; __device__ __forceinline__ float ex2(float x) { return __builtin_amdgcn_exp2f(x); }
; __device__ __forceinline__ void cmp_sm2(const f32x4 (&sc)[4], int gr, int t0, const LAS float* bt, const float (&inv)[4], LAS bf16_t* Pb, LAS float* psum, int r16, int q4) {
; #pragma unroll
;     for (int cc = 0; cc < 4; ++cc) {
;         const int kk = gr * 64 + cc * 16 + r16, cend = kk * 16 + 31;
; #pragma unroll
;         for (int i = 0; i < 4; ++i) { const int dist = t0 + i - cend; float p = dist >= 0 ? ex2(sc[cc][i] + bt[clampd(dist)]) * inv[i] : 0.f;
;             Pb[(4 * q4 + i) * 72 + cc * 16 + r16] = tobf(p); p += __shfl_xor(p, 16); p += __shfl_xor(p, 32); if (q4 == 0) psum[i * 512 + kk] = p; }
;     }
; __device__ __forceinline__ void nsa_quad_pre(int bg, int quad, const bf16_t* Q, const bf16_t* KV, const bf16_t* KCMP, const bf16_t* VCMPT, const float* GN, bf16_t* ONSA, ...
;     ...
;         for (int gr = 0; gr < ngr; ++gr) {
;             const bool more = gr + 1 < ngr;
;             qk_scores(KF, qf, sc);
;             if (more) load_k(KF, KP_C(gr + 1));
;             cmp_sm2(sc, gr, t0, bt, inv, Pb, psum, r16, q4);
;             pv_step(VF, oc, Pb, r16, q4);
;             if (more) load_v(VF, VP_C(gr + 1));
.Lcmp_nok_q0p2f:
	s_nop 1
	s_waitcnt vmcnt(0)
	s_waitcnt lgkmcnt(0)
.Lcmp_kj_q0p2f:
	s_nop 1
	v_mfma_f32_16x16x32_bf16 v[2:5], v[82:85], v[216:219], v[2:5]
	v_mfma_f32_16x16x32_bf16 v[2:5], v[86:89], v[220:223], v[2:5]
	v_mfma_f32_16x16x32_bf16 v[6:9], v[90:93], v[216:219], v[6:9]
	v_mfma_f32_16x16x32_bf16 v[6:9], v[94:97], v[220:223], v[6:9]
	v_mfma_f32_16x16x32_bf16 v[10:13], v[236:239], v[216:219], v[10:13]
	v_mfma_f32_16x16x32_bf16 v[10:13], v[240:243], v[220:223], v[10:13]
	v_mfma_f32_16x16x32_bf16 v[14:17], v[244:247], v[216:219], v[14:17]
	v_mfma_f32_16x16x32_bf16 v[14:17], v[248:251], v[220:223], v[14:17]
	s_branch .Lcmp_nx_q0p2
.Lcmp_gen_q0p2:
	s_nop 1
	s_lshl_b32 s0, s57, 7
	s_add_u32 s14, s68, s0
	s_addc_u32 s15, s69, 0
	global_load_dwordx4 v[82:85], v176, s[14:15] offset:0
	global_load_dwordx4 v[86:89], v176, s[14:15] offset:64
	global_load_dwordx4 v[90:93], v177, s[14:15] offset:0
	global_load_dwordx4 v[94:97], v177, s[14:15] offset:64
	global_load_dwordx4 v[236:239], v178, s[14:15] offset:0
	global_load_dwordx4 v[240:243], v178, s[14:15] offset:64
	global_load_dwordx4 v[244:247], v179, s[14:15] offset:0
	global_load_dwordx4 v[248:251], v179, s[14:15] offset:64
	s_waitcnt vmcnt(8)
	v_mfma_f32_16x16x32_bf16 v[18:21], v[50:53], v[34:37], 0
	v_mfma_f32_16x16x32_bf16 v[18:21], v[54:57], v[38:41], v[18:21]
	v_mfma_f32_16x16x32_bf16 v[22:25], v[58:61], v[34:37], 0
	v_mfma_f32_16x16x32_bf16 v[22:25], v[62:65], v[38:41], v[22:25]
	v_mfma_f32_16x16x32_bf16 v[26:29], v[66:69], v[34:37], 0
	v_mfma_f32_16x16x32_bf16 v[26:29], v[70:73], v[38:41], v[26:29]
	v_mfma_f32_16x16x32_bf16 v[30:33], v[74:77], v[34:37], 0
	v_mfma_f32_16x16x32_bf16 v[30:33], v[78:81], v[38:41], v[30:33]
	s_lshl_b32 s0, s57, 10
	v_subrev_u32_e32 v224, s0, v99
	v_add_u32_e32 v232, 0x0, v224
	v_min_u32_e32 v232, 0x400, v232
	v_lshl_add_u32 v232, v232, 2, v173
	ds_read_b32 v216, v232
	v_add_u32_e32 v232, 0xfffffff0, v224
	v_min_u32_e32 v232, 0x400, v232
	v_lshl_add_u32 v232, v232, 2, v173
	ds_read_b32 v217, v232
	v_add_u32_e32 v232, 0xffffffe0, v224
	v_min_u32_e32 v232, 0x400, v232
	v_lshl_add_u32 v232, v232, 2, v173
	ds_read_b32 v218, v232
	v_add_u32_e32 v232, 0xffffffd0, v224
	v_min_u32_e32 v232, 0x400, v232
	v_lshl_add_u32 v232, v232, 2, v173
	ds_read_b32 v219, v232
	v_add_u32_e32 v232, 0xffffffc0, v224
	v_min_u32_e32 v232, 0x400, v232
	v_lshl_add_u32 v232, v232, 2, v173
	ds_read_b32 v220, v232
	v_add_u32_e32 v232, 0xffffffb0, v224
	v_min_u32_e32 v232, 0x400, v232
	v_lshl_add_u32 v232, v232, 2, v173
	ds_read_b32 v221, v232
	v_add_u32_e32 v232, 0xffffffa0, v224
	v_min_u32_e32 v232, 0x400, v232
	v_lshl_add_u32 v232, v232, 2, v173
	ds_read_b32 v222, v232
	v_add_u32_e32 v232, 0xffffff90, v224
	v_min_u32_e32 v232, 0x400, v232
	v_lshl_add_u32 v232, v232, 2, v173
	ds_read_b32 v223, v232
	s_waitcnt lgkmcnt(7)
	v_add_u32_e32 v232, 0x0, v224
	v_cmp_le_i32_e32 vcc, 0, v232
	s_nop 1
	v_cndmask_b32_e32 v216, v252, v216, vcc
	v_add_f32_e32 v18, v18, v216
	s_waitcnt lgkmcnt(6)
	v_add_u32_e32 v232, 0xfffffff0, v224
	v_cmp_le_i32_e32 vcc, 0, v232
	s_nop 1
	v_cndmask_b32_e32 v217, v252, v217, vcc
	v_add_f32_e32 v19, v19, v217
	s_waitcnt lgkmcnt(5)
	v_add_u32_e32 v232, 0xffffffe0, v224
	v_cmp_le_i32_e32 vcc, 0, v232
	s_nop 1
	v_cndmask_b32_e32 v218, v252, v218, vcc
	v_add_f32_e32 v20, v20, v218
	s_waitcnt lgkmcnt(4)
	v_add_u32_e32 v232, 0xffffffd0, v224
	v_cmp_le_i32_e32 vcc, 0, v232
	s_nop 1
	v_cndmask_b32_e32 v219, v252, v219, vcc
	v_add_f32_e32 v21, v21, v219
	s_waitcnt lgkmcnt(3)
	v_add_u32_e32 v232, 0xffffffc0, v224
	v_cmp_le_i32_e32 vcc, 0, v232
	s_nop 1
	v_cndmask_b32_e32 v220, v252, v220, vcc
	v_add_f32_e32 v22, v22, v220
	s_waitcnt lgkmcnt(2)
	v_add_u32_e32 v232, 0xffffffb0, v224
	v_cmp_le_i32_e32 vcc, 0, v232
	s_nop 1
	v_cndmask_b32_e32 v221, v252, v221, vcc
	v_add_f32_e32 v23, v23, v221
	s_waitcnt lgkmcnt(1)
	v_add_u32_e32 v232, 0xffffffa0, v224
	v_cmp_le_i32_e32 vcc, 0, v232
	s_nop 1
	v_cndmask_b32_e32 v222, v252, v222, vcc
	v_add_f32_e32 v24, v24, v222
	s_waitcnt lgkmcnt(0)
	v_add_u32_e32 v232, 0xffffff90, v224
	v_cmp_le_i32_e32 vcc, 0, v232
	s_nop 1
	v_cndmask_b32_e32 v223, v252, v223, vcc
	v_add_f32_e32 v25, v25, v223
	v_add_u32_e32 v232, 0xfffffe00, v224
	v_min_u32_e32 v232, 0x400, v232
	v_lshl_add_u32 v232, v232, 2, v173
	ds_read_b32 v216, v232
	v_add_u32_e32 v232, 0xfffffdf0, v224
	v_min_u32_e32 v232, 0x400, v232
	v_lshl_add_u32 v232, v232, 2, v173
	ds_read_b32 v217, v232
	v_add_u32_e32 v232, 0xfffffde0, v224
	v_min_u32_e32 v232, 0x400, v232
	v_lshl_add_u32 v232, v232, 2, v173
	ds_read_b32 v218, v232
	v_add_u32_e32 v232, 0xfffffdd0, v224
	v_min_u32_e32 v232, 0x400, v232
	v_lshl_add_u32 v232, v232, 2, v173
	ds_read_b32 v219, v232
	v_add_u32_e32 v232, 0xfffffdc0, v224
	v_min_u32_e32 v232, 0x400, v232
	v_lshl_add_u32 v232, v232, 2, v173
	ds_read_b32 v220, v232
	v_add_u32_e32 v232, 0xfffffdb0, v224
	v_min_u32_e32 v232, 0x400, v232
	v_lshl_add_u32 v232, v232, 2, v173
	ds_read_b32 v221, v232
	v_add_u32_e32 v232, 0xfffffda0, v224
	v_min_u32_e32 v232, 0x400, v232
	v_lshl_add_u32 v232, v232, 2, v173
	ds_read_b32 v222, v232
	v_add_u32_e32 v232, 0xfffffd90, v224
	v_min_u32_e32 v232, 0x400, v232
	v_lshl_add_u32 v232, v232, 2, v173
	ds_read_b32 v223, v232
	s_waitcnt lgkmcnt(7)
	v_add_u32_e32 v232, 0xfffffe00, v224
	v_cmp_le_i32_e32 vcc, 0, v232
	s_nop 1
	v_cndmask_b32_e32 v216, v252, v216, vcc
	v_add_f32_e32 v26, v26, v216
	s_waitcnt lgkmcnt(6)
; #define LAS __attribute__((address_space(3)))
; __device__ __forceinline__ bf16_t tobf(float x) { return (bf16_t)pk2(x, 0.f); }
; __device__ __forceinline__ float ex2(float x) { return __builtin_amdgcn_exp2f(x); }
; __device__ __forceinline__ void cmp_sm2(const f32x4 (&sc)[4], int gr, int t0, const LAS float* bt, const float (&inv)[4], LAS bf16_t* Pb, LAS float* psum, int r16, int q4) {
; #pragma unroll
;     for (int cc = 0; cc < 4; ++cc) {
;         const int kk = gr * 64 + cc * 16 + r16, cend = kk * 16 + 31;
; #pragma unroll
;         for (int i = 0; i < 4; ++i) { const int dist = t0 + i - cend; float p = dist >= 0 ? ex2(sc[cc][i] + bt[clampd(dist)]) * inv[i] : 0.f;
;             Pb[(4 * q4 + i) * 72 + cc * 16 + r16] = tobf(p); p += __shfl_xor(p, 16); p += __shfl_xor(p, 32); if (q4 == 0) psum[i * 512 + kk] = p; }
;     }
; __device__ __forceinline__ void nsa_quad_pre(int bg, int quad, const bf16_t* Q, const bf16_t* KV, const bf16_t* KCMP, const bf16_t* VCMPT, const float* GN, bf16_t* ONSA, ...
;     ...
;         for (int gr = 0; gr < ngr; ++gr) {
;             const bool more = gr + 1 < ngr;
;             qk_scores(KF, qf, sc);
;             if (more) load_k(KF, KP_C(gr + 1));
;             cmp_sm2(sc, gr, t0, bt, inv, Pb, psum, r16, q4);
;             pv_step(VF, oc, Pb, r16, q4);
;             if (more) load_v(VF, VP_C(gr + 1));
	v_add_u32_e32 v232, 0xfffffdf0, v224
	v_cmp_le_i32_e32 vcc, 0, v232
	s_nop 1
	v_cndmask_b32_e32 v217, v252, v217, vcc
	v_add_f32_e32 v27, v27, v217
	s_waitcnt lgkmcnt(5)
	v_add_u32_e32 v232, 0xfffffde0, v224
	v_cmp_le_i32_e32 vcc, 0, v232
	s_nop 1
	v_cndmask_b32_e32 v218, v252, v218, vcc
	v_add_f32_e32 v28, v28, v218
	s_waitcnt lgkmcnt(4)
	v_add_u32_e32 v232, 0xfffffdd0, v224
	v_cmp_le_i32_e32 vcc, 0, v232
	s_nop 1
	v_cndmask_b32_e32 v219, v252, v219, vcc
	v_add_f32_e32 v29, v29, v219
	s_waitcnt lgkmcnt(3)
	v_add_u32_e32 v232, 0xfffffdc0, v224
	v_cmp_le_i32_e32 vcc, 0, v232
	s_nop 1
	v_cndmask_b32_e32 v220, v252, v220, vcc
	v_add_f32_e32 v30, v30, v220
	s_waitcnt lgkmcnt(2)
	v_add_u32_e32 v232, 0xfffffdb0, v224
	v_cmp_le_i32_e32 vcc, 0, v232
	s_nop 1
	v_cndmask_b32_e32 v221, v252, v221, vcc
	v_add_f32_e32 v31, v31, v221
	s_waitcnt lgkmcnt(1)
	v_add_u32_e32 v232, 0xfffffda0, v224
	v_cmp_le_i32_e32 vcc, 0, v232
	s_nop 1
	v_cndmask_b32_e32 v222, v252, v222, vcc
	v_add_f32_e32 v32, v32, v222
	s_waitcnt lgkmcnt(0)
	v_add_u32_e32 v232, 0xfffffd90, v224
	v_cmp_le_i32_e32 vcc, 0, v232
	s_nop 1
	v_cndmask_b32_e32 v223, v252, v223, vcc
	v_add_f32_e32 v33, v33, v223
	v_exp_f32_e32 v18, v18
	v_exp_f32_e32 v19, v19
	v_exp_f32_e32 v20, v20
	v_exp_f32_e32 v21, v21
	v_exp_f32_e32 v22, v22
	v_exp_f32_e32 v23, v23
	v_exp_f32_e32 v24, v24
	v_exp_f32_e32 v25, v25
	v_exp_f32_e32 v26, v26
	v_exp_f32_e32 v27, v27
	v_exp_f32_e32 v28, v28
	v_exp_f32_e32 v29, v29
	v_exp_f32_e32 v30, v30
	v_exp_f32_e32 v31, v31
	v_exp_f32_e32 v32, v32
	v_exp_f32_e32 v33, v33
	v_mul_f32_e32 v18, v18, v171
	v_mul_f32_e32 v19, v19, v171
	v_mul_f32_e32 v20, v20, v171
	v_mul_f32_e32 v21, v21, v171
	v_mul_f32_e32 v22, v22, v171
	v_mul_f32_e32 v23, v23, v171
	v_mul_f32_e32 v24, v24, v171
	v_mul_f32_e32 v25, v25, v171
	v_mul_f32_e32 v26, v26, v171
	v_mul_f32_e32 v27, v27, v171
	v_mul_f32_e32 v28, v28, v171
	v_mul_f32_e32 v29, v29, v171
	v_mul_f32_e32 v30, v30, v171
	v_mul_f32_e32 v31, v31, v171
	v_mul_f32_e32 v32, v32, v171
	v_mul_f32_e32 v33, v33, v171
	v_add_f32_dpp v50, v18, v18 row_shr:4 row_mask:0xf bank_mask:0xf
	v_add_f32_dpp v51, v19, v19 row_shr:4 row_mask:0xf bank_mask:0xf
	v_add_f32_dpp v52, v20, v20 row_shr:4 row_mask:0xf bank_mask:0xf
	v_add_f32_dpp v53, v21, v21 row_shr:4 row_mask:0xf bank_mask:0xf
	v_add_f32_dpp v54, v22, v22 row_shr:4 row_mask:0xf bank_mask:0xf
	v_add_f32_dpp v55, v23, v23 row_shr:4 row_mask:0xf bank_mask:0xf
	v_add_f32_dpp v56, v24, v24 row_shr:4 row_mask:0xf bank_mask:0xf
	v_add_f32_dpp v57, v25, v25 row_shr:4 row_mask:0xf bank_mask:0xf
	v_add_f32_dpp v58, v26, v26 row_shr:4 row_mask:0xf bank_mask:0xf
	v_add_f32_dpp v59, v27, v27 row_shr:4 row_mask:0xf bank_mask:0xf
	v_add_f32_dpp v60, v28, v28 row_shr:4 row_mask:0xf bank_mask:0xf
	v_add_f32_dpp v61, v29, v29 row_shr:4 row_mask:0xf bank_mask:0xf
	v_add_f32_dpp v62, v30, v30 row_shr:4 row_mask:0xf bank_mask:0xf
	v_add_f32_dpp v63, v31, v31 row_shr:4 row_mask:0xf bank_mask:0xf
	v_add_f32_dpp v64, v32, v32 row_shr:4 row_mask:0xf bank_mask:0xf
	v_add_f32_dpp v65, v33, v33 row_shr:4 row_mask:0xf bank_mask:0xf
	v_add_f32_dpp v50, v50, v50 row_shr:8 row_mask:0xf bank_mask:0xf
	v_add_f32_dpp v51, v51, v51 row_shr:8 row_mask:0xf bank_mask:0xf
	v_add_f32_dpp v52, v52, v52 row_shr:8 row_mask:0xf bank_mask:0xf
	v_add_f32_dpp v53, v53, v53 row_shr:8 row_mask:0xf bank_mask:0xf
	v_add_f32_dpp v54, v54, v54 row_shr:8 row_mask:0xf bank_mask:0xf
	v_add_f32_dpp v55, v55, v55 row_shr:8 row_mask:0xf bank_mask:0xf
	v_add_f32_dpp v56, v56, v56 row_shr:8 row_mask:0xf bank_mask:0xf
	v_add_f32_dpp v57, v57, v57 row_shr:8 row_mask:0xf bank_mask:0xf
	v_add_f32_dpp v58, v58, v58 row_shr:8 row_mask:0xf bank_mask:0xf
	v_add_f32_dpp v59, v59, v59 row_shr:8 row_mask:0xf bank_mask:0xf
	v_add_f32_dpp v60, v60, v60 row_shr:8 row_mask:0xf bank_mask:0xf
	v_add_f32_dpp v61, v61, v61 row_shr:8 row_mask:0xf bank_mask:0xf
	v_add_f32_dpp v62, v62, v62 row_shr:8 row_mask:0xf bank_mask:0xf
	v_add_f32_dpp v63, v63, v63 row_shr:8 row_mask:0xf bank_mask:0xf
	v_add_f32_dpp v64, v64, v64 row_shr:8 row_mask:0xf bank_mask:0xf
	v_add_f32_dpp v65, v65, v65 row_shr:8 row_mask:0xf bank_mask:0xf
	s_lshl_b32 s0, s57, 8
	v_add_u32_e32 v232, s0, v215
	v_cmp_lt_u32_e32 vcc, 11, v98
	s_nop 0
	s_and_saveexec_b64 s[20:21], vcc
	ds_write_b128 v232, v[50:53] offset:0
	ds_write_b128 v232, v[54:57] offset:16
	ds_write_b128 v232, v[58:61] offset:128
	ds_write_b128 v232, v[62:65] offset:144
	s_or_b64 exec, exec, s[20:21]
	v_cvt_pk_bf16_f32 v216, v18, v19
	v_cvt_pk_bf16_f32 v217, v20, v21
	v_cvt_pk_bf16_f32 v218, v22, v23
	v_cvt_pk_bf16_f32 v219, v24, v25
	v_cvt_pk_bf16_f32 v220, v26, v27
	v_cvt_pk_bf16_f32 v221, v28, v29
	v_cvt_pk_bf16_f32 v222, v30, v31
	v_cvt_pk_bf16_f32 v223, v32, v33
	s_add_i32 s1, s57, 1
	s_cmp_lt_i32 s1, s53
	s_cbranch_scc0 .Lcmp_nok_q0p2g
	s_waitcnt lgkmcnt(0)
	s_lshl_b32 s0, s1, 13
	s_add_u32 s70, s66, s0
	s_addc_u32 s71, s67, 0
	global_load_dwordx4 v[50:53], v174, s[70:71] offset:0
	global_load_dwordx4 v[54:57], v174, s[70:71] offset:64
	global_load_dwordx4 v[58:61], v174, s[70:71] offset:512
	global_load_dwordx4 v[62:65], v174, s[70:71] offset:576
	global_load_dwordx4 v[66:69], v175, s[70:71] offset:0
	global_load_dwordx4 v[70:73], v175, s[70:71] offset:64
	global_load_dwordx4 v[74:77], v175, s[70:71] offset:512
	global_load_dwordx4 v[78:81], v175, s[70:71] offset:576
	s_waitcnt vmcnt(8)
	s_branch .Lcmp_kj_q0p2g

; #define LAS __attribute__((address_space(3)))
; #define CBAR() asm volatile("" ::: "memory")
; #define MFMA16(a, b, c) __builtin_amdgcn_mfma_f32_16x16x32_bf16(a, b, c, 0, 0, 0)
; __device__ __forceinline__ bf16_t tobf(float x) { return (bf16_t)pk2(x, 0.f); }
; __device__ __forceinline__ void pv_step(const VFrag& f, f32x4 (&o)[4], const LAS bf16_t* Pb, int r16, int q4) {
;     ...
;     for (int ks = 0; ks < 2; ++ks) { const bf16x8 aP = *(const LAS bf16x8*)(Pb + r16 * 72 + ks * 32 + q4 * 8);
; #pragma unroll
;         for (int nt = 0; nt < 4; ++nt) o[nt] = MFMA16(aP, f.v[ks][nt], o[nt]); }
; __device__ __forceinline__ void nsa_quad_pre(int bg, int quad, const bf16_t* Q, const bf16_t* KV, const bf16_t* KCMP, const bf16_t* VCMPT, const float* GN, bf16_t* ONSA, ...
;     ...
;     for (int tt = 0; tt < 4; ++tt) {
;         const int tok = t0 + tt, cur = tok >> 6;
;         if (cur < 16) { if (lane < 16) selq[tt * 16 + lane] = lane; }
;         else {
;             unsigned k0 = 0u, k1 = 0u;
;             { const int j = lane; if (j >= 1 && j <= cur - 2) { const LAS float* ps = psum + tt * 512 + 4 * j - 1; const float v = ps[0] + ps[1] + ps[2] + ps[3] + ps[4]; k0 = (__builtin_bit_cast(unsigned, v) & ~127u) | (unsigned)(127 - j); } }
;             { const int j = lane + 64; if (j <= cur - 2) { const LAS float* ps = psum + tt * 512 + 4 * j - 1; const float v = ps[0] + ps[1] + ps[2] + ps[3] + ps[4]; k1 = (__builtin_bit_cast(unsigned, v) & ~127u) | (unsigned)(127 - j); } }
;             for (int it = 0; it < 13; ++it) {
;                 unsigned m = k0 > k1 ? k0 : k1;
; #pragma unroll
;                 for (int off = 32; off >= 1; off >>= 1) { const unsigned o = (unsigned)__shfl_xor((int)m, off); m = o > m ? o : m; }
;                 if (k0 == m) k0 = 0u; if (k1 == m) k1 = 0u;
;                 if (lane == 0) selq[tt * 16 + it] = 127 - (int)(m & 127u);
;             }
;             if (lane == 0) { selq[tt * 16 + 13] = 0; selq[tt * 16 + 14] = cur - 1; selq[tt * 16 + 15] = cur; }
;         }
;     }
;     CBAR();
; #pragma unroll
;     for (int tt = 0; tt < 4; ++tt) { const float gc = GN[(size_t)(b * SEQ + t0 + tt) * 48 + (g * 4 + q4) * 3];
;         bf16_t* op = ONSA + (size_t)(b * SEQ + t0 + tt) * 1024 + (g * 4 + q4) * 64 + r16;
; #pragma unroll
;         for (int nt = 0; nt < 4; ++nt) op[nt * 16] = tobf(gc * oc[nt][tt]); }
.Lcmp_kj_q0p2g:
	s_nop 1
	v_mfma_f32_16x16x32_bf16 v[2:5], v[82:85], v[216:219], v[2:5]
	v_mfma_f32_16x16x32_bf16 v[2:5], v[86:89], v[220:223], v[2:5]
	v_mfma_f32_16x16x32_bf16 v[6:9], v[90:93], v[216:219], v[6:9]
	v_mfma_f32_16x16x32_bf16 v[6:9], v[94:97], v[220:223], v[6:9]
	v_mfma_f32_16x16x32_bf16 v[10:13], v[236:239], v[216:219], v[10:13]
	v_mfma_f32_16x16x32_bf16 v[10:13], v[240:243], v[220:223], v[10:13]
	v_mfma_f32_16x16x32_bf16 v[14:17], v[244:247], v[216:219], v[14:17]
	v_mfma_f32_16x16x32_bf16 v[14:17], v[248:251], v[220:223], v[14:17]
.Lcmp_nx_q0p2:
	s_nop 1
	s_add_i32 s57, s57, 1
	s_cmp_lt_i32 s57, s53
	s_cbranch_scc1 .Lcmp_top_q0p2
.Lcmp_none_q0:
	s_nop 1
	s_nop 7
	s_nop 3
	v_and_b32_e32 v232, 15, v184
	v_lshrrev_b32_e32 v233, 4, v184
	v_and_b32_e32 v234, 3, v232
	v_lshrrev_b32_e32 v235, 2, v232
	s_add_i32 s0, s47, s97
	v_add_u32_e32 v253, s0, v234
	s_and_b32 s1, s88, 3
	s_lshl_b32 s1, s1, 2
	v_add_u32_e32 v0, s1, v235
	v_lshlrev_b32_e32 v98, 7, v0
	v_lshl_add_u32 v98, v253, 11, v98
	v_lshl_add_u32 v98, v233, 3, v98
	v_mul_u32_u24_e32 v99, 0xc0, v253
	v_mul_u32_u24_e32 v0, 12, v0
	v_add_u32_e32 v99, v99, v0
	s_add_u32 s70, s30, 0x38310000
	s_addc_u32 s71, s31, 0
	s_add_u32 s14, s30, 0xf900000
	s_addc_u32 s15, s31, 0
	global_load_dword v232, v99, s[70:71]
	s_waitcnt vmcnt(0)
	v_mul_f32_e32 v2, v2, v232
	v_mul_f32_e32 v3, v3, v232
	v_mul_f32_e32 v4, v4, v232
	v_mul_f32_e32 v5, v5, v232
	v_mul_f32_e32 v6, v6, v232
	v_mul_f32_e32 v7, v7, v232
	v_mul_f32_e32 v8, v8, v232
	v_mul_f32_e32 v9, v9, v232
	v_mul_f32_e32 v10, v10, v232
	v_mul_f32_e32 v11, v11, v232
	v_mul_f32_e32 v12, v12, v232
	v_mul_f32_e32 v13, v13, v232
	v_mul_f32_e32 v14, v14, v232
	v_mul_f32_e32 v15, v15, v232
	v_mul_f32_e32 v16, v16, v232
	v_mul_f32_e32 v17, v17, v232
	v_cvt_pk_bf16_f32 v216, v2, v3
	v_cvt_pk_bf16_f32 v217, v4, v5
	v_cvt_pk_bf16_f32 v218, v6, v7
	v_cvt_pk_bf16_f32 v219, v8, v9
	v_cvt_pk_bf16_f32 v220, v10, v11
	v_cvt_pk_bf16_f32 v221, v12, v13
	v_cvt_pk_bf16_f32 v222, v14, v15
	v_cvt_pk_bf16_f32 v223, v16, v17
	global_store_dwordx2 v98, v[216:217], s[14:15] offset:0
	global_store_dwordx2 v98, v[218:219], s[14:15] offset:32
	global_store_dwordx2 v98, v[220:221], s[14:15] offset:64
	global_store_dwordx2 v98, v[222:223], s[14:15] offset:96
	s_waitcnt lgkmcnt(0)
	s_cmp_gt_i32 s18, 15
	s_cbranch_scc0 .Ltopk_small_q0
	s_lshl_b32 s19, s80, 10
	s_add_i32 s19, s19, 56384
	v_lshlrev_b32_e32 v96, 4, v184
	v_add_u32_e32 v96, s19, v96
	v_add_u32_e32 v97, 0xfffffffc, v96
	v_sub_u32_e32 v94, 127, v184
	v_sub_u32_e32 v95, 63, v184
	s_mov_b32 s54, 0xffffff80
	s_add_i32 s21, s18, -2
	v_add_u32_e32 v236, 64, v184
	ds_read_b32 v86, v97 offset:0
	ds_read_b128 v[50:53], v96 offset:0
	ds_read_b32 v87, v97 offset:1024
	ds_read_b128 v[54:57], v96 offset:1024
	ds_read_b32 v88, v97 offset:2048
	ds_read_b128 v[58:61], v96 offset:2048
	ds_read_b32 v89, v97 offset:3072
	ds_read_b128 v[62:65], v96 offset:3072
	s_waitcnt lgkmcnt(6)
	v_add_f32_e32 v86, v86, v50
	v_add_f32_e32 v86, v86, v51
	v_add_f32_e32 v86, v86, v52
	v_add_f32_e32 v86, v86, v53
	v_and_or_b32 v18, v86, s54, v94
	s_waitcnt lgkmcnt(4)
	v_add_f32_e32 v87, v87, v54
	v_add_f32_e32 v87, v87, v55
	v_add_f32_e32 v87, v87, v56
	v_add_f32_e32 v87, v87, v57
	v_and_or_b32 v22, v87, s54, v95
	s_waitcnt lgkmcnt(2)
	v_add_f32_e32 v88, v88, v58
	v_add_f32_e32 v88, v88, v59
	v_add_f32_e32 v88, v88, v60
	v_add_f32_e32 v88, v88, v61
	v_and_or_b32 v19, v88, s54, v94
	s_waitcnt lgkmcnt(0)
	v_add_f32_e32 v89, v89, v62
	v_add_f32_e32 v89, v89, v63
	v_add_f32_e32 v89, v89, v64
	v_add_f32_e32 v89, v89, v65
	v_and_or_b32 v23, v89, s54, v95
	ds_read_b32 v90, v97 offset:4096
	ds_read_b128 v[66:69], v96 offset:4096
	ds_read_b32 v91, v97 offset:5120
	ds_read_b128 v[70:73], v96 offset:5120
	ds_read_b32 v92, v97 offset:6144
	ds_read_b128 v[74:77], v96 offset:6144
	ds_read_b32 v93, v97 offset:7168
	ds_read_b128 v[78:81], v96 offset:7168
	s_waitcnt lgkmcnt(6)
	v_add_f32_e32 v90, v90, v66
	v_add_f32_e32 v90, v90, v67
	v_add_f32_e32 v90, v90, v68
	v_add_f32_e32 v90, v90, v69
	v_and_or_b32 v20, v90, s54, v94
	s_waitcnt lgkmcnt(4)
	v_add_f32_e32 v91, v91, v70
	v_add_f32_e32 v91, v91, v71
	v_add_f32_e32 v91, v91, v72
	v_add_f32_e32 v91, v91, v73
	v_and_or_b32 v24, v91, s54, v95
	s_waitcnt lgkmcnt(2)
	v_add_f32_e32 v92, v92, v74
	v_add_f32_e32 v92, v92, v75
	v_add_f32_e32 v92, v92, v76
	v_add_f32_e32 v92, v92, v77
	v_and_or_b32 v21, v92, s54, v94
	s_waitcnt lgkmcnt(0)
	v_add_f32_e32 v93, v93, v78
	v_add_f32_e32 v93, v93, v79
	v_add_f32_e32 v93, v93, v80
	v_add_f32_e32 v93, v93, v81
	v_and_or_b32 v25, v93, s54, v95
	v_cmp_le_i32_e64 s[14:15], v184, s21
	v_cmp_lt_i32_e64 s[34:35], 0, v184
	s_nop 0
	s_and_b64 s[14:15], s[14:15], s[34:35]
	v_cmp_le_i32_e64 s[34:35], v236, s21
	v_cndmask_b32_e64 v18, 0, v18, s[14:15]
	s_nop 0
	v_cndmask_b32_e64 v22, 0, v22, s[34:35]
	v_mov_b32_e32 v82, 0
	v_cndmask_b32_e64 v19, 0, v19, s[14:15]
	v_cndmask_b32_e64 v23, 0, v23, s[34:35]
	v_mov_b32_e32 v83, 0
	v_cndmask_b32_e64 v20, 0, v20, s[14:15]
	v_cndmask_b32_e64 v24, 0, v24, s[34:35]
	v_mov_b32_e32 v84, 0
	v_cndmask_b32_e64 v21, 0, v21, s[14:15]
	v_cndmask_b32_e64 v25, 0, v25, s[34:35]
	v_mov_b32_e32 v85, 0
	v_max_u32_e32 v26, v18, v22
	v_max_u32_e32 v27, v19, v23
	v_max_u32_e32 v28, v20, v24
	v_max_u32_e32 v29, v21, v25
	v_max_u32_dpp v26, v26, v26 quad_perm:[1,0,3,2] row_mask:0xf bank_mask:0xf
	v_max_u32_dpp v27, v27, v27 quad_perm:[1,0,3,2] row_mask:0xf bank_mask:0xf
	v_max_u32_dpp v28, v28, v28 quad_perm:[1,0,3,2] row_mask:0xf bank_mask:0xf
	v_max_u32_dpp v29, v29, v29 quad_perm:[1,0,3,2] row_mask:0xf bank_mask:0xf
	v_max_u32_dpp v26, v26, v26 quad_perm:[2,3,0,1] row_mask:0xf bank_mask:0xf
	v_max_u32_dpp v27, v27, v27 quad_perm:[2,3,0,1] row_mask:0xf bank_mask:0xf
	v_max_u32_dpp v28, v28, v28 quad_perm:[2,3,0,1] row_mask:0xf bank_mask:0xf
	v_max_u32_dpp v29, v29, v29 quad_perm:[2,3,0,1] row_mask:0xf bank_mask:0xf
	v_max_u32_dpp v26, v26, v26 row_half_mirror row_mask:0xf bank_mask:0xf
	v_max_u32_dpp v27, v27, v27 row_half_mirror row_mask:0xf bank_mask:0xf
	v_max_u32_dpp v28, v28, v28 row_half_mirror row_mask:0xf bank_mask:0xf
	v_max_u32_dpp v29, v29, v29 row_half_mirror row_mask:0xf bank_mask:0xf
	v_max_u32_dpp v26, v26, v26 row_mirror row_mask:0xf bank_mask:0xf
	v_max_u32_dpp v27, v27, v27 row_mirror row_mask:0xf bank_mask:0xf
	v_max_u32_dpp v28, v28, v28 row_mirror row_mask:0xf bank_mask:0xf
	v_max_u32_dpp v29, v29, v29 row_mirror row_mask:0xf bank_mask:0xf
	ds_swizzle_b32 v30, v26 offset:0x401f
	ds_swizzle_b32 v31, v27 offset:0x401f
	ds_swizzle_b32 v32, v28 offset:0x401f
	ds_swizzle_b32 v33, v29 offset:0x401f
	s_waitcnt lgkmcnt(3)
; #define LAS __attribute__((address_space(3)))
; __device__ __forceinline__ void nsa_quad_pre(int bg, int quad, const bf16_t* Q, const bf16_t* KV, const bf16_t* KCMP, const bf16_t* VCMPT, const float* GN, bf16_t* ONSA, ...
;     ...
;             unsigned k0 = 0u, k1 = 0u;
;             { const int j = lane; if (j >= 1 && j <= cur - 2) { const LAS float* ps = psum + tt * 512 + 4 * j - 1; const float v = ps[0] + ps[1] + ps[2] + ps[3] + ps[4]; k0 = (__builtin_bit_cast(unsigned, v) & ~127u) | (unsigned)(127 - j); } }
;             { const int j = lane + 64; if (j <= cur - 2) { const LAS float* ps = psum + tt * 512 + 4 * j - 1; const float v = ps[0] + ps[1] + ps[2] + ps[3] + ps[4]; k1 = (__builtin_bit_cast(unsigned, v) & ~127u) | (unsigned)(127 - j); } }
;             for (int it = 0; it < 13; ++it) {
;                 unsigned m = k0 > k1 ? k0 : k1;
; #pragma unroll
;                 for (int off = 32; off >= 1; off >>= 1) { const unsigned o = (unsigned)__shfl_xor((int)m, off); m = o > m ? o : m; }
;                 if (k0 == m) k0 = 0u; if (k1 == m) k1 = 0u;
;                 if (lane == 0) selq[tt * 16 + it] = 127 - (int)(m & 127u);
;             }
;             if (lane == 0) { selq[tt * 16 + 13] = 0; selq[tt * 16 + 14] = cur - 1; selq[tt * 16 + 15] = cur; }
	v_max_u32_e32 v26, v26, v30
	s_waitcnt lgkmcnt(2)
	v_max_u32_e32 v27, v27, v31
	s_waitcnt lgkmcnt(1)
	v_max_u32_e32 v28, v28, v32
	s_waitcnt lgkmcnt(0)
	v_max_u32_e32 v29, v29, v33
	v_mov_b32_e32 v30, v26
	v_mov_b32_e32 v31, v27
	v_mov_b32_e32 v32, v28
	v_mov_b32_e32 v33, v29
	v_permlane32_swap_b32_e32 v26, v30
	v_permlane32_swap_b32_e32 v27, v31
	v_permlane32_swap_b32_e32 v28, v32
	v_permlane32_swap_b32_e32 v29, v33
	v_max_u32_e32 v26, v26, v30
	v_max_u32_e32 v27, v27, v31
	v_max_u32_e32 v28, v28, v32
	v_max_u32_e32 v29, v29, v33
	v_cmp_eq_u32_e64 s[0:1], 0, v184
	v_and_b32_e32 v236, 127, v26
	v_sub_u32_e32 v236, 127, v236
	v_and_b32_e32 v237, 127, v27
	v_sub_u32_e32 v237, 127, v237
	v_and_b32_e32 v238, 127, v28
	v_sub_u32_e32 v238, 127, v238
	v_and_b32_e32 v239, 127, v29
	v_sub_u32_e32 v239, 127, v239
	v_cndmask_b32_e64 v82, v82, v236, s[0:1]
	v_cndmask_b32_e64 v83, v83, v237, s[0:1]
	v_cndmask_b32_e64 v84, v84, v238, s[0:1]
	v_cndmask_b32_e64 v85, v85, v239, s[0:1]
	v_cmp_eq_u32_e64 s[14:15], v26, v18
	v_cmp_eq_u32_e64 s[34:35], v26, v22
	v_cmp_eq_u32_e64 s[42:43], v27, v19
	v_cmp_eq_u32_e64 s[66:67], v27, v23
	v_cndmask_b32_e64 v18, v18, 0, s[14:15]
	v_cndmask_b32_e64 v22, v22, 0, s[34:35]
	v_cndmask_b32_e64 v19, v19, 0, s[42:43]
	v_cndmask_b32_e64 v23, v23, 0, s[66:67]
	v_cmp_eq_u32_e64 s[14:15], v28, v20
	v_cmp_eq_u32_e64 s[34:35], v28, v24
	v_cmp_eq_u32_e64 s[42:43], v29, v21
	v_cmp_eq_u32_e64 s[66:67], v29, v25
	v_cndmask_b32_e64 v20, v20, 0, s[14:15]
	v_cndmask_b32_e64 v24, v24, 0, s[34:35]
	v_cndmask_b32_e64 v21, v21, 0, s[42:43]
	v_cndmask_b32_e64 v25, v25, 0, s[66:67]
	v_max_u32_e32 v26, v18, v22
	v_max_u32_e32 v27, v19, v23
	v_max_u32_e32 v28, v20, v24
	v_max_u32_e32 v29, v21, v25
	v_max_u32_dpp v26, v26, v26 quad_perm:[1,0,3,2] row_mask:0xf bank_mask:0xf
	v_max_u32_dpp v27, v27, v27 quad_perm:[1,0,3,2] row_mask:0xf bank_mask:0xf
	v_max_u32_dpp v28, v28, v28 quad_perm:[1,0,3,2] row_mask:0xf bank_mask:0xf
	v_max_u32_dpp v29, v29, v29 quad_perm:[1,0,3,2] row_mask:0xf bank_mask:0xf
	v_max_u32_dpp v26, v26, v26 quad_perm:[2,3,0,1] row_mask:0xf bank_mask:0xf
	v_max_u32_dpp v27, v27, v27 quad_perm:[2,3,0,1] row_mask:0xf bank_mask:0xf
	v_max_u32_dpp v28, v28, v28 quad_perm:[2,3,0,1] row_mask:0xf bank_mask:0xf
	v_max_u32_dpp v29, v29, v29 quad_perm:[2,3,0,1] row_mask:0xf bank_mask:0xf
	v_max_u32_dpp v26, v26, v26 row_half_mirror row_mask:0xf bank_mask:0xf
	v_max_u32_dpp v27, v27, v27 row_half_mirror row_mask:0xf bank_mask:0xf
	v_max_u32_dpp v28, v28, v28 row_half_mirror row_mask:0xf bank_mask:0xf
	v_max_u32_dpp v29, v29, v29 row_half_mirror row_mask:0xf bank_mask:0xf
	v_max_u32_dpp v26, v26, v26 row_mirror row_mask:0xf bank_mask:0xf
	v_max_u32_dpp v27, v27, v27 row_mirror row_mask:0xf bank_mask:0xf
	v_max_u32_dpp v28, v28, v28 row_mirror row_mask:0xf bank_mask:0xf
	v_max_u32_dpp v29, v29, v29 row_mirror row_mask:0xf bank_mask:0xf
	ds_swizzle_b32 v30, v26 offset:0x401f
	ds_swizzle_b32 v31, v27 offset:0x401f
	ds_swizzle_b32 v32, v28 offset:0x401f
	ds_swizzle_b32 v33, v29 offset:0x401f
	s_waitcnt lgkmcnt(3)
	v_max_u32_e32 v26, v26, v30
	s_waitcnt lgkmcnt(2)
	v_max_u32_e32 v27, v27, v31
	s_waitcnt lgkmcnt(1)
	v_max_u32_e32 v28, v28, v32
	s_waitcnt lgkmcnt(0)
	v_max_u32_e32 v29, v29, v33
	v_mov_b32_e32 v30, v26
	v_mov_b32_e32 v31, v27
	v_mov_b32_e32 v32, v28
	v_mov_b32_e32 v33, v29
	v_permlane32_swap_b32_e32 v26, v30
	v_permlane32_swap_b32_e32 v27, v31
	v_permlane32_swap_b32_e32 v28, v32
	v_permlane32_swap_b32_e32 v29, v33
	v_max_u32_e32 v26, v26, v30
	v_max_u32_e32 v27, v27, v31
	v_max_u32_e32 v28, v28, v32
	v_max_u32_e32 v29, v29, v33
	v_cmp_eq_u32_e64 s[0:1], 1, v184
	v_and_b32_e32 v236, 127, v26
	v_sub_u32_e32 v236, 127, v236
	v_and_b32_e32 v237, 127, v27
	v_sub_u32_e32 v237, 127, v237
	v_and_b32_e32 v238, 127, v28
	v_sub_u32_e32 v238, 127, v238
	v_and_b32_e32 v239, 127, v29
	v_sub_u32_e32 v239, 127, v239
	v_cndmask_b32_e64 v82, v82, v236, s[0:1]
	v_cndmask_b32_e64 v83, v83, v237, s[0:1]
	v_cndmask_b32_e64 v84, v84, v238, s[0:1]
	v_cndmask_b32_e64 v85, v85, v239, s[0:1]
	v_cmp_eq_u32_e64 s[14:15], v26, v18
	v_cmp_eq_u32_e64 s[34:35], v26, v22
	v_cmp_eq_u32_e64 s[42:43], v27, v19
	v_cmp_eq_u32_e64 s[66:67], v27, v23
	v_cndmask_b32_e64 v18, v18, 0, s[14:15]
	v_cndmask_b32_e64 v22, v22, 0, s[34:35]
	v_cndmask_b32_e64 v19, v19, 0, s[42:43]
	v_cndmask_b32_e64 v23, v23, 0, s[66:67]
	v_cmp_eq_u32_e64 s[14:15], v28, v20
	v_cmp_eq_u32_e64 s[34:35], v28, v24
	v_cmp_eq_u32_e64 s[42:43], v29, v21
	v_cmp_eq_u32_e64 s[66:67], v29, v25
	v_cndmask_b32_e64 v20, v20, 0, s[14:15]
	v_cndmask_b32_e64 v24, v24, 0, s[34:35]
	v_cndmask_b32_e64 v21, v21, 0, s[42:43]
	v_cndmask_b32_e64 v25, v25, 0, s[66:67]
	v_max_u32_e32 v26, v18, v22
	v_max_u32_e32 v27, v19, v23
	v_max_u32_e32 v28, v20, v24
	v_max_u32_e32 v29, v21, v25
	v_max_u32_dpp v26, v26, v26 quad_perm:[1,0,3,2] row_mask:0xf bank_mask:0xf
	v_max_u32_dpp v27, v27, v27 quad_perm:[1,0,3,2] row_mask:0xf bank_mask:0xf
	v_max_u32_dpp v28, v28, v28 quad_perm:[1,0,3,2] row_mask:0xf bank_mask:0xf
	v_max_u32_dpp v29, v29, v29 quad_perm:[1,0,3,2] row_mask:0xf bank_mask:0xf
	v_max_u32_dpp v26, v26, v26 quad_perm:[2,3,0,1] row_mask:0xf bank_mask:0xf
	v_max_u32_dpp v27, v27, v27 quad_perm:[2,3,0,1] row_mask:0xf bank_mask:0xf
	v_max_u32_dpp v28, v28, v28 quad_perm:[2,3,0,1] row_mask:0xf bank_mask:0xf
	v_max_u32_dpp v29, v29, v29 quad_perm:[2,3,0,1] row_mask:0xf bank_mask:0xf
	v_max_u32_dpp v26, v26, v26 row_half_mirror row_mask:0xf bank_mask:0xf
	v_max_u32_dpp v27, v27, v27 row_half_mirror row_mask:0xf bank_mask:0xf
	v_max_u32_dpp v28, v28, v28 row_half_mirror row_mask:0xf bank_mask:0xf
	v_max_u32_dpp v29, v29, v29 row_half_mirror row_mask:0xf bank_mask:0xf
	v_max_u32_dpp v26, v26, v26 row_mirror row_mask:0xf bank_mask:0xf
	v_max_u32_dpp v27, v27, v27 row_mirror row_mask:0xf bank_mask:0xf
	v_max_u32_dpp v28, v28, v28 row_mirror row_mask:0xf bank_mask:0xf
	v_max_u32_dpp v29, v29, v29 row_mirror row_mask:0xf bank_mask:0xf
	ds_swizzle_b32 v30, v26 offset:0x401f
	ds_swizzle_b32 v31, v27 offset:0x401f
	ds_swizzle_b32 v32, v28 offset:0x401f
	ds_swizzle_b32 v33, v29 offset:0x401f
	s_waitcnt lgkmcnt(3)
; #define LAS __attribute__((address_space(3)))
; __device__ __forceinline__ void nsa_quad_pre(int bg, int quad, const bf16_t* Q, const bf16_t* KV, const bf16_t* KCMP, const bf16_t* VCMPT, const float* GN, bf16_t* ONSA, ...
;     ...
;             unsigned k0 = 0u, k1 = 0u;
;             { const int j = lane; if (j >= 1 && j <= cur - 2) { const LAS float* ps = psum + tt * 512 + 4 * j - 1; const float v = ps[0] + ps[1] + ps[2] + ps[3] + ps[4]; k0 = (__builtin_bit_cast(unsigned, v) & ~127u) | (unsigned)(127 - j); } }
;             { const int j = lane + 64; if (j <= cur - 2) { const LAS float* ps = psum + tt * 512 + 4 * j - 1; const float v = ps[0] + ps[1] + ps[2] + ps[3] + ps[4]; k1 = (__builtin_bit_cast(unsigned, v) & ~127u) | (unsigned)(127 - j); } }
;             for (int it = 0; it < 13; ++it) {
;                 unsigned m = k0 > k1 ? k0 : k1;
; #pragma unroll
;                 for (int off = 32; off >= 1; off >>= 1) { const unsigned o = (unsigned)__shfl_xor((int)m, off); m = o > m ? o : m; }
;                 if (k0 == m) k0 = 0u; if (k1 == m) k1 = 0u;
;                 if (lane == 0) selq[tt * 16 + it] = 127 - (int)(m & 127u);
;             }
;             if (lane == 0) { selq[tt * 16 + 13] = 0; selq[tt * 16 + 14] = cur - 1; selq[tt * 16 + 15] = cur; }
	v_max_u32_e32 v26, v26, v30
	s_waitcnt lgkmcnt(2)
	v_max_u32_e32 v27, v27, v31
	s_waitcnt lgkmcnt(1)
	v_max_u32_e32 v28, v28, v32
	s_waitcnt lgkmcnt(0)
	v_max_u32_e32 v29, v29, v33
	v_mov_b32_e32 v30, v26
	v_mov_b32_e32 v31, v27
	v_mov_b32_e32 v32, v28
	v_mov_b32_e32 v33, v29
	v_permlane32_swap_b32_e32 v26, v30
	v_permlane32_swap_b32_e32 v27, v31
	v_permlane32_swap_b32_e32 v28, v32
	v_permlane32_swap_b32_e32 v29, v33
	v_max_u32_e32 v26, v26, v30
	v_max_u32_e32 v27, v27, v31
	v_max_u32_e32 v28, v28, v32
	v_max_u32_e32 v29, v29, v33
	v_cmp_eq_u32_e64 s[0:1], 2, v184
	v_and_b32_e32 v236, 127, v26
	v_sub_u32_e32 v236, 127, v236
	v_and_b32_e32 v237, 127, v27
	v_sub_u32_e32 v237, 127, v237
	v_and_b32_e32 v238, 127, v28
	v_sub_u32_e32 v238, 127, v238
	v_and_b32_e32 v239, 127, v29
	v_sub_u32_e32 v239, 127, v239
	v_cndmask_b32_e64 v82, v82, v236, s[0:1]
	v_cndmask_b32_e64 v83, v83, v237, s[0:1]
	v_cndmask_b32_e64 v84, v84, v238, s[0:1]
	v_cndmask_b32_e64 v85, v85, v239, s[0:1]
	v_cmp_eq_u32_e64 s[14:15], v26, v18
	v_cmp_eq_u32_e64 s[34:35], v26, v22
	v_cmp_eq_u32_e64 s[42:43], v27, v19
	v_cmp_eq_u32_e64 s[66:67], v27, v23
	v_cndmask_b32_e64 v18, v18, 0, s[14:15]
	v_cndmask_b32_e64 v22, v22, 0, s[34:35]
	v_cndmask_b32_e64 v19, v19, 0, s[42:43]
	v_cndmask_b32_e64 v23, v23, 0, s[66:67]
	v_cmp_eq_u32_e64 s[14:15], v28, v20
	v_cmp_eq_u32_e64 s[34:35], v28, v24
	v_cmp_eq_u32_e64 s[42:43], v29, v21
	v_cmp_eq_u32_e64 s[66:67], v29, v25
	v_cndmask_b32_e64 v20, v20, 0, s[14:15]
	v_cndmask_b32_e64 v24, v24, 0, s[34:35]
	v_cndmask_b32_e64 v21, v21, 0, s[42:43]
	v_cndmask_b32_e64 v25, v25, 0, s[66:67]
	v_max_u32_e32 v26, v18, v22
	v_max_u32_e32 v27, v19, v23
	v_max_u32_e32 v28, v20, v24
	v_max_u32_e32 v29, v21, v25
	v_max_u32_dpp v26, v26, v26 quad_perm:[1,0,3,2] row_mask:0xf bank_mask:0xf
	v_max_u32_dpp v27, v27, v27 quad_perm:[1,0,3,2] row_mask:0xf bank_mask:0xf
	v_max_u32_dpp v28, v28, v28 quad_perm:[1,0,3,2] row_mask:0xf bank_mask:0xf
	v_max_u32_dpp v29, v29, v29 quad_perm:[1,0,3,2] row_mask:0xf bank_mask:0xf
	v_max_u32_dpp v26, v26, v26 quad_perm:[2,3,0,1] row_mask:0xf bank_mask:0xf
	v_max_u32_dpp v27, v27, v27 quad_perm:[2,3,0,1] row_mask:0xf bank_mask:0xf
	v_max_u32_dpp v28, v28, v28 quad_perm:[2,3,0,1] row_mask:0xf bank_mask:0xf
	v_max_u32_dpp v29, v29, v29 quad_perm:[2,3,0,1] row_mask:0xf bank_mask:0xf
	v_max_u32_dpp v26, v26, v26 row_half_mirror row_mask:0xf bank_mask:0xf
	v_max_u32_dpp v27, v27, v27 row_half_mirror row_mask:0xf bank_mask:0xf
	v_max_u32_dpp v28, v28, v28 row_half_mirror row_mask:0xf bank_mask:0xf
	v_max_u32_dpp v29, v29, v29 row_half_mirror row_mask:0xf bank_mask:0xf
	v_max_u32_dpp v26, v26, v26 row_mirror row_mask:0xf bank_mask:0xf
	v_max_u32_dpp v27, v27, v27 row_mirror row_mask:0xf bank_mask:0xf
	v_max_u32_dpp v28, v28, v28 row_mirror row_mask:0xf bank_mask:0xf
	v_max_u32_dpp v29, v29, v29 row_mirror row_mask:0xf bank_mask:0xf
	ds_swizzle_b32 v30, v26 offset:0x401f
	ds_swizzle_b32 v31, v27 offset:0x401f
	ds_swizzle_b32 v32, v28 offset:0x401f
	ds_swizzle_b32 v33, v29 offset:0x401f
	s_waitcnt lgkmcnt(3)
	v_max_u32_e32 v26, v26, v30
	s_waitcnt lgkmcnt(2)
	v_max_u32_e32 v27, v27, v31
	s_waitcnt lgkmcnt(1)
	v_max_u32_e32 v28, v28, v32
	s_waitcnt lgkmcnt(0)
	v_max_u32_e32 v29, v29, v33
	v_mov_b32_e32 v30, v26
	v_mov_b32_e32 v31, v27
	v_mov_b32_e32 v32, v28
	v_mov_b32_e32 v33, v29
	v_permlane32_swap_b32_e32 v26, v30
	v_permlane32_swap_b32_e32 v27, v31
	v_permlane32_swap_b32_e32 v28, v32
	v_permlane32_swap_b32_e32 v29, v33
	v_max_u32_e32 v26, v26, v30
	v_max_u32_e32 v27, v27, v31
	v_max_u32_e32 v28, v28, v32
	v_max_u32_e32 v29, v29, v33
	v_cmp_eq_u32_e64 s[0:1], 3, v184
	v_and_b32_e32 v236, 127, v26
	v_sub_u32_e32 v236, 127, v236
	v_and_b32_e32 v237, 127, v27
	v_sub_u32_e32 v237, 127, v237
	v_and_b32_e32 v238, 127, v28
	v_sub_u32_e32 v238, 127, v238
	v_and_b32_e32 v239, 127, v29
	v_sub_u32_e32 v239, 127, v239
	v_cndmask_b32_e64 v82, v82, v236, s[0:1]
	v_cndmask_b32_e64 v83, v83, v237, s[0:1]
	v_cndmask_b32_e64 v84, v84, v238, s[0:1]
	v_cndmask_b32_e64 v85, v85, v239, s[0:1]
	v_cmp_eq_u32_e64 s[14:15], v26, v18
	v_cmp_eq_u32_e64 s[34:35], v26, v22
	v_cmp_eq_u32_e64 s[42:43], v27, v19
	v_cmp_eq_u32_e64 s[66:67], v27, v23
	v_cndmask_b32_e64 v18, v18, 0, s[14:15]
	v_cndmask_b32_e64 v22, v22, 0, s[34:35]
	v_cndmask_b32_e64 v19, v19, 0, s[42:43]
	v_cndmask_b32_e64 v23, v23, 0, s[66:67]
	v_cmp_eq_u32_e64 s[14:15], v28, v20
	v_cmp_eq_u32_e64 s[34:35], v28, v24
	v_cmp_eq_u32_e64 s[42:43], v29, v21
	v_cmp_eq_u32_e64 s[66:67], v29, v25
	v_cndmask_b32_e64 v20, v20, 0, s[14:15]
	v_cndmask_b32_e64 v24, v24, 0, s[34:35]
	v_cndmask_b32_e64 v21, v21, 0, s[42:43]
	v_cndmask_b32_e64 v25, v25, 0, s[66:67]
	v_max_u32_e32 v26, v18, v22
	v_max_u32_e32 v27, v19, v23
	v_max_u32_e32 v28, v20, v24
	v_max_u32_e32 v29, v21, v25
	v_max_u32_dpp v26, v26, v26 quad_perm:[1,0,3,2] row_mask:0xf bank_mask:0xf
	v_max_u32_dpp v27, v27, v27 quad_perm:[1,0,3,2] row_mask:0xf bank_mask:0xf
	v_max_u32_dpp v28, v28, v28 quad_perm:[1,0,3,2] row_mask:0xf bank_mask:0xf
	v_max_u32_dpp v29, v29, v29 quad_perm:[1,0,3,2] row_mask:0xf bank_mask:0xf
	v_max_u32_dpp v26, v26, v26 quad_perm:[2,3,0,1] row_mask:0xf bank_mask:0xf
	v_max_u32_dpp v27, v27, v27 quad_perm:[2,3,0,1] row_mask:0xf bank_mask:0xf
	v_max_u32_dpp v28, v28, v28 quad_perm:[2,3,0,1] row_mask:0xf bank_mask:0xf
	v_max_u32_dpp v29, v29, v29 quad_perm:[2,3,0,1] row_mask:0xf bank_mask:0xf
	v_max_u32_dpp v26, v26, v26 row_half_mirror row_mask:0xf bank_mask:0xf
	v_max_u32_dpp v27, v27, v27 row_half_mirror row_mask:0xf bank_mask:0xf
	v_max_u32_dpp v28, v28, v28 row_half_mirror row_mask:0xf bank_mask:0xf
	v_max_u32_dpp v29, v29, v29 row_half_mirror row_mask:0xf bank_mask:0xf
	v_max_u32_dpp v26, v26, v26 row_mirror row_mask:0xf bank_mask:0xf
	v_max_u32_dpp v27, v27, v27 row_mirror row_mask:0xf bank_mask:0xf
	v_max_u32_dpp v28, v28, v28 row_mirror row_mask:0xf bank_mask:0xf
	v_max_u32_dpp v29, v29, v29 row_mirror row_mask:0xf bank_mask:0xf
	ds_swizzle_b32 v30, v26 offset:0x401f
	ds_swizzle_b32 v31, v27 offset:0x401f
	ds_swizzle_b32 v32, v28 offset:0x401f
	ds_swizzle_b32 v33, v29 offset:0x401f
	s_waitcnt lgkmcnt(3)
; #define LAS __attribute__((address_space(3)))
; __device__ __forceinline__ void nsa_quad_pre(int bg, int quad, const bf16_t* Q, const bf16_t* KV, const bf16_t* KCMP, const bf16_t* VCMPT, const float* GN, bf16_t* ONSA, ...
;     ...
;             unsigned k0 = 0u, k1 = 0u;
;             { const int j = lane; if (j >= 1 && j <= cur - 2) { const LAS float* ps = psum + tt * 512 + 4 * j - 1; const float v = ps[0] + ps[1] + ps[2] + ps[3] + ps[4]; k0 = (__builtin_bit_cast(unsigned, v) & ~127u) | (unsigned)(127 - j); } }
;             { const int j = lane + 64; if (j <= cur - 2) { const LAS float* ps = psum + tt * 512 + 4 * j - 1; const float v = ps[0] + ps[1] + ps[2] + ps[3] + ps[4]; k1 = (__builtin_bit_cast(unsigned, v) & ~127u) | (unsigned)(127 - j); } }
;             for (int it = 0; it < 13; ++it) {
;                 unsigned m = k0 > k1 ? k0 : k1;
; #pragma unroll
;                 for (int off = 32; off >= 1; off >>= 1) { const unsigned o = (unsigned)__shfl_xor((int)m, off); m = o > m ? o : m; }
;                 if (k0 == m) k0 = 0u; if (k1 == m) k1 = 0u;
;                 if (lane == 0) selq[tt * 16 + it] = 127 - (int)(m & 127u);
;             }
;             if (lane == 0) { selq[tt * 16 + 13] = 0; selq[tt * 16 + 14] = cur - 1; selq[tt * 16 + 15] = cur; }
	v_max_u32_e32 v26, v26, v30
	s_waitcnt lgkmcnt(2)
	v_max_u32_e32 v27, v27, v31
	s_waitcnt lgkmcnt(1)
	v_max_u32_e32 v28, v28, v32
	s_waitcnt lgkmcnt(0)
	v_max_u32_e32 v29, v29, v33
	v_mov_b32_e32 v30, v26
	v_mov_b32_e32 v31, v27
	v_mov_b32_e32 v32, v28
	v_mov_b32_e32 v33, v29
	v_permlane32_swap_b32_e32 v26, v30
	v_permlane32_swap_b32_e32 v27, v31
	v_permlane32_swap_b32_e32 v28, v32
	v_permlane32_swap_b32_e32 v29, v33
	v_max_u32_e32 v26, v26, v30
	v_max_u32_e32 v27, v27, v31
	v_max_u32_e32 v28, v28, v32
	v_max_u32_e32 v29, v29, v33
	v_cmp_eq_u32_e64 s[0:1], 4, v184
	v_and_b32_e32 v236, 127, v26
	v_sub_u32_e32 v236, 127, v236
	v_and_b32_e32 v237, 127, v27
	v_sub_u32_e32 v237, 127, v237
	v_and_b32_e32 v238, 127, v28
	v_sub_u32_e32 v238, 127, v238
	v_and_b32_e32 v239, 127, v29
	v_sub_u32_e32 v239, 127, v239
	v_cndmask_b32_e64 v82, v82, v236, s[0:1]
	v_cndmask_b32_e64 v83, v83, v237, s[0:1]
	v_cndmask_b32_e64 v84, v84, v238, s[0:1]
	v_cndmask_b32_e64 v85, v85, v239, s[0:1]
	v_cmp_eq_u32_e64 s[14:15], v26, v18
	v_cmp_eq_u32_e64 s[34:35], v26, v22
	v_cmp_eq_u32_e64 s[42:43], v27, v19
	v_cmp_eq_u32_e64 s[66:67], v27, v23
	v_cndmask_b32_e64 v18, v18, 0, s[14:15]
	v_cndmask_b32_e64 v22, v22, 0, s[34:35]
	v_cndmask_b32_e64 v19, v19, 0, s[42:43]
	v_cndmask_b32_e64 v23, v23, 0, s[66:67]
	v_cmp_eq_u32_e64 s[14:15], v28, v20
	v_cmp_eq_u32_e64 s[34:35], v28, v24
	v_cmp_eq_u32_e64 s[42:43], v29, v21
	v_cmp_eq_u32_e64 s[66:67], v29, v25
	v_cndmask_b32_e64 v20, v20, 0, s[14:15]
	v_cndmask_b32_e64 v24, v24, 0, s[34:35]
	v_cndmask_b32_e64 v21, v21, 0, s[42:43]
	v_cndmask_b32_e64 v25, v25, 0, s[66:67]
	v_max_u32_e32 v26, v18, v22
	v_max_u32_e32 v27, v19, v23
	v_max_u32_e32 v28, v20, v24
	v_max_u32_e32 v29, v21, v25
	v_max_u32_dpp v26, v26, v26 quad_perm:[1,0,3,2] row_mask:0xf bank_mask:0xf
	v_max_u32_dpp v27, v27, v27 quad_perm:[1,0,3,2] row_mask:0xf bank_mask:0xf
	v_max_u32_dpp v28, v28, v28 quad_perm:[1,0,3,2] row_mask:0xf bank_mask:0xf
	v_max_u32_dpp v29, v29, v29 quad_perm:[1,0,3,2] row_mask:0xf bank_mask:0xf
	v_max_u32_dpp v26, v26, v26 quad_perm:[2,3,0,1] row_mask:0xf bank_mask:0xf
	v_max_u32_dpp v27, v27, v27 quad_perm:[2,3,0,1] row_mask:0xf bank_mask:0xf
	v_max_u32_dpp v28, v28, v28 quad_perm:[2,3,0,1] row_mask:0xf bank_mask:0xf
	v_max_u32_dpp v29, v29, v29 quad_perm:[2,3,0,1] row_mask:0xf bank_mask:0xf
	v_max_u32_dpp v26, v26, v26 row_half_mirror row_mask:0xf bank_mask:0xf
	v_max_u32_dpp v27, v27, v27 row_half_mirror row_mask:0xf bank_mask:0xf
	v_max_u32_dpp v28, v28, v28 row_half_mirror row_mask:0xf bank_mask:0xf
	v_max_u32_dpp v29, v29, v29 row_half_mirror row_mask:0xf bank_mask:0xf
	v_max_u32_dpp v26, v26, v26 row_mirror row_mask:0xf bank_mask:0xf
	v_max_u32_dpp v27, v27, v27 row_mirror row_mask:0xf bank_mask:0xf
	v_max_u32_dpp v28, v28, v28 row_mirror row_mask:0xf bank_mask:0xf
	v_max_u32_dpp v29, v29, v29 row_mirror row_mask:0xf bank_mask:0xf
	ds_swizzle_b32 v30, v26 offset:0x401f
	ds_swizzle_b32 v31, v27 offset:0x401f
	ds_swizzle_b32 v32, v28 offset:0x401f
	ds_swizzle_b32 v33, v29 offset:0x401f
	s_waitcnt lgkmcnt(3)
	v_max_u32_e32 v26, v26, v30
	s_waitcnt lgkmcnt(2)
	v_max_u32_e32 v27, v27, v31
	s_waitcnt lgkmcnt(1)
	v_max_u32_e32 v28, v28, v32
	s_waitcnt lgkmcnt(0)
	v_max_u32_e32 v29, v29, v33
	v_mov_b32_e32 v30, v26
	v_mov_b32_e32 v31, v27
	v_mov_b32_e32 v32, v28
	v_mov_b32_e32 v33, v29
	v_permlane32_swap_b32_e32 v26, v30
	v_permlane32_swap_b32_e32 v27, v31
	v_permlane32_swap_b32_e32 v28, v32
	v_permlane32_swap_b32_e32 v29, v33
	v_max_u32_e32 v26, v26, v30
	v_max_u32_e32 v27, v27, v31
	v_max_u32_e32 v28, v28, v32
	v_max_u32_e32 v29, v29, v33
	v_cmp_eq_u32_e64 s[0:1], 5, v184
	v_and_b32_e32 v236, 127, v26
	v_sub_u32_e32 v236, 127, v236
	v_and_b32_e32 v237, 127, v27
	v_sub_u32_e32 v237, 127, v237
	v_and_b32_e32 v238, 127, v28
	v_sub_u32_e32 v238, 127, v238
	v_and_b32_e32 v239, 127, v29
	v_sub_u32_e32 v239, 127, v239
	v_cndmask_b32_e64 v82, v82, v236, s[0:1]
	v_cndmask_b32_e64 v83, v83, v237, s[0:1]
	v_cndmask_b32_e64 v84, v84, v238, s[0:1]
	v_cndmask_b32_e64 v85, v85, v239, s[0:1]
	v_cmp_eq_u32_e64 s[14:15], v26, v18
	v_cmp_eq_u32_e64 s[34:35], v26, v22
	v_cmp_eq_u32_e64 s[42:43], v27, v19
	v_cmp_eq_u32_e64 s[66:67], v27, v23
	v_cndmask_b32_e64 v18, v18, 0, s[14:15]
	v_cndmask_b32_e64 v22, v22, 0, s[34:35]
	v_cndmask_b32_e64 v19, v19, 0, s[42:43]
	v_cndmask_b32_e64 v23, v23, 0, s[66:67]
	v_cmp_eq_u32_e64 s[14:15], v28, v20
	v_cmp_eq_u32_e64 s[34:35], v28, v24
	v_cmp_eq_u32_e64 s[42:43], v29, v21
	v_cmp_eq_u32_e64 s[66:67], v29, v25
	v_cndmask_b32_e64 v20, v20, 0, s[14:15]
	v_cndmask_b32_e64 v24, v24, 0, s[34:35]
	v_cndmask_b32_e64 v21, v21, 0, s[42:43]
	v_cndmask_b32_e64 v25, v25, 0, s[66:67]
	v_max_u32_e32 v26, v18, v22
	v_max_u32_e32 v27, v19, v23
	v_max_u32_e32 v28, v20, v24
	v_max_u32_e32 v29, v21, v25
	v_max_u32_dpp v26, v26, v26 quad_perm:[1,0,3,2] row_mask:0xf bank_mask:0xf
	v_max_u32_dpp v27, v27, v27 quad_perm:[1,0,3,2] row_mask:0xf bank_mask:0xf
	v_max_u32_dpp v28, v28, v28 quad_perm:[1,0,3,2] row_mask:0xf bank_mask:0xf
	v_max_u32_dpp v29, v29, v29 quad_perm:[1,0,3,2] row_mask:0xf bank_mask:0xf
	v_max_u32_dpp v26, v26, v26 quad_perm:[2,3,0,1] row_mask:0xf bank_mask:0xf
	v_max_u32_dpp v27, v27, v27 quad_perm:[2,3,0,1] row_mask:0xf bank_mask:0xf
	v_max_u32_dpp v28, v28, v28 quad_perm:[2,3,0,1] row_mask:0xf bank_mask:0xf
	v_max_u32_dpp v29, v29, v29 quad_perm:[2,3,0,1] row_mask:0xf bank_mask:0xf
	v_max_u32_dpp v26, v26, v26 row_half_mirror row_mask:0xf bank_mask:0xf
	v_max_u32_dpp v27, v27, v27 row_half_mirror row_mask:0xf bank_mask:0xf
	v_max_u32_dpp v28, v28, v28 row_half_mirror row_mask:0xf bank_mask:0xf
	v_max_u32_dpp v29, v29, v29 row_half_mirror row_mask:0xf bank_mask:0xf
	v_max_u32_dpp v26, v26, v26 row_mirror row_mask:0xf bank_mask:0xf
	v_max_u32_dpp v27, v27, v27 row_mirror row_mask:0xf bank_mask:0xf
	v_max_u32_dpp v28, v28, v28 row_mirror row_mask:0xf bank_mask:0xf
	v_max_u32_dpp v29, v29, v29 row_mirror row_mask:0xf bank_mask:0xf
	ds_swizzle_b32 v30, v26 offset:0x401f
	ds_swizzle_b32 v31, v27 offset:0x401f
	ds_swizzle_b32 v32, v28 offset:0x401f
	ds_swizzle_b32 v33, v29 offset:0x401f
	s_waitcnt lgkmcnt(3)
; #define LAS __attribute__((address_space(3)))
; __device__ __forceinline__ void nsa_quad_pre(int bg, int quad, const bf16_t* Q, const bf16_t* KV, const bf16_t* KCMP, const bf16_t* VCMPT, const float* GN, bf16_t* ONSA, ...
;     ...
;             unsigned k0 = 0u, k1 = 0u;
;             { const int j = lane; if (j >= 1 && j <= cur - 2) { const LAS float* ps = psum + tt * 512 + 4 * j - 1; const float v = ps[0] + ps[1] + ps[2] + ps[3] + ps[4]; k0 = (__builtin_bit_cast(unsigned, v) & ~127u) | (unsigned)(127 - j); } }
;             { const int j = lane + 64; if (j <= cur - 2) { const LAS float* ps = psum + tt * 512 + 4 * j - 1; const float v = ps[0] + ps[1] + ps[2] + ps[3] + ps[4]; k1 = (__builtin_bit_cast(unsigned, v) & ~127u) | (unsigned)(127 - j); } }
;             for (int it = 0; it < 13; ++it) {
;                 unsigned m = k0 > k1 ? k0 : k1;
; #pragma unroll
;                 for (int off = 32; off >= 1; off >>= 1) { const unsigned o = (unsigned)__shfl_xor((int)m, off); m = o > m ? o : m; }
;                 if (k0 == m) k0 = 0u; if (k1 == m) k1 = 0u;
;                 if (lane == 0) selq[tt * 16 + it] = 127 - (int)(m & 127u);
;             }
;             if (lane == 0) { selq[tt * 16 + 13] = 0; selq[tt * 16 + 14] = cur - 1; selq[tt * 16 + 15] = cur; }
	v_max_u32_e32 v26, v26, v30
	s_waitcnt lgkmcnt(2)
	v_max_u32_e32 v27, v27, v31
	s_waitcnt lgkmcnt(1)
	v_max_u32_e32 v28, v28, v32
	s_waitcnt lgkmcnt(0)
	v_max_u32_e32 v29, v29, v33
	v_mov_b32_e32 v30, v26
	v_mov_b32_e32 v31, v27
	v_mov_b32_e32 v32, v28
	v_mov_b32_e32 v33, v29
	v_permlane32_swap_b32_e32 v26, v30
	v_permlane32_swap_b32_e32 v27, v31
	v_permlane32_swap_b32_e32 v28, v32
	v_permlane32_swap_b32_e32 v29, v33
	v_max_u32_e32 v26, v26, v30
	v_max_u32_e32 v27, v27, v31
	v_max_u32_e32 v28, v28, v32
	v_max_u32_e32 v29, v29, v33
	v_cmp_eq_u32_e64 s[0:1], 6, v184
	v_and_b32_e32 v236, 127, v26
	v_sub_u32_e32 v236, 127, v236
	v_and_b32_e32 v237, 127, v27
	v_sub_u32_e32 v237, 127, v237
	v_and_b32_e32 v238, 127, v28
	v_sub_u32_e32 v238, 127, v238
	v_and_b32_e32 v239, 127, v29
	v_sub_u32_e32 v239, 127, v239
	v_cndmask_b32_e64 v82, v82, v236, s[0:1]
	v_cndmask_b32_e64 v83, v83, v237, s[0:1]
	v_cndmask_b32_e64 v84, v84, v238, s[0:1]
	v_cndmask_b32_e64 v85, v85, v239, s[0:1]
	v_cmp_eq_u32_e64 s[14:15], v26, v18
	v_cmp_eq_u32_e64 s[34:35], v26, v22
	v_cmp_eq_u32_e64 s[42:43], v27, v19
	v_cmp_eq_u32_e64 s[66:67], v27, v23
	v_cndmask_b32_e64 v18, v18, 0, s[14:15]
	v_cndmask_b32_e64 v22, v22, 0, s[34:35]
	v_cndmask_b32_e64 v19, v19, 0, s[42:43]
	v_cndmask_b32_e64 v23, v23, 0, s[66:67]
	v_cmp_eq_u32_e64 s[14:15], v28, v20
	v_cmp_eq_u32_e64 s[34:35], v28, v24
	v_cmp_eq_u32_e64 s[42:43], v29, v21
	v_cmp_eq_u32_e64 s[66:67], v29, v25
	v_cndmask_b32_e64 v20, v20, 0, s[14:15]
	v_cndmask_b32_e64 v24, v24, 0, s[34:35]
	v_cndmask_b32_e64 v21, v21, 0, s[42:43]
	v_cndmask_b32_e64 v25, v25, 0, s[66:67]
	v_max_u32_e32 v26, v18, v22
	v_max_u32_e32 v27, v19, v23
	v_max_u32_e32 v28, v20, v24
	v_max_u32_e32 v29, v21, v25
	v_max_u32_dpp v26, v26, v26 quad_perm:[1,0,3,2] row_mask:0xf bank_mask:0xf
	v_max_u32_dpp v27, v27, v27 quad_perm:[1,0,3,2] row_mask:0xf bank_mask:0xf
	v_max_u32_dpp v28, v28, v28 quad_perm:[1,0,3,2] row_mask:0xf bank_mask:0xf
	v_max_u32_dpp v29, v29, v29 quad_perm:[1,0,3,2] row_mask:0xf bank_mask:0xf
	v_max_u32_dpp v26, v26, v26 quad_perm:[2,3,0,1] row_mask:0xf bank_mask:0xf
	v_max_u32_dpp v27, v27, v27 quad_perm:[2,3,0,1] row_mask:0xf bank_mask:0xf
	v_max_u32_dpp v28, v28, v28 quad_perm:[2,3,0,1] row_mask:0xf bank_mask:0xf
	v_max_u32_dpp v29, v29, v29 quad_perm:[2,3,0,1] row_mask:0xf bank_mask:0xf
	v_max_u32_dpp v26, v26, v26 row_half_mirror row_mask:0xf bank_mask:0xf
	v_max_u32_dpp v27, v27, v27 row_half_mirror row_mask:0xf bank_mask:0xf
	v_max_u32_dpp v28, v28, v28 row_half_mirror row_mask:0xf bank_mask:0xf
	v_max_u32_dpp v29, v29, v29 row_half_mirror row_mask:0xf bank_mask:0xf
	v_max_u32_dpp v26, v26, v26 row_mirror row_mask:0xf bank_mask:0xf
	v_max_u32_dpp v27, v27, v27 row_mirror row_mask:0xf bank_mask:0xf
	v_max_u32_dpp v28, v28, v28 row_mirror row_mask:0xf bank_mask:0xf
	v_max_u32_dpp v29, v29, v29 row_mirror row_mask:0xf bank_mask:0xf
	ds_swizzle_b32 v30, v26 offset:0x401f
	ds_swizzle_b32 v31, v27 offset:0x401f
	ds_swizzle_b32 v32, v28 offset:0x401f
	ds_swizzle_b32 v33, v29 offset:0x401f
	s_waitcnt lgkmcnt(3)
	v_max_u32_e32 v26, v26, v30
	s_waitcnt lgkmcnt(2)
	v_max_u32_e32 v27, v27, v31
	s_waitcnt lgkmcnt(1)
	v_max_u32_e32 v28, v28, v32
	s_waitcnt lgkmcnt(0)
	v_max_u32_e32 v29, v29, v33
	v_mov_b32_e32 v30, v26
	v_mov_b32_e32 v31, v27
	v_mov_b32_e32 v32, v28
	v_mov_b32_e32 v33, v29
	v_permlane32_swap_b32_e32 v26, v30
	v_permlane32_swap_b32_e32 v27, v31
	v_permlane32_swap_b32_e32 v28, v32
	v_permlane32_swap_b32_e32 v29, v33
	v_max_u32_e32 v26, v26, v30
	v_max_u32_e32 v27, v27, v31
	v_max_u32_e32 v28, v28, v32
	v_max_u32_e32 v29, v29, v33
	v_cmp_eq_u32_e64 s[0:1], 7, v184
	v_and_b32_e32 v236, 127, v26
	v_sub_u32_e32 v236, 127, v236
	v_and_b32_e32 v237, 127, v27
	v_sub_u32_e32 v237, 127, v237
	v_and_b32_e32 v238, 127, v28
	v_sub_u32_e32 v238, 127, v238
	v_and_b32_e32 v239, 127, v29
	v_sub_u32_e32 v239, 127, v239
	v_cndmask_b32_e64 v82, v82, v236, s[0:1]
	v_cndmask_b32_e64 v83, v83, v237, s[0:1]
	v_cndmask_b32_e64 v84, v84, v238, s[0:1]
	v_cndmask_b32_e64 v85, v85, v239, s[0:1]
	v_cmp_eq_u32_e64 s[14:15], v26, v18
	v_cmp_eq_u32_e64 s[34:35], v26, v22
	v_cmp_eq_u32_e64 s[42:43], v27, v19
	v_cmp_eq_u32_e64 s[66:67], v27, v23
	v_cndmask_b32_e64 v18, v18, 0, s[14:15]
	v_cndmask_b32_e64 v22, v22, 0, s[34:35]
	v_cndmask_b32_e64 v19, v19, 0, s[42:43]
	v_cndmask_b32_e64 v23, v23, 0, s[66:67]
	v_cmp_eq_u32_e64 s[14:15], v28, v20
	v_cmp_eq_u32_e64 s[34:35], v28, v24
	v_cmp_eq_u32_e64 s[42:43], v29, v21
	v_cmp_eq_u32_e64 s[66:67], v29, v25
	v_cndmask_b32_e64 v20, v20, 0, s[14:15]
	v_cndmask_b32_e64 v24, v24, 0, s[34:35]
	v_cndmask_b32_e64 v21, v21, 0, s[42:43]
	v_cndmask_b32_e64 v25, v25, 0, s[66:67]
	v_max_u32_e32 v26, v18, v22
	v_max_u32_e32 v27, v19, v23
	v_max_u32_e32 v28, v20, v24
	v_max_u32_e32 v29, v21, v25
	v_max_u32_dpp v26, v26, v26 quad_perm:[1,0,3,2] row_mask:0xf bank_mask:0xf
	v_max_u32_dpp v27, v27, v27 quad_perm:[1,0,3,2] row_mask:0xf bank_mask:0xf
	v_max_u32_dpp v28, v28, v28 quad_perm:[1,0,3,2] row_mask:0xf bank_mask:0xf
	v_max_u32_dpp v29, v29, v29 quad_perm:[1,0,3,2] row_mask:0xf bank_mask:0xf
	v_max_u32_dpp v26, v26, v26 quad_perm:[2,3,0,1] row_mask:0xf bank_mask:0xf
	v_max_u32_dpp v27, v27, v27 quad_perm:[2,3,0,1] row_mask:0xf bank_mask:0xf
	v_max_u32_dpp v28, v28, v28 quad_perm:[2,3,0,1] row_mask:0xf bank_mask:0xf
	v_max_u32_dpp v29, v29, v29 quad_perm:[2,3,0,1] row_mask:0xf bank_mask:0xf
	v_max_u32_dpp v26, v26, v26 row_half_mirror row_mask:0xf bank_mask:0xf
	v_max_u32_dpp v27, v27, v27 row_half_mirror row_mask:0xf bank_mask:0xf
	v_max_u32_dpp v28, v28, v28 row_half_mirror row_mask:0xf bank_mask:0xf
	v_max_u32_dpp v29, v29, v29 row_half_mirror row_mask:0xf bank_mask:0xf
	v_max_u32_dpp v26, v26, v26 row_mirror row_mask:0xf bank_mask:0xf
	v_max_u32_dpp v27, v27, v27 row_mirror row_mask:0xf bank_mask:0xf
	v_max_u32_dpp v28, v28, v28 row_mirror row_mask:0xf bank_mask:0xf
	v_max_u32_dpp v29, v29, v29 row_mirror row_mask:0xf bank_mask:0xf
	ds_swizzle_b32 v30, v26 offset:0x401f
	ds_swizzle_b32 v31, v27 offset:0x401f
	ds_swizzle_b32 v32, v28 offset:0x401f
	ds_swizzle_b32 v33, v29 offset:0x401f
	s_waitcnt lgkmcnt(3)
; #define LAS __attribute__((address_space(3)))
; __device__ __forceinline__ void nsa_quad_pre(int bg, int quad, const bf16_t* Q, const bf16_t* KV, const bf16_t* KCMP, const bf16_t* VCMPT, const float* GN, bf16_t* ONSA, ...
;     ...
;             unsigned k0 = 0u, k1 = 0u;
;             { const int j = lane; if (j >= 1 && j <= cur - 2) { const LAS float* ps = psum + tt * 512 + 4 * j - 1; const float v = ps[0] + ps[1] + ps[2] + ps[3] + ps[4]; k0 = (__builtin_bit_cast(unsigned, v) & ~127u) | (unsigned)(127 - j); } }
;             { const int j = lane + 64; if (j <= cur - 2) { const LAS float* ps = psum + tt * 512 + 4 * j - 1; const float v = ps[0] + ps[1] + ps[2] + ps[3] + ps[4]; k1 = (__builtin_bit_cast(unsigned, v) & ~127u) | (unsigned)(127 - j); } }
;             for (int it = 0; it < 13; ++it) {
;                 unsigned m = k0 > k1 ? k0 : k1;
; #pragma unroll
;                 for (int off = 32; off >= 1; off >>= 1) { const unsigned o = (unsigned)__shfl_xor((int)m, off); m = o > m ? o : m; }
;                 if (k0 == m) k0 = 0u; if (k1 == m) k1 = 0u;
;                 if (lane == 0) selq[tt * 16 + it] = 127 - (int)(m & 127u);
;             }
;             if (lane == 0) { selq[tt * 16 + 13] = 0; selq[tt * 16 + 14] = cur - 1; selq[tt * 16 + 15] = cur; }
	v_max_u32_e32 v26, v26, v30
	s_waitcnt lgkmcnt(2)
	v_max_u32_e32 v27, v27, v31
	s_waitcnt lgkmcnt(1)
	v_max_u32_e32 v28, v28, v32
	s_waitcnt lgkmcnt(0)
	v_max_u32_e32 v29, v29, v33
	v_mov_b32_e32 v30, v26
	v_mov_b32_e32 v31, v27
	v_mov_b32_e32 v32, v28
	v_mov_b32_e32 v33, v29
	v_permlane32_swap_b32_e32 v26, v30
	v_permlane32_swap_b32_e32 v27, v31
	v_permlane32_swap_b32_e32 v28, v32
	v_permlane32_swap_b32_e32 v29, v33
	v_max_u32_e32 v26, v26, v30
	v_max_u32_e32 v27, v27, v31
	v_max_u32_e32 v28, v28, v32
	v_max_u32_e32 v29, v29, v33
	v_cmp_eq_u32_e64 s[0:1], 8, v184
	v_and_b32_e32 v236, 127, v26
	v_sub_u32_e32 v236, 127, v236
	v_and_b32_e32 v237, 127, v27
	v_sub_u32_e32 v237, 127, v237
	v_and_b32_e32 v238, 127, v28
	v_sub_u32_e32 v238, 127, v238
	v_and_b32_e32 v239, 127, v29
	v_sub_u32_e32 v239, 127, v239
	v_cndmask_b32_e64 v82, v82, v236, s[0:1]
	v_cndmask_b32_e64 v83, v83, v237, s[0:1]
	v_cndmask_b32_e64 v84, v84, v238, s[0:1]
	v_cndmask_b32_e64 v85, v85, v239, s[0:1]
	v_cmp_eq_u32_e64 s[14:15], v26, v18
	v_cmp_eq_u32_e64 s[34:35], v26, v22
	v_cmp_eq_u32_e64 s[42:43], v27, v19
	v_cmp_eq_u32_e64 s[66:67], v27, v23
	v_cndmask_b32_e64 v18, v18, 0, s[14:15]
	v_cndmask_b32_e64 v22, v22, 0, s[34:35]
	v_cndmask_b32_e64 v19, v19, 0, s[42:43]
	v_cndmask_b32_e64 v23, v23, 0, s[66:67]
	v_cmp_eq_u32_e64 s[14:15], v28, v20
	v_cmp_eq_u32_e64 s[34:35], v28, v24
	v_cmp_eq_u32_e64 s[42:43], v29, v21
	v_cmp_eq_u32_e64 s[66:67], v29, v25
	v_cndmask_b32_e64 v20, v20, 0, s[14:15]
	v_cndmask_b32_e64 v24, v24, 0, s[34:35]
	v_cndmask_b32_e64 v21, v21, 0, s[42:43]
	v_cndmask_b32_e64 v25, v25, 0, s[66:67]
	v_max_u32_e32 v26, v18, v22
	v_max_u32_e32 v27, v19, v23
	v_max_u32_e32 v28, v20, v24
	v_max_u32_e32 v29, v21, v25
	v_max_u32_dpp v26, v26, v26 quad_perm:[1,0,3,2] row_mask:0xf bank_mask:0xf
	v_max_u32_dpp v27, v27, v27 quad_perm:[1,0,3,2] row_mask:0xf bank_mask:0xf
	v_max_u32_dpp v28, v28, v28 quad_perm:[1,0,3,2] row_mask:0xf bank_mask:0xf
	v_max_u32_dpp v29, v29, v29 quad_perm:[1,0,3,2] row_mask:0xf bank_mask:0xf
	v_max_u32_dpp v26, v26, v26 quad_perm:[2,3,0,1] row_mask:0xf bank_mask:0xf
	v_max_u32_dpp v27, v27, v27 quad_perm:[2,3,0,1] row_mask:0xf bank_mask:0xf
	v_max_u32_dpp v28, v28, v28 quad_perm:[2,3,0,1] row_mask:0xf bank_mask:0xf
	v_max_u32_dpp v29, v29, v29 quad_perm:[2,3,0,1] row_mask:0xf bank_mask:0xf
	v_max_u32_dpp v26, v26, v26 row_half_mirror row_mask:0xf bank_mask:0xf
	v_max_u32_dpp v27, v27, v27 row_half_mirror row_mask:0xf bank_mask:0xf
	v_max_u32_dpp v28, v28, v28 row_half_mirror row_mask:0xf bank_mask:0xf
	v_max_u32_dpp v29, v29, v29 row_half_mirror row_mask:0xf bank_mask:0xf
	v_max_u32_dpp v26, v26, v26 row_mirror row_mask:0xf bank_mask:0xf
	v_max_u32_dpp v27, v27, v27 row_mirror row_mask:0xf bank_mask:0xf
	v_max_u32_dpp v28, v28, v28 row_mirror row_mask:0xf bank_mask:0xf
	v_max_u32_dpp v29, v29, v29 row_mirror row_mask:0xf bank_mask:0xf
	ds_swizzle_b32 v30, v26 offset:0x401f
	ds_swizzle_b32 v31, v27 offset:0x401f
	ds_swizzle_b32 v32, v28 offset:0x401f
	ds_swizzle_b32 v33, v29 offset:0x401f
	s_waitcnt lgkmcnt(3)
	v_max_u32_e32 v26, v26, v30
	s_waitcnt lgkmcnt(2)
	v_max_u32_e32 v27, v27, v31
	s_waitcnt lgkmcnt(1)
	v_max_u32_e32 v28, v28, v32
	s_waitcnt lgkmcnt(0)
	v_max_u32_e32 v29, v29, v33
	v_mov_b32_e32 v30, v26
	v_mov_b32_e32 v31, v27
	v_mov_b32_e32 v32, v28
	v_mov_b32_e32 v33, v29
	v_permlane32_swap_b32_e32 v26, v30
	v_permlane32_swap_b32_e32 v27, v31
	v_permlane32_swap_b32_e32 v28, v32
	v_permlane32_swap_b32_e32 v29, v33
	v_max_u32_e32 v26, v26, v30
	v_max_u32_e32 v27, v27, v31
	v_max_u32_e32 v28, v28, v32
	v_max_u32_e32 v29, v29, v33
	v_cmp_eq_u32_e64 s[0:1], 9, v184
	v_and_b32_e32 v236, 127, v26
	v_sub_u32_e32 v236, 127, v236
	v_and_b32_e32 v237, 127, v27
	v_sub_u32_e32 v237, 127, v237
	v_and_b32_e32 v238, 127, v28
	v_sub_u32_e32 v238, 127, v238
	v_and_b32_e32 v239, 127, v29
	v_sub_u32_e32 v239, 127, v239
	v_cndmask_b32_e64 v82, v82, v236, s[0:1]
	v_cndmask_b32_e64 v83, v83, v237, s[0:1]
	v_cndmask_b32_e64 v84, v84, v238, s[0:1]
	v_cndmask_b32_e64 v85, v85, v239, s[0:1]
	v_cmp_eq_u32_e64 s[14:15], v26, v18
	v_cmp_eq_u32_e64 s[34:35], v26, v22
	v_cmp_eq_u32_e64 s[42:43], v27, v19
	v_cmp_eq_u32_e64 s[66:67], v27, v23
	v_cndmask_b32_e64 v18, v18, 0, s[14:15]
	v_cndmask_b32_e64 v22, v22, 0, s[34:35]
	v_cndmask_b32_e64 v19, v19, 0, s[42:43]
	v_cndmask_b32_e64 v23, v23, 0, s[66:67]
	v_cmp_eq_u32_e64 s[14:15], v28, v20
	v_cmp_eq_u32_e64 s[34:35], v28, v24
	v_cmp_eq_u32_e64 s[42:43], v29, v21
	v_cmp_eq_u32_e64 s[66:67], v29, v25
	v_cndmask_b32_e64 v20, v20, 0, s[14:15]
	v_cndmask_b32_e64 v24, v24, 0, s[34:35]
	v_cndmask_b32_e64 v21, v21, 0, s[42:43]
	v_cndmask_b32_e64 v25, v25, 0, s[66:67]
	v_max_u32_e32 v26, v18, v22
	v_max_u32_e32 v27, v19, v23
	v_max_u32_e32 v28, v20, v24
	v_max_u32_e32 v29, v21, v25
	v_max_u32_dpp v26, v26, v26 quad_perm:[1,0,3,2] row_mask:0xf bank_mask:0xf
	v_max_u32_dpp v27, v27, v27 quad_perm:[1,0,3,2] row_mask:0xf bank_mask:0xf
	v_max_u32_dpp v28, v28, v28 quad_perm:[1,0,3,2] row_mask:0xf bank_mask:0xf
	v_max_u32_dpp v29, v29, v29 quad_perm:[1,0,3,2] row_mask:0xf bank_mask:0xf
	v_max_u32_dpp v26, v26, v26 quad_perm:[2,3,0,1] row_mask:0xf bank_mask:0xf
	v_max_u32_dpp v27, v27, v27 quad_perm:[2,3,0,1] row_mask:0xf bank_mask:0xf
	v_max_u32_dpp v28, v28, v28 quad_perm:[2,3,0,1] row_mask:0xf bank_mask:0xf
	v_max_u32_dpp v29, v29, v29 quad_perm:[2,3,0,1] row_mask:0xf bank_mask:0xf
	v_max_u32_dpp v26, v26, v26 row_half_mirror row_mask:0xf bank_mask:0xf
	v_max_u32_dpp v27, v27, v27 row_half_mirror row_mask:0xf bank_mask:0xf
	v_max_u32_dpp v28, v28, v28 row_half_mirror row_mask:0xf bank_mask:0xf
	v_max_u32_dpp v29, v29, v29 row_half_mirror row_mask:0xf bank_mask:0xf
	v_max_u32_dpp v26, v26, v26 row_mirror row_mask:0xf bank_mask:0xf
	v_max_u32_dpp v27, v27, v27 row_mirror row_mask:0xf bank_mask:0xf
	v_max_u32_dpp v28, v28, v28 row_mirror row_mask:0xf bank_mask:0xf
	v_max_u32_dpp v29, v29, v29 row_mirror row_mask:0xf bank_mask:0xf
	ds_swizzle_b32 v30, v26 offset:0x401f
	ds_swizzle_b32 v31, v27 offset:0x401f
	ds_swizzle_b32 v32, v28 offset:0x401f
	ds_swizzle_b32 v33, v29 offset:0x401f
	s_waitcnt lgkmcnt(3)
; #define LAS __attribute__((address_space(3)))
; __device__ __forceinline__ void nsa_quad_pre(int bg, int quad, const bf16_t* Q, const bf16_t* KV, const bf16_t* KCMP, const bf16_t* VCMPT, const float* GN, bf16_t* ONSA, ...
;     ...
;             unsigned k0 = 0u, k1 = 0u;
;             { const int j = lane; if (j >= 1 && j <= cur - 2) { const LAS float* ps = psum + tt * 512 + 4 * j - 1; const float v = ps[0] + ps[1] + ps[2] + ps[3] + ps[4]; k0 = (__builtin_bit_cast(unsigned, v) & ~127u) | (unsigned)(127 - j); } }
;             { const int j = lane + 64; if (j <= cur - 2) { const LAS float* ps = psum + tt * 512 + 4 * j - 1; const float v = ps[0] + ps[1] + ps[2] + ps[3] + ps[4]; k1 = (__builtin_bit_cast(unsigned, v) & ~127u) | (unsigned)(127 - j); } }
;             for (int it = 0; it < 13; ++it) {
;                 unsigned m = k0 > k1 ? k0 : k1;
; #pragma unroll
;                 for (int off = 32; off >= 1; off >>= 1) { const unsigned o = (unsigned)__shfl_xor((int)m, off); m = o > m ? o : m; }
;                 if (k0 == m) k0 = 0u; if (k1 == m) k1 = 0u;
;                 if (lane == 0) selq[tt * 16 + it] = 127 - (int)(m & 127u);
	v_max_u32_e32 v26, v26, v30
	s_waitcnt lgkmcnt(2)
	v_max_u32_e32 v27, v27, v31
	s_waitcnt lgkmcnt(1)
	v_max_u32_e32 v28, v28, v32
	s_waitcnt lgkmcnt(0)
	v_max_u32_e32 v29, v29, v33
	v_mov_b32_e32 v30, v26
	v_mov_b32_e32 v31, v27
	v_mov_b32_e32 v32, v28
	v_mov_b32_e32 v33, v29
	v_permlane32_swap_b32_e32 v26, v30
	v_permlane32_swap_b32_e32 v27, v31
	v_permlane32_swap_b32_e32 v28, v32
	v_permlane32_swap_b32_e32 v29, v33
	v_max_u32_e32 v26, v26, v30
	v_max_u32_e32 v27, v27, v31
	v_max_u32_e32 v28, v28, v32
	v_max_u32_e32 v29, v29, v33
	v_cmp_eq_u32_e64 s[0:1], 10, v184
	v_and_b32_e32 v236, 127, v26
	v_sub_u32_e32 v236, 127, v236
	v_and_b32_e32 v237, 127, v27
	v_sub_u32_e32 v237, 127, v237
	v_and_b32_e32 v238, 127, v28
	v_sub_u32_e32 v238, 127, v238
	v_and_b32_e32 v239, 127, v29
	v_sub_u32_e32 v239, 127, v239
	v_cndmask_b32_e64 v82, v82, v236, s[0:1]
	v_cndmask_b32_e64 v83, v83, v237, s[0:1]
	v_cndmask_b32_e64 v84, v84, v238, s[0:1]
	v_cndmask_b32_e64 v85, v85, v239, s[0:1]
	v_cmp_eq_u32_e64 s[14:15], v26, v18
	v_cmp_eq_u32_e64 s[34:35], v26, v22
	v_cmp_eq_u32_e64 s[42:43], v27, v19
	v_cmp_eq_u32_e64 s[66:67], v27, v23
	v_cndmask_b32_e64 v18, v18, 0, s[14:15]
	v_cndmask_b32_e64 v22, v22, 0, s[34:35]
	v_cndmask_b32_e64 v19, v19, 0, s[42:43]
	v_cndmask_b32_e64 v23, v23, 0, s[66:67]
	v_cmp_eq_u32_e64 s[14:15], v28, v20
	v_cmp_eq_u32_e64 s[34:35], v28, v24
	v_cmp_eq_u32_e64 s[42:43], v29, v21
	v_cmp_eq_u32_e64 s[66:67], v29, v25
	v_cndmask_b32_e64 v20, v20, 0, s[14:15]
	v_cndmask_b32_e64 v24, v24, 0, s[34:35]
	v_cndmask_b32_e64 v21, v21, 0, s[42:43]
	v_cndmask_b32_e64 v25, v25, 0, s[66:67]
	v_max_u32_e32 v26, v18, v22
	v_max_u32_e32 v27, v19, v23
	v_max_u32_e32 v28, v20, v24
	v_max_u32_e32 v29, v21, v25
	v_max_u32_dpp v26, v26, v26 quad_perm:[1,0,3,2] row_mask:0xf bank_mask:0xf
	v_max_u32_dpp v27, v27, v27 quad_perm:[1,0,3,2] row_mask:0xf bank_mask:0xf
	v_max_u32_dpp v28, v28, v28 quad_perm:[1,0,3,2] row_mask:0xf bank_mask:0xf
	v_max_u32_dpp v29, v29, v29 quad_perm:[1,0,3,2] row_mask:0xf bank_mask:0xf
	v_max_u32_dpp v26, v26, v26 quad_perm:[2,3,0,1] row_mask:0xf bank_mask:0xf
	v_max_u32_dpp v27, v27, v27 quad_perm:[2,3,0,1] row_mask:0xf bank_mask:0xf
	v_max_u32_dpp v28, v28, v28 quad_perm:[2,3,0,1] row_mask:0xf bank_mask:0xf
	v_max_u32_dpp v29, v29, v29 quad_perm:[2,3,0,1] row_mask:0xf bank_mask:0xf
	v_max_u32_dpp v26, v26, v26 row_half_mirror row_mask:0xf bank_mask:0xf
	v_max_u32_dpp v27, v27, v27 row_half_mirror row_mask:0xf bank_mask:0xf
	v_max_u32_dpp v28, v28, v28 row_half_mirror row_mask:0xf bank_mask:0xf
	v_max_u32_dpp v29, v29, v29 row_half_mirror row_mask:0xf bank_mask:0xf
	v_max_u32_dpp v26, v26, v26 row_mirror row_mask:0xf bank_mask:0xf
	v_max_u32_dpp v27, v27, v27 row_mirror row_mask:0xf bank_mask:0xf
	v_max_u32_dpp v28, v28, v28 row_mirror row_mask:0xf bank_mask:0xf
	v_max_u32_dpp v29, v29, v29 row_mirror row_mask:0xf bank_mask:0xf
	ds_swizzle_b32 v30, v26 offset:0x401f
	ds_swizzle_b32 v31, v27 offset:0x401f
	ds_swizzle_b32 v32, v28 offset:0x401f
	ds_swizzle_b32 v33, v29 offset:0x401f
	s_waitcnt lgkmcnt(3)
	v_max_u32_e32 v26, v26, v30
	s_waitcnt lgkmcnt(2)
	v_max_u32_e32 v27, v27, v31
	s_waitcnt lgkmcnt(1)
	v_max_u32_e32 v28, v28, v32
	s_waitcnt lgkmcnt(0)
; __device__ __forceinline__ void nsa_quad_pre(int bg, int quad, const bf16_t* Q, const bf16_t* KV, const bf16_t* KCMP, const bf16_t* VCMPT, const float* GN, bf16_t* ONSA, ...
;     ...
;             for (int it = 0; it < 13; ++it) {
;                 unsigned m = k0 > k1 ? k0 : k1;
; #pragma unroll
;                 for (int off = 32; off >= 1; off >>= 1) { const unsigned o = (unsigned)__shfl_xor((int)m, off); m = o > m ? o : m; }
;                 if (k0 == m) k0 = 0u; if (k1 == m) k1 = 0u;
;                 if (lane == 0) selq[tt * 16 + it] = 127 - (int)(m & 127u);
;             }
;             if (lane == 0) { selq[tt * 16 + 13] = 0; selq[tt * 16 + 14] = cur - 1; selq[tt * 16 + 15] = cur; }
	v_max_u32_e32 v29, v29, v33
	v_mov_b32_e32 v30, v26
	v_mov_b32_e32 v31, v27
	v_mov_b32_e32 v32, v28
	v_mov_b32_e32 v33, v29
	v_permlane32_swap_b32_e32 v26, v30
	v_permlane32_swap_b32_e32 v27, v31
	v_permlane32_swap_b32_e32 v28, v32
	v_permlane32_swap_b32_e32 v29, v33
	v_max_u32_e32 v26, v26, v30
	v_max_u32_e32 v27, v27, v31
	v_max_u32_e32 v28, v28, v32
	v_max_u32_e32 v29, v29, v33
	v_cmp_eq_u32_e64 s[0:1], 11, v184
	v_and_b32_e32 v236, 127, v26
	v_sub_u32_e32 v236, 127, v236
	v_and_b32_e32 v237, 127, v27
	v_sub_u32_e32 v237, 127, v237
	v_and_b32_e32 v238, 127, v28
	v_sub_u32_e32 v238, 127, v238
	v_and_b32_e32 v239, 127, v29
	v_sub_u32_e32 v239, 127, v239
	v_cndmask_b32_e64 v82, v82, v236, s[0:1]
	v_cndmask_b32_e64 v83, v83, v237, s[0:1]
	v_cndmask_b32_e64 v84, v84, v238, s[0:1]
	v_cndmask_b32_e64 v85, v85, v239, s[0:1]
	v_cmp_eq_u32_e64 s[14:15], v26, v18
	v_cmp_eq_u32_e64 s[34:35], v26, v22
	v_cmp_eq_u32_e64 s[42:43], v27, v19
	v_cmp_eq_u32_e64 s[66:67], v27, v23
	v_cndmask_b32_e64 v18, v18, 0, s[14:15]
	v_cndmask_b32_e64 v22, v22, 0, s[34:35]
	v_cndmask_b32_e64 v19, v19, 0, s[42:43]
	v_cndmask_b32_e64 v23, v23, 0, s[66:67]
	v_cmp_eq_u32_e64 s[14:15], v28, v20
	v_cmp_eq_u32_e64 s[34:35], v28, v24
	v_cmp_eq_u32_e64 s[42:43], v29, v21
	v_cmp_eq_u32_e64 s[66:67], v29, v25
	v_cndmask_b32_e64 v20, v20, 0, s[14:15]
	v_cndmask_b32_e64 v24, v24, 0, s[34:35]
	v_cndmask_b32_e64 v21, v21, 0, s[42:43]
	v_cndmask_b32_e64 v25, v25, 0, s[66:67]
	v_max_u32_e32 v26, v18, v22
	v_max_u32_e32 v27, v19, v23
	v_max_u32_e32 v28, v20, v24
	v_max_u32_e32 v29, v21, v25
	v_max_u32_dpp v26, v26, v26 quad_perm:[1,0,3,2] row_mask:0xf bank_mask:0xf
	v_max_u32_dpp v27, v27, v27 quad_perm:[1,0,3,2] row_mask:0xf bank_mask:0xf
	v_max_u32_dpp v28, v28, v28 quad_perm:[1,0,3,2] row_mask:0xf bank_mask:0xf
	v_max_u32_dpp v29, v29, v29 quad_perm:[1,0,3,2] row_mask:0xf bank_mask:0xf
	v_max_u32_dpp v26, v26, v26 quad_perm:[2,3,0,1] row_mask:0xf bank_mask:0xf
	v_max_u32_dpp v27, v27, v27 quad_perm:[2,3,0,1] row_mask:0xf bank_mask:0xf
	v_max_u32_dpp v28, v28, v28 quad_perm:[2,3,0,1] row_mask:0xf bank_mask:0xf
	v_max_u32_dpp v29, v29, v29 quad_perm:[2,3,0,1] row_mask:0xf bank_mask:0xf
	v_max_u32_dpp v26, v26, v26 row_half_mirror row_mask:0xf bank_mask:0xf
	v_max_u32_dpp v27, v27, v27 row_half_mirror row_mask:0xf bank_mask:0xf
	v_max_u32_dpp v28, v28, v28 row_half_mirror row_mask:0xf bank_mask:0xf
	v_max_u32_dpp v29, v29, v29 row_half_mirror row_mask:0xf bank_mask:0xf
	v_max_u32_dpp v26, v26, v26 row_mirror row_mask:0xf bank_mask:0xf
	v_max_u32_dpp v27, v27, v27 row_mirror row_mask:0xf bank_mask:0xf
	v_max_u32_dpp v28, v28, v28 row_mirror row_mask:0xf bank_mask:0xf
	v_max_u32_dpp v29, v29, v29 row_mirror row_mask:0xf bank_mask:0xf
	ds_swizzle_b32 v30, v26 offset:0x401f
	ds_swizzle_b32 v31, v27 offset:0x401f
	ds_swizzle_b32 v32, v28 offset:0x401f
	ds_swizzle_b32 v33, v29 offset:0x401f
	s_waitcnt lgkmcnt(3)
	v_max_u32_e32 v26, v26, v30
	s_waitcnt lgkmcnt(2)
	v_max_u32_e32 v27, v27, v31
	s_waitcnt lgkmcnt(1)
	v_max_u32_e32 v28, v28, v32
	s_waitcnt lgkmcnt(0)
	v_max_u32_e32 v29, v29, v33
	v_mov_b32_e32 v30, v26
	v_mov_b32_e32 v31, v27
	v_mov_b32_e32 v32, v28
	v_mov_b32_e32 v33, v29
	v_permlane32_swap_b32_e32 v26, v30
	v_permlane32_swap_b32_e32 v27, v31
	v_permlane32_swap_b32_e32 v28, v32
	v_permlane32_swap_b32_e32 v29, v33
	v_max_u32_e32 v26, v26, v30
	v_max_u32_e32 v27, v27, v31
	v_max_u32_e32 v28, v28, v32
	v_max_u32_e32 v29, v29, v33
	v_cmp_eq_u32_e64 s[0:1], 12, v184
	v_and_b32_e32 v236, 127, v26
	v_sub_u32_e32 v236, 127, v236
	v_and_b32_e32 v237, 127, v27
	v_sub_u32_e32 v237, 127, v237
	v_and_b32_e32 v238, 127, v28
	v_sub_u32_e32 v238, 127, v238
	v_and_b32_e32 v239, 127, v29
	v_sub_u32_e32 v239, 127, v239
	v_cndmask_b32_e64 v82, v82, v236, s[0:1]
	v_cndmask_b32_e64 v83, v83, v237, s[0:1]
	v_cndmask_b32_e64 v84, v84, v238, s[0:1]
	v_cndmask_b32_e64 v85, v85, v239, s[0:1]
	s_add_i32 s19, s18, -1
	v_mov_b32_e32 v236, s19
	v_mov_b32_e32 v237, s18
	v_cmp_eq_u32_e64 s[14:15], 14, v184
	v_cmp_eq_u32_e64 s[34:35], 15, v184
	s_nop 0
	v_cndmask_b32_e64 v82, v82, v236, s[14:15]
	v_cndmask_b32_e64 v82, v82, v237, s[34:35]
	v_cndmask_b32_e64 v83, v83, v236, s[14:15]
	v_cndmask_b32_e64 v83, v83, v237, s[34:35]
	v_cndmask_b32_e64 v84, v84, v236, s[14:15]
	v_cndmask_b32_e64 v84, v84, v237, s[34:35]
	v_cndmask_b32_e64 v85, v85, v236, s[14:15]
	v_cndmask_b32_e64 v85, v85, v237, s[34:35]
	s_and_saveexec_b64 s[42:43], s[6:7]
	ds_write_b32 v196, v82 offset:51264
	ds_write_b32 v196, v83 offset:51328
	ds_write_b32 v196, v84 offset:51392
	ds_write_b32 v196, v85 offset:51456
	s_or_b64 exec, exec, s[42:43]
	s_branch .Ltopk_done_q0

; #define LAS __attribute__((address_space(3)))
; __device__ __forceinline__ float ex2(float x) { return __builtin_amdgcn_exp2f(x); }
; __device__ __forceinline__ void cmp_sm1(const f32x4 (&sc)[4], int gr, int t0, const LAS float* bt, float (&ls)[4], int r16) {
; #pragma unroll
;     for (int cc = 0; cc < 4; ++cc) {
;         const int cend = (gr * 64 + cc * 16 + r16) * 16 + 31;
; #pragma unroll
;         for (int i = 0; i < 4; ++i) { const int dist = t0 + i - cend; ls[i] += dist >= 0 ? ex2(sc[cc][i] + bt[clampd(dist)]) : 0.f; }
;     }
; }
; __device__ __forceinline__ void nsa_quad_pre(int bg, int quad, const bf16_t* Q, const bf16_t* KV, const bf16_t* KCMP, const bf16_t* VCMPT, const float* GN, bf16_t* ONSA, ...
;     ...
;     const int tl = t0 + 3, nvmax = tl >= 31 ? ((tl - 31) >> 4) + 1 : 0, ngr = (nvmax + 63) >> 6;
;     if (ngr > 0) {
;         float ls[4] = {0.f, 0.f, 0.f, 0.f};
;         load_k(KF, KP_C(0));
;         for (int gr = 0; gr < ngr; ++gr) {
;             qk_scores(KF, qf, sc);
;             load_k(KF, KP_C(gr + 1 < ngr ? gr + 1 : 0));
;             cmp_sm1(sc, gr, t0, bt, ls, r16);
;         }
.Ltopk_done_q0:
	s_nop 0
	s_waitcnt lgkmcnt(0)
	s_lshr_b32 s15, s97, 13
	s_lshl_b32 s15, s15, 2
	s_and_b32 s1, s88, 3
	s_or_b32 s15, s15, s1
	s_lshl_b32 s15, s15, 16
	s_add_u32 s66, s30, 0x38110000
	s_addc_u32 s67, s31, 0
	s_add_u32 s66, s66, s15
	s_addc_u32 s67, s67, 0
	s_add_u32 s68, s30, 0x38210000
	s_addc_u32 s69, s31, 0
	s_add_u32 s68, s68, s15
	s_addc_u32 s69, s69, 0
	s_lshl_b32 s47, s18, 6
	s_add_i32 s47, s47, s80
	s_add_i32 s47, s47, 4
	v_mov_b32_e32 v2, 0
	v_mov_b32_e32 v3, 0
	v_mov_b32_e32 v4, 0
	v_mov_b32_e32 v5, 0
	v_mov_b32_e32 v6, 0
	v_mov_b32_e32 v7, 0
	v_mov_b32_e32 v8, 0
	v_mov_b32_e32 v9, 0
	v_mov_b32_e32 v10, 0
	v_mov_b32_e32 v11, 0
	v_mov_b32_e32 v12, 0
	v_mov_b32_e32 v13, 0
	v_mov_b32_e32 v14, 0
	v_mov_b32_e32 v15, 0
	v_mov_b32_e32 v16, 0
	v_mov_b32_e32 v17, 0
	s_sub_i32 s0, s47, 28
	s_ashr_i32 s0, s0, 4
	s_add_i32 s0, s0, 64
	s_ashr_i32 s53, s0, 6
	s_cmp_gt_i32 s47, 27
	s_cselect_b32 s53, s53, 0
	s_cmp_lt_i32 s53, 1
	s_cbranch_scc1 .Lcmp_none_q1
	s_sub_i32 s0, s47, 2063
	s_ashr_i32 s52, s0, 10
	s_add_i32 s52, s52, 1
	s_max_i32 s52, s52, 0
	s_min_i32 s52, s52, s53
	v_add_u32_e32 v99, s47, v172
	v_and_b32_e32 v98, 15, v184
	v_mov_b32_e32 v170, 0
	s_mov_b32 s57, 0
	s_lshl_b32 s0, s57, 13
	s_add_u32 s70, s66, s0
	s_addc_u32 s71, s67, 0
	global_load_dwordx4 v[50:53], v174, s[70:71] offset:0
	global_load_dwordx4 v[54:57], v174, s[70:71] offset:64
	global_load_dwordx4 v[58:61], v174, s[70:71] offset:512
	global_load_dwordx4 v[62:65], v174, s[70:71] offset:576
	global_load_dwordx4 v[66:69], v175, s[70:71] offset:0
	global_load_dwordx4 v[70:73], v175, s[70:71] offset:64
	global_load_dwordx4 v[74:77], v175, s[70:71] offset:512
	global_load_dwordx4 v[78:81], v175, s[70:71] offset:576
	s_mov_b32 s57, 0
.Lcmp_top_q1p1:
	s_nop 1
	s_cmp_lt_i32 s57, s52
	s_cbranch_scc0 .Lcmp_gen_q1p1
	s_waitcnt vmcnt(0)
	v_mov_b32_e32 v228, v225
	v_mov_b32_e32 v229, v225
	v_mov_b32_e32 v230, v225
	v_mov_b32_e32 v231, v225
	s_nop 1
	v_mfma_f32_16x16x32_bf16 v[18:21], v[50:53], v[42:45], v[228:231]
	v_mfma_f32_16x16x32_bf16 v[18:21], v[54:57], v[46:49], v[18:21]
	v_mfma_f32_16x16x32_bf16 v[22:25], v[58:61], v[42:45], v[228:231]
	v_mfma_f32_16x16x32_bf16 v[22:25], v[62:65], v[46:49], v[22:25]
	v_mfma_f32_16x16x32_bf16 v[26:29], v[66:69], v[42:45], v[228:231]
	v_mfma_f32_16x16x32_bf16 v[26:29], v[70:73], v[46:49], v[26:29]
	v_mfma_f32_16x16x32_bf16 v[30:33], v[74:77], v[42:45], v[228:231]
	v_mfma_f32_16x16x32_bf16 v[30:33], v[78:81], v[46:49], v[30:33]
	s_add_i32 s1, s57, 1
	s_cmp_lt_i32 s1, s53
	s_cselect_b32 s1, s1, 0
	s_lshl_b32 s0, s1, 13
	s_add_u32 s70, s66, s0
	s_addc_u32 s71, s67, 0
	global_load_dwordx4 v[50:53], v174, s[70:71] offset:0
	global_load_dwordx4 v[54:57], v174, s[70:71] offset:64
	global_load_dwordx4 v[58:61], v174, s[70:71] offset:512
	global_load_dwordx4 v[62:65], v174, s[70:71] offset:576
	global_load_dwordx4 v[66:69], v175, s[70:71] offset:0
	global_load_dwordx4 v[70:73], v175, s[70:71] offset:64
	global_load_dwordx4 v[74:77], v175, s[70:71] offset:512
	global_load_dwordx4 v[78:81], v175, s[70:71] offset:576
	v_exp_f32_e32 v18, v18
	v_exp_f32_e32 v19, v19
	v_exp_f32_e32 v20, v20
	v_exp_f32_e32 v21, v21
	v_exp_f32_e32 v22, v22
	v_exp_f32_e32 v23, v23
	v_exp_f32_e32 v24, v24
	v_exp_f32_e32 v25, v25
	v_exp_f32_e32 v26, v26
	v_exp_f32_e32 v27, v27
	v_exp_f32_e32 v28, v28
	v_exp_f32_e32 v29, v29
	v_exp_f32_e32 v30, v30
	v_exp_f32_e32 v31, v31
	v_exp_f32_e32 v32, v32
	v_exp_f32_e32 v33, v33
	v_add_f32_e32 v170, v170, v18
	v_add_f32_e32 v170, v170, v19
	v_add_f32_e32 v170, v170, v20
	v_add_f32_e32 v170, v170, v21
	v_add_f32_e32 v170, v170, v22
	v_add_f32_e32 v170, v170, v23
	v_add_f32_e32 v170, v170, v24
	v_add_f32_e32 v170, v170, v25
	v_add_f32_e32 v170, v170, v26
	v_add_f32_e32 v170, v170, v27
	v_add_f32_e32 v170, v170, v28
	v_add_f32_e32 v170, v170, v29
	v_add_f32_e32 v170, v170, v30
	v_add_f32_e32 v170, v170, v31
	v_add_f32_e32 v170, v170, v32
	v_add_f32_e32 v170, v170, v33
	s_branch .Lcmp_nx_q1p1
; #define LAS __attribute__((address_space(3)))
; __device__ __forceinline__ float ex2(float x) { return __builtin_amdgcn_exp2f(x); }
; __device__ __forceinline__ void cmp_sm1(const f32x4 (&sc)[4], int gr, int t0, const LAS float* bt, float (&ls)[4], int r16) {
; #pragma unroll
;     for (int cc = 0; cc < 4; ++cc) {
;         const int cend = (gr * 64 + cc * 16 + r16) * 16 + 31;
; #pragma unroll
;         for (int i = 0; i < 4; ++i) { const int dist = t0 + i - cend; ls[i] += dist >= 0 ? ex2(sc[cc][i] + bt[clampd(dist)]) : 0.f; }
;     }
; }
; __device__ __forceinline__ void nsa_quad_pre(int bg, int quad, const bf16_t* Q, const bf16_t* KV, const bf16_t* KCMP, const bf16_t* VCMPT, const float* GN, bf16_t* ONSA, ...
;     ...
;         for (int gr = 0; gr < ngr; ++gr) {
;             qk_scores(KF, qf, sc);
;             load_k(KF, KP_C(gr + 1 < ngr ? gr + 1 : 0));
;             cmp_sm1(sc, gr, t0, bt, ls, r16);
;         }
.Lcmp_gen_q1p1:
	s_nop 1
	s_waitcnt vmcnt(0)
	v_mfma_f32_16x16x32_bf16 v[18:21], v[50:53], v[42:45], 0
	v_mfma_f32_16x16x32_bf16 v[18:21], v[54:57], v[46:49], v[18:21]
	v_mfma_f32_16x16x32_bf16 v[22:25], v[58:61], v[42:45], 0
	v_mfma_f32_16x16x32_bf16 v[22:25], v[62:65], v[46:49], v[22:25]
	v_mfma_f32_16x16x32_bf16 v[26:29], v[66:69], v[42:45], 0
	v_mfma_f32_16x16x32_bf16 v[26:29], v[70:73], v[46:49], v[26:29]
	v_mfma_f32_16x16x32_bf16 v[30:33], v[74:77], v[42:45], 0
	v_mfma_f32_16x16x32_bf16 v[30:33], v[78:81], v[46:49], v[30:33]
	s_add_i32 s1, s57, 1
	s_cmp_lt_i32 s1, s53
	s_cselect_b32 s1, s1, 0
	s_lshl_b32 s0, s1, 13
	s_add_u32 s70, s66, s0
	s_addc_u32 s71, s67, 0
	global_load_dwordx4 v[50:53], v174, s[70:71] offset:0
	global_load_dwordx4 v[54:57], v174, s[70:71] offset:64
	global_load_dwordx4 v[58:61], v174, s[70:71] offset:512
	global_load_dwordx4 v[62:65], v174, s[70:71] offset:576
	global_load_dwordx4 v[66:69], v175, s[70:71] offset:0
	global_load_dwordx4 v[70:73], v175, s[70:71] offset:64
	global_load_dwordx4 v[74:77], v175, s[70:71] offset:512
	global_load_dwordx4 v[78:81], v175, s[70:71] offset:576
	s_lshl_b32 s0, s57, 10
	v_subrev_u32_e32 v224, s0, v99
	v_add_u32_e32 v232, 0x0, v224
	v_min_u32_e32 v232, 0x400, v232
	v_lshl_add_u32 v232, v232, 2, v173
	ds_read_b32 v216, v232
	v_add_u32_e32 v232, 0xfffffff0, v224
	v_min_u32_e32 v232, 0x400, v232
	v_lshl_add_u32 v232, v232, 2, v173
	ds_read_b32 v217, v232
	v_add_u32_e32 v232, 0xffffffe0, v224
	v_min_u32_e32 v232, 0x400, v232
	v_lshl_add_u32 v232, v232, 2, v173
	ds_read_b32 v218, v232
	v_add_u32_e32 v232, 0xffffffd0, v224
	v_min_u32_e32 v232, 0x400, v232
	v_lshl_add_u32 v232, v232, 2, v173
	ds_read_b32 v219, v232
	v_add_u32_e32 v232, 0xffffffc0, v224
	v_min_u32_e32 v232, 0x400, v232
	v_lshl_add_u32 v232, v232, 2, v173
	ds_read_b32 v220, v232
	v_add_u32_e32 v232, 0xffffffb0, v224
	v_min_u32_e32 v232, 0x400, v232
	v_lshl_add_u32 v232, v232, 2, v173
	ds_read_b32 v221, v232
	v_add_u32_e32 v232, 0xffffffa0, v224
	v_min_u32_e32 v232, 0x400, v232
	v_lshl_add_u32 v232, v232, 2, v173
	ds_read_b32 v222, v232
	v_add_u32_e32 v232, 0xffffff90, v224
	v_min_u32_e32 v232, 0x400, v232
	v_lshl_add_u32 v232, v232, 2, v173
	ds_read_b32 v223, v232
	s_waitcnt lgkmcnt(7)
	v_add_u32_e32 v232, 0x0, v224
	v_cmp_le_i32_e32 vcc, 0, v232
	s_nop 1
	v_cndmask_b32_e32 v216, v252, v216, vcc
	v_add_f32_e32 v18, v18, v216
	s_waitcnt lgkmcnt(6)
	v_add_u32_e32 v232, 0xfffffff0, v224
	v_cmp_le_i32_e32 vcc, 0, v232
	s_nop 1
	v_cndmask_b32_e32 v217, v252, v217, vcc
	v_add_f32_e32 v19, v19, v217
	s_waitcnt lgkmcnt(5)
	v_add_u32_e32 v232, 0xffffffe0, v224
	v_cmp_le_i32_e32 vcc, 0, v232
	s_nop 1
	v_cndmask_b32_e32 v218, v252, v218, vcc
	v_add_f32_e32 v20, v20, v218
	s_waitcnt lgkmcnt(4)
	v_add_u32_e32 v232, 0xffffffd0, v224
	v_cmp_le_i32_e32 vcc, 0, v232
	s_nop 1
	v_cndmask_b32_e32 v219, v252, v219, vcc
	v_add_f32_e32 v21, v21, v219
	s_waitcnt lgkmcnt(3)
	v_add_u32_e32 v232, 0xffffffc0, v224
	v_cmp_le_i32_e32 vcc, 0, v232
	s_nop 1
	v_cndmask_b32_e32 v220, v252, v220, vcc
	v_add_f32_e32 v22, v22, v220
	s_waitcnt lgkmcnt(2)
	v_add_u32_e32 v232, 0xffffffb0, v224
	v_cmp_le_i32_e32 vcc, 0, v232
	s_nop 1
	v_cndmask_b32_e32 v221, v252, v221, vcc
	v_add_f32_e32 v23, v23, v221
	s_waitcnt lgkmcnt(1)
	v_add_u32_e32 v232, 0xffffffa0, v224
	v_cmp_le_i32_e32 vcc, 0, v232
	s_nop 1
	v_cndmask_b32_e32 v222, v252, v222, vcc
	v_add_f32_e32 v24, v24, v222
	s_waitcnt lgkmcnt(0)
	v_add_u32_e32 v232, 0xffffff90, v224
	v_cmp_le_i32_e32 vcc, 0, v232
	s_nop 1
	v_cndmask_b32_e32 v223, v252, v223, vcc
	v_add_f32_e32 v25, v25, v223
	v_add_u32_e32 v232, 0xfffffe00, v224
	v_min_u32_e32 v232, 0x400, v232
	v_lshl_add_u32 v232, v232, 2, v173
	ds_read_b32 v216, v232
	v_add_u32_e32 v232, 0xfffffdf0, v224
	v_min_u32_e32 v232, 0x400, v232
	v_lshl_add_u32 v232, v232, 2, v173
	ds_read_b32 v217, v232
	v_add_u32_e32 v232, 0xfffffde0, v224
	v_min_u32_e32 v232, 0x400, v232
	v_lshl_add_u32 v232, v232, 2, v173
	ds_read_b32 v218, v232
	v_add_u32_e32 v232, 0xfffffdd0, v224
	v_min_u32_e32 v232, 0x400, v232
	v_lshl_add_u32 v232, v232, 2, v173
	ds_read_b32 v219, v232
	v_add_u32_e32 v232, 0xfffffdc0, v224
	v_min_u32_e32 v232, 0x400, v232
	v_lshl_add_u32 v232, v232, 2, v173
	ds_read_b32 v220, v232
	v_add_u32_e32 v232, 0xfffffdb0, v224
	v_min_u32_e32 v232, 0x400, v232
	v_lshl_add_u32 v232, v232, 2, v173
	ds_read_b32 v221, v232
	v_add_u32_e32 v232, 0xfffffda0, v224
	v_min_u32_e32 v232, 0x400, v232
	v_lshl_add_u32 v232, v232, 2, v173
	ds_read_b32 v222, v232
	v_add_u32_e32 v232, 0xfffffd90, v224
	v_min_u32_e32 v232, 0x400, v232
	v_lshl_add_u32 v232, v232, 2, v173
	ds_read_b32 v223, v232
	s_waitcnt lgkmcnt(7)
	v_add_u32_e32 v232, 0xfffffe00, v224
	v_cmp_le_i32_e32 vcc, 0, v232
	s_nop 1
	v_cndmask_b32_e32 v216, v252, v216, vcc
	v_add_f32_e32 v26, v26, v216
	s_waitcnt lgkmcnt(6)
	v_add_u32_e32 v232, 0xfffffdf0, v224
	v_cmp_le_i32_e32 vcc, 0, v232
	s_nop 1
	v_cndmask_b32_e32 v217, v252, v217, vcc
	v_add_f32_e32 v27, v27, v217
	s_waitcnt lgkmcnt(5)
	v_add_u32_e32 v232, 0xfffffde0, v224
	v_cmp_le_i32_e32 vcc, 0, v232
	s_nop 1
	v_cndmask_b32_e32 v218, v252, v218, vcc
	v_add_f32_e32 v28, v28, v218
	s_waitcnt lgkmcnt(4)
	v_add_u32_e32 v232, 0xfffffdd0, v224
	v_cmp_le_i32_e32 vcc, 0, v232
	s_nop 1
	v_cndmask_b32_e32 v219, v252, v219, vcc
	v_add_f32_e32 v29, v29, v219
	s_waitcnt lgkmcnt(3)
	v_add_u32_e32 v232, 0xfffffdc0, v224
	v_cmp_le_i32_e32 vcc, 0, v232
	s_nop 1
	v_cndmask_b32_e32 v220, v252, v220, vcc
	v_add_f32_e32 v30, v30, v220
	s_waitcnt lgkmcnt(2)
	v_add_u32_e32 v232, 0xfffffdb0, v224
	v_cmp_le_i32_e32 vcc, 0, v232
	s_nop 1
	v_cndmask_b32_e32 v221, v252, v221, vcc
	v_add_f32_e32 v31, v31, v221
	s_waitcnt lgkmcnt(1)
	v_add_u32_e32 v232, 0xfffffda0, v224
	v_cmp_le_i32_e32 vcc, 0, v232
	s_nop 1
	v_cndmask_b32_e32 v222, v252, v222, vcc
	v_add_f32_e32 v32, v32, v222
	s_waitcnt lgkmcnt(0)
	v_add_u32_e32 v232, 0xfffffd90, v224
	v_cmp_le_i32_e32 vcc, 0, v232
	s_nop 1
	v_cndmask_b32_e32 v223, v252, v223, vcc
	v_add_f32_e32 v33, v33, v223
	v_exp_f32_e32 v18, v18
	v_exp_f32_e32 v19, v19
	v_exp_f32_e32 v20, v20
	v_exp_f32_e32 v21, v21
	v_exp_f32_e32 v22, v22
	v_exp_f32_e32 v23, v23
	v_exp_f32_e32 v24, v24
	v_exp_f32_e32 v25, v25
	v_exp_f32_e32 v26, v26
	v_exp_f32_e32 v27, v27
	v_exp_f32_e32 v28, v28
	v_exp_f32_e32 v29, v29
	v_exp_f32_e32 v30, v30
	v_exp_f32_e32 v31, v31
	v_exp_f32_e32 v32, v32
	v_exp_f32_e32 v33, v33
	v_add_f32_e32 v170, v170, v18
	v_add_f32_e32 v170, v170, v19
	v_add_f32_e32 v170, v170, v20
	v_add_f32_e32 v170, v170, v21
	v_add_f32_e32 v170, v170, v22
	v_add_f32_e32 v170, v170, v23
	v_add_f32_e32 v170, v170, v24
	v_add_f32_e32 v170, v170, v25
	v_add_f32_e32 v170, v170, v26
	v_add_f32_e32 v170, v170, v27
	v_add_f32_e32 v170, v170, v28
	v_add_f32_e32 v170, v170, v29
	v_add_f32_e32 v170, v170, v30
	v_add_f32_e32 v170, v170, v31
	v_add_f32_e32 v170, v170, v32
	v_add_f32_e32 v170, v170, v33

; #define LAS __attribute__((address_space(3)))
; __device__ __forceinline__ bf16_t tobf(float x) { return (bf16_t)pk2(x, 0.f); }
; __device__ __forceinline__ float ex2(float x) { return __builtin_amdgcn_exp2f(x); }
; __device__ __forceinline__ void cmp_sm2(const f32x4 (&sc)[4], int gr, int t0, const LAS float* bt, const float (&inv)[4], LAS bf16_t* Pb, LAS float* psum, int r16, int q4) {
; #pragma unroll
;     for (int cc = 0; cc < 4; ++cc) {
;         const int kk = gr * 64 + cc * 16 + r16, cend = kk * 16 + 31;
; #pragma unroll
;         for (int i = 0; i < 4; ++i) { const int dist = t0 + i - cend; float p = dist >= 0 ? ex2(sc[cc][i] + bt[clampd(dist)]) * inv[i] : 0.f;
;             Pb[(4 * q4 + i) * 72 + cc * 16 + r16] = tobf(p); p += __shfl_xor(p, 16); p += __shfl_xor(p, 32); if (q4 == 0) psum[i * 512 + kk] = p; }
;     }
; __device__ __forceinline__ void nsa_quad_pre(int bg, int quad, const bf16_t* Q, const bf16_t* KV, const bf16_t* KCMP, const bf16_t* VCMPT, const float* GN, bf16_t* ONSA, ...
;     ...
;         for (int gr = 0; gr < ngr; ++gr) {
;             const bool more = gr + 1 < ngr;
;             qk_scores(KF, qf, sc);
;             if (more) load_k(KF, KP_C(gr + 1));
;             cmp_sm2(sc, gr, t0, bt, inv, Pb, psum, r16, q4);
;             pv_step(VF, oc, Pb, r16, q4);
;             if (more) load_v(VF, VP_C(gr + 1));
;         }
.Lcmp_top_q1p2:
	s_nop 1
	s_cmp_lt_i32 s57, s52
	s_cbranch_scc0 .Lcmp_gen_q1p2
	s_lshl_b32 s0, s57, 7
	s_add_u32 s14, s68, s0
	s_addc_u32 s15, s69, 0
	global_load_dwordx4 v[82:85], v176, s[14:15] offset:0
	global_load_dwordx4 v[86:89], v176, s[14:15] offset:64
	global_load_dwordx4 v[90:93], v177, s[14:15] offset:0
	global_load_dwordx4 v[94:97], v177, s[14:15] offset:64
	global_load_dwordx4 v[236:239], v178, s[14:15] offset:0
	global_load_dwordx4 v[240:243], v178, s[14:15] offset:64
	global_load_dwordx4 v[244:247], v179, s[14:15] offset:0
	global_load_dwordx4 v[248:251], v179, s[14:15] offset:64
	s_waitcnt vmcnt(8)
	v_mov_b32_e32 v228, v225
	v_mov_b32_e32 v229, v225
	v_mov_b32_e32 v230, v225
	v_mov_b32_e32 v231, v225
	s_nop 1
	v_mfma_f32_16x16x32_bf16 v[18:21], v[50:53], v[42:45], v[228:231]
	v_mfma_f32_16x16x32_bf16 v[18:21], v[54:57], v[46:49], v[18:21]
	v_mfma_f32_16x16x32_bf16 v[22:25], v[58:61], v[42:45], v[228:231]
	v_mfma_f32_16x16x32_bf16 v[22:25], v[62:65], v[46:49], v[22:25]
	v_mfma_f32_16x16x32_bf16 v[26:29], v[66:69], v[42:45], v[228:231]
	v_mfma_f32_16x16x32_bf16 v[26:29], v[70:73], v[46:49], v[26:29]
	v_mfma_f32_16x16x32_bf16 v[30:33], v[74:77], v[42:45], v[228:231]
	v_mfma_f32_16x16x32_bf16 v[30:33], v[78:81], v[46:49], v[30:33]
	s_nop 1
	v_exp_f32_e32 v18, v18
	v_exp_f32_e32 v19, v19
	v_exp_f32_e32 v20, v20
	v_exp_f32_e32 v21, v21
	v_exp_f32_e32 v22, v22
	v_exp_f32_e32 v23, v23
	v_exp_f32_e32 v24, v24
	v_exp_f32_e32 v25, v25
	v_exp_f32_e32 v26, v26
	v_exp_f32_e32 v27, v27
	v_exp_f32_e32 v28, v28
	v_exp_f32_e32 v29, v29
	v_exp_f32_e32 v30, v30
	v_exp_f32_e32 v31, v31
	v_exp_f32_e32 v32, v32
	v_exp_f32_e32 v33, v33
	v_mul_f32_e32 v18, v18, v171
	v_mul_f32_e32 v19, v19, v171
	v_mul_f32_e32 v20, v20, v171
	v_mul_f32_e32 v21, v21, v171
	v_mul_f32_e32 v22, v22, v171
	v_mul_f32_e32 v23, v23, v171
	v_mul_f32_e32 v24, v24, v171
	v_mul_f32_e32 v25, v25, v171
	v_mul_f32_e32 v26, v26, v171
	v_mul_f32_e32 v27, v27, v171
	v_mul_f32_e32 v28, v28, v171
	v_mul_f32_e32 v29, v29, v171
	v_mul_f32_e32 v30, v30, v171
	v_mul_f32_e32 v31, v31, v171
	v_mul_f32_e32 v32, v32, v171
	v_mul_f32_e32 v33, v33, v171
	v_add_f32_dpp v50, v18, v18 row_shr:4 row_mask:0xf bank_mask:0xf
	v_add_f32_dpp v51, v19, v19 row_shr:4 row_mask:0xf bank_mask:0xf
	v_add_f32_dpp v52, v20, v20 row_shr:4 row_mask:0xf bank_mask:0xf
	v_add_f32_dpp v53, v21, v21 row_shr:4 row_mask:0xf bank_mask:0xf
	v_add_f32_dpp v54, v22, v22 row_shr:4 row_mask:0xf bank_mask:0xf
	v_add_f32_dpp v55, v23, v23 row_shr:4 row_mask:0xf bank_mask:0xf
	v_add_f32_dpp v56, v24, v24 row_shr:4 row_mask:0xf bank_mask:0xf
	v_add_f32_dpp v57, v25, v25 row_shr:4 row_mask:0xf bank_mask:0xf
	v_add_f32_dpp v58, v26, v26 row_shr:4 row_mask:0xf bank_mask:0xf
	v_add_f32_dpp v59, v27, v27 row_shr:4 row_mask:0xf bank_mask:0xf
	v_add_f32_dpp v60, v28, v28 row_shr:4 row_mask:0xf bank_mask:0xf
	v_add_f32_dpp v61, v29, v29 row_shr:4 row_mask:0xf bank_mask:0xf
	v_add_f32_dpp v62, v30, v30 row_shr:4 row_mask:0xf bank_mask:0xf
	v_add_f32_dpp v63, v31, v31 row_shr:4 row_mask:0xf bank_mask:0xf
	v_add_f32_dpp v64, v32, v32 row_shr:4 row_mask:0xf bank_mask:0xf
	v_add_f32_dpp v65, v33, v33 row_shr:4 row_mask:0xf bank_mask:0xf
	v_add_f32_dpp v50, v50, v50 row_shr:8 row_mask:0xf bank_mask:0xf
	v_add_f32_dpp v51, v51, v51 row_shr:8 row_mask:0xf bank_mask:0xf
	v_add_f32_dpp v52, v52, v52 row_shr:8 row_mask:0xf bank_mask:0xf
	v_add_f32_dpp v53, v53, v53 row_shr:8 row_mask:0xf bank_mask:0xf
	v_add_f32_dpp v54, v54, v54 row_shr:8 row_mask:0xf bank_mask:0xf
	v_add_f32_dpp v55, v55, v55 row_shr:8 row_mask:0xf bank_mask:0xf
	v_add_f32_dpp v56, v56, v56 row_shr:8 row_mask:0xf bank_mask:0xf
	v_add_f32_dpp v57, v57, v57 row_shr:8 row_mask:0xf bank_mask:0xf
	v_add_f32_dpp v58, v58, v58 row_shr:8 row_mask:0xf bank_mask:0xf
	v_add_f32_dpp v59, v59, v59 row_shr:8 row_mask:0xf bank_mask:0xf
	v_add_f32_dpp v60, v60, v60 row_shr:8 row_mask:0xf bank_mask:0xf
	v_add_f32_dpp v61, v61, v61 row_shr:8 row_mask:0xf bank_mask:0xf
	v_add_f32_dpp v62, v62, v62 row_shr:8 row_mask:0xf bank_mask:0xf
	v_add_f32_dpp v63, v63, v63 row_shr:8 row_mask:0xf bank_mask:0xf
	v_add_f32_dpp v64, v64, v64 row_shr:8 row_mask:0xf bank_mask:0xf
	v_add_f32_dpp v65, v65, v65 row_shr:8 row_mask:0xf bank_mask:0xf
	s_lshl_b32 s0, s57, 8
	v_add_u32_e32 v232, s0, v215
	v_cmp_lt_u32_e32 vcc, 11, v98
	s_nop 0
	s_and_saveexec_b64 s[20:21], vcc
	ds_write_b128 v232, v[50:53] offset:0
	ds_write_b128 v232, v[54:57] offset:16
	ds_write_b128 v232, v[58:61] offset:128
	ds_write_b128 v232, v[62:65] offset:144
	s_or_b64 exec, exec, s[20:21]
	v_cvt_pk_bf16_f32 v216, v18, v19
	v_cvt_pk_bf16_f32 v217, v20, v21
	v_cvt_pk_bf16_f32 v218, v22, v23
	v_cvt_pk_bf16_f32 v219, v24, v25
	v_cvt_pk_bf16_f32 v220, v26, v27
	v_cvt_pk_bf16_f32 v221, v28, v29
	v_cvt_pk_bf16_f32 v222, v30, v31
	v_cvt_pk_bf16_f32 v223, v32, v33
	s_add_i32 s1, s57, 1
	s_cmp_lt_i32 s1, s53
	s_cbranch_scc0 .Lcmp_nok_q1p2f
	s_waitcnt lgkmcnt(0)
	s_lshl_b32 s0, s1, 13
	s_add_u32 s70, s66, s0
	s_addc_u32 s71, s67, 0
	global_load_dwordx4 v[50:53], v174, s[70:71] offset:0
	global_load_dwordx4 v[54:57], v174, s[70:71] offset:64
	global_load_dwordx4 v[58:61], v174, s[70:71] offset:512
	global_load_dwordx4 v[62:65], v174, s[70:71] offset:576
	global_load_dwordx4 v[66:69], v175, s[70:71] offset:0
	global_load_dwordx4 v[70:73], v175, s[70:71] offset:64
	global_load_dwordx4 v[74:77], v175, s[70:71] offset:512
	global_load_dwordx4 v[78:81], v175, s[70:71] offset:576
	s_waitcnt vmcnt(8)
	s_branch .Lcmp_kj_q1p2f

; #define LAS __attribute__((address_space(3)))
; __device__ __forceinline__ bf16_t tobf(float x) { return (bf16_t)pk2(x, 0.f); }
; __device__ __forceinline__ float ex2(float x) { return __builtin_amdgcn_exp2f(x); }
; __device__ __forceinline__ void cmp_sm2(const f32x4 (&sc)[4], int gr, int t0, const LAS float* bt, const float (&inv)[4], LAS bf16_t* Pb, LAS float* psum, int r16, int q4) {
; #pragma unroll
;     for (int cc = 0; cc < 4; ++cc) {
;         const int kk = gr * 64 + cc * 16 + r16, cend = kk * 16 + 31;
; #pragma unroll
;         for (int i = 0; i < 4; ++i) { const int dist = t0 + i - cend; float p = dist >= 0 ? ex2(sc[cc][i] + bt[clampd(dist)]) * inv[i] : 0.f;
;             Pb[(4 * q4 + i) * 72 + cc * 16 + r16] = tobf(p); p += __shfl_xor(p, 16); p += __shfl_xor(p, 32); if (q4 == 0) psum[i * 512 + kk] = p; }
;     }
; __device__ __forceinline__ void nsa_quad_pre(int bg, int quad, const bf16_t* Q, const bf16_t* KV, const bf16_t* KCMP, const bf16_t* VCMPT, const float* GN, bf16_t* ONSA, ...
;     ...
;         for (int gr = 0; gr < ngr; ++gr) {
;             const bool more = gr + 1 < ngr;
;             qk_scores(KF, qf, sc);
;             if (more) load_k(KF, KP_C(gr + 1));
;             cmp_sm2(sc, gr, t0, bt, inv, Pb, psum, r16, q4);
.Lcmp_gen_q1p2:
	s_nop 1
	s_lshl_b32 s0, s57, 7
	s_add_u32 s14, s68, s0
	s_addc_u32 s15, s69, 0
	global_load_dwordx4 v[82:85], v176, s[14:15] offset:0
	global_load_dwordx4 v[86:89], v176, s[14:15] offset:64
	global_load_dwordx4 v[90:93], v177, s[14:15] offset:0
	global_load_dwordx4 v[94:97], v177, s[14:15] offset:64
	global_load_dwordx4 v[236:239], v178, s[14:15] offset:0
	global_load_dwordx4 v[240:243], v178, s[14:15] offset:64
	global_load_dwordx4 v[244:247], v179, s[14:15] offset:0
	global_load_dwordx4 v[248:251], v179, s[14:15] offset:64
	s_waitcnt vmcnt(8)
	v_mfma_f32_16x16x32_bf16 v[18:21], v[50:53], v[42:45], 0
	v_mfma_f32_16x16x32_bf16 v[18:21], v[54:57], v[46:49], v[18:21]
	v_mfma_f32_16x16x32_bf16 v[22:25], v[58:61], v[42:45], 0
	v_mfma_f32_16x16x32_bf16 v[22:25], v[62:65], v[46:49], v[22:25]
	v_mfma_f32_16x16x32_bf16 v[26:29], v[66:69], v[42:45], 0
	v_mfma_f32_16x16x32_bf16 v[26:29], v[70:73], v[46:49], v[26:29]
	v_mfma_f32_16x16x32_bf16 v[30:33], v[74:77], v[42:45], 0
	v_mfma_f32_16x16x32_bf16 v[30:33], v[78:81], v[46:49], v[30:33]
	s_lshl_b32 s0, s57, 10
	v_subrev_u32_e32 v224, s0, v99
	v_add_u32_e32 v232, 0x0, v224
	v_min_u32_e32 v232, 0x400, v232
	v_lshl_add_u32 v232, v232, 2, v173
	ds_read_b32 v216, v232
	v_add_u32_e32 v232, 0xfffffff0, v224
	v_min_u32_e32 v232, 0x400, v232
	v_lshl_add_u32 v232, v232, 2, v173
	ds_read_b32 v217, v232
	v_add_u32_e32 v232, 0xffffffe0, v224
	v_min_u32_e32 v232, 0x400, v232
	v_lshl_add_u32 v232, v232, 2, v173
	ds_read_b32 v218, v232
	v_add_u32_e32 v232, 0xffffffd0, v224
	v_min_u32_e32 v232, 0x400, v232
	v_lshl_add_u32 v232, v232, 2, v173
	ds_read_b32 v219, v232
	v_add_u32_e32 v232, 0xffffffc0, v224
	v_min_u32_e32 v232, 0x400, v232
	v_lshl_add_u32 v232, v232, 2, v173
	ds_read_b32 v220, v232
	v_add_u32_e32 v232, 0xffffffb0, v224
	v_min_u32_e32 v232, 0x400, v232
	v_lshl_add_u32 v232, v232, 2, v173
	ds_read_b32 v221, v232
	v_add_u32_e32 v232, 0xffffffa0, v224
	v_min_u32_e32 v232, 0x400, v232
	v_lshl_add_u32 v232, v232, 2, v173
	ds_read_b32 v222, v232
	v_add_u32_e32 v232, 0xffffff90, v224
	v_min_u32_e32 v232, 0x400, v232
	v_lshl_add_u32 v232, v232, 2, v173
	ds_read_b32 v223, v232
	s_waitcnt lgkmcnt(7)
	v_add_u32_e32 v232, 0x0, v224
	v_cmp_le_i32_e32 vcc, 0, v232
	s_nop 1
	v_cndmask_b32_e32 v216, v252, v216, vcc
	v_add_f32_e32 v18, v18, v216
	s_waitcnt lgkmcnt(6)
	v_add_u32_e32 v232, 0xfffffff0, v224
	v_cmp_le_i32_e32 vcc, 0, v232
	s_nop 1
	v_cndmask_b32_e32 v217, v252, v217, vcc
	v_add_f32_e32 v19, v19, v217
	s_waitcnt lgkmcnt(5)
	v_add_u32_e32 v232, 0xffffffe0, v224
	v_cmp_le_i32_e32 vcc, 0, v232
	s_nop 1
	v_cndmask_b32_e32 v218, v252, v218, vcc
	v_add_f32_e32 v20, v20, v218
	s_waitcnt lgkmcnt(4)
	v_add_u32_e32 v232, 0xffffffd0, v224
	v_cmp_le_i32_e32 vcc, 0, v232
	s_nop 1
	v_cndmask_b32_e32 v219, v252, v219, vcc
	v_add_f32_e32 v21, v21, v219
	s_waitcnt lgkmcnt(3)
	v_add_u32_e32 v232, 0xffffffc0, v224
	v_cmp_le_i32_e32 vcc, 0, v232
	s_nop 1
	v_cndmask_b32_e32 v220, v252, v220, vcc
	v_add_f32_e32 v22, v22, v220
	s_waitcnt lgkmcnt(2)
	v_add_u32_e32 v232, 0xffffffb0, v224
	v_cmp_le_i32_e32 vcc, 0, v232
	s_nop 1
	v_cndmask_b32_e32 v221, v252, v221, vcc
	v_add_f32_e32 v23, v23, v221
	s_waitcnt lgkmcnt(1)
	v_add_u32_e32 v232, 0xffffffa0, v224
	v_cmp_le_i32_e32 vcc, 0, v232
	s_nop 1
	v_cndmask_b32_e32 v222, v252, v222, vcc
	v_add_f32_e32 v24, v24, v222
	s_waitcnt lgkmcnt(0)
	v_add_u32_e32 v232, 0xffffff90, v224
	v_cmp_le_i32_e32 vcc, 0, v232
	s_nop 1
	v_cndmask_b32_e32 v223, v252, v223, vcc
	v_add_f32_e32 v25, v25, v223
	v_add_u32_e32 v232, 0xfffffe00, v224
	v_min_u32_e32 v232, 0x400, v232
	v_lshl_add_u32 v232, v232, 2, v173
	ds_read_b32 v216, v232
	v_add_u32_e32 v232, 0xfffffdf0, v224
	v_min_u32_e32 v232, 0x400, v232
	v_lshl_add_u32 v232, v232, 2, v173
	ds_read_b32 v217, v232
	v_add_u32_e32 v232, 0xfffffde0, v224
	v_min_u32_e32 v232, 0x400, v232
	v_lshl_add_u32 v232, v232, 2, v173
	ds_read_b32 v218, v232
	v_add_u32_e32 v232, 0xfffffdd0, v224
	v_min_u32_e32 v232, 0x400, v232
	v_lshl_add_u32 v232, v232, 2, v173
	ds_read_b32 v219, v232
	v_add_u32_e32 v232, 0xfffffdc0, v224
	v_min_u32_e32 v232, 0x400, v232
	v_lshl_add_u32 v232, v232, 2, v173
	ds_read_b32 v220, v232
	v_add_u32_e32 v232, 0xfffffdb0, v224
	v_min_u32_e32 v232, 0x400, v232
	v_lshl_add_u32 v232, v232, 2, v173
	ds_read_b32 v221, v232
	v_add_u32_e32 v232, 0xfffffda0, v224
	v_min_u32_e32 v232, 0x400, v232
	v_lshl_add_u32 v232, v232, 2, v173
	ds_read_b32 v222, v232
	v_add_u32_e32 v232, 0xfffffd90, v224
	v_min_u32_e32 v232, 0x400, v232
	v_lshl_add_u32 v232, v232, 2, v173
	ds_read_b32 v223, v232
	s_waitcnt lgkmcnt(7)
	v_add_u32_e32 v232, 0xfffffe00, v224
	v_cmp_le_i32_e32 vcc, 0, v232
	s_nop 1
	v_cndmask_b32_e32 v216, v252, v216, vcc
	v_add_f32_e32 v26, v26, v216
	s_waitcnt lgkmcnt(6)
	v_add_u32_e32 v232, 0xfffffdf0, v224
	v_cmp_le_i32_e32 vcc, 0, v232
	s_nop 1
	v_cndmask_b32_e32 v217, v252, v217, vcc
	v_add_f32_e32 v27, v27, v217
	s_waitcnt lgkmcnt(5)
	v_add_u32_e32 v232, 0xfffffde0, v224
	v_cmp_le_i32_e32 vcc, 0, v232
	s_nop 1
	v_cndmask_b32_e32 v218, v252, v218, vcc
	v_add_f32_e32 v28, v28, v218
	s_waitcnt lgkmcnt(4)
; #define LAS __attribute__((address_space(3)))
; __device__ __forceinline__ bf16_t tobf(float x) { return (bf16_t)pk2(x, 0.f); }
; __device__ __forceinline__ float ex2(float x) { return __builtin_amdgcn_exp2f(x); }
; __device__ __forceinline__ void cmp_sm2(const f32x4 (&sc)[4], int gr, int t0, const LAS float* bt, const float (&inv)[4], LAS bf16_t* Pb, LAS float* psum, int r16, int q4) {
; #pragma unroll
;     for (int cc = 0; cc < 4; ++cc) {
;         const int kk = gr * 64 + cc * 16 + r16, cend = kk * 16 + 31;
; #pragma unroll
;         for (int i = 0; i < 4; ++i) { const int dist = t0 + i - cend; float p = dist >= 0 ? ex2(sc[cc][i] + bt[clampd(dist)]) * inv[i] : 0.f;
;             Pb[(4 * q4 + i) * 72 + cc * 16 + r16] = tobf(p); p += __shfl_xor(p, 16); p += __shfl_xor(p, 32); if (q4 == 0) psum[i * 512 + kk] = p; }
;     }
; __device__ __forceinline__ void nsa_quad_pre(int bg, int quad, const bf16_t* Q, const bf16_t* KV, const bf16_t* KCMP, const bf16_t* VCMPT, const float* GN, bf16_t* ONSA, ...
;     ...
;         for (int gr = 0; gr < ngr; ++gr) {
;             const bool more = gr + 1 < ngr;
;             qk_scores(KF, qf, sc);
;             if (more) load_k(KF, KP_C(gr + 1));
;             cmp_sm2(sc, gr, t0, bt, inv, Pb, psum, r16, q4);
;             pv_step(VF, oc, Pb, r16, q4);
;             if (more) load_v(VF, VP_C(gr + 1));
;         }
	v_add_u32_e32 v232, 0xfffffdd0, v224
	v_cmp_le_i32_e32 vcc, 0, v232
	s_nop 1
	v_cndmask_b32_e32 v219, v252, v219, vcc
	v_add_f32_e32 v29, v29, v219
	s_waitcnt lgkmcnt(3)
	v_add_u32_e32 v232, 0xfffffdc0, v224
	v_cmp_le_i32_e32 vcc, 0, v232
	s_nop 1
	v_cndmask_b32_e32 v220, v252, v220, vcc
	v_add_f32_e32 v30, v30, v220
	s_waitcnt lgkmcnt(2)
	v_add_u32_e32 v232, 0xfffffdb0, v224
	v_cmp_le_i32_e32 vcc, 0, v232
	s_nop 1
	v_cndmask_b32_e32 v221, v252, v221, vcc
	v_add_f32_e32 v31, v31, v221
	s_waitcnt lgkmcnt(1)
	v_add_u32_e32 v232, 0xfffffda0, v224
	v_cmp_le_i32_e32 vcc, 0, v232
	s_nop 1
	v_cndmask_b32_e32 v222, v252, v222, vcc
	v_add_f32_e32 v32, v32, v222
	s_waitcnt lgkmcnt(0)
	v_add_u32_e32 v232, 0xfffffd90, v224
	v_cmp_le_i32_e32 vcc, 0, v232
	s_nop 1
	v_cndmask_b32_e32 v223, v252, v223, vcc
	v_add_f32_e32 v33, v33, v223
	v_exp_f32_e32 v18, v18
	v_exp_f32_e32 v19, v19
	v_exp_f32_e32 v20, v20
	v_exp_f32_e32 v21, v21
	v_exp_f32_e32 v22, v22
	v_exp_f32_e32 v23, v23
	v_exp_f32_e32 v24, v24
	v_exp_f32_e32 v25, v25
	v_exp_f32_e32 v26, v26
	v_exp_f32_e32 v27, v27
	v_exp_f32_e32 v28, v28
	v_exp_f32_e32 v29, v29
	v_exp_f32_e32 v30, v30
	v_exp_f32_e32 v31, v31
	v_exp_f32_e32 v32, v32
	v_exp_f32_e32 v33, v33
	v_mul_f32_e32 v18, v18, v171
	v_mul_f32_e32 v19, v19, v171
	v_mul_f32_e32 v20, v20, v171
	v_mul_f32_e32 v21, v21, v171
	v_mul_f32_e32 v22, v22, v171
	v_mul_f32_e32 v23, v23, v171
	v_mul_f32_e32 v24, v24, v171
	v_mul_f32_e32 v25, v25, v171
	v_mul_f32_e32 v26, v26, v171
	v_mul_f32_e32 v27, v27, v171
	v_mul_f32_e32 v28, v28, v171
	v_mul_f32_e32 v29, v29, v171
	v_mul_f32_e32 v30, v30, v171
	v_mul_f32_e32 v31, v31, v171
	v_mul_f32_e32 v32, v32, v171
	v_mul_f32_e32 v33, v33, v171
	v_add_f32_dpp v50, v18, v18 row_shr:4 row_mask:0xf bank_mask:0xf
	v_add_f32_dpp v51, v19, v19 row_shr:4 row_mask:0xf bank_mask:0xf
	v_add_f32_dpp v52, v20, v20 row_shr:4 row_mask:0xf bank_mask:0xf
	v_add_f32_dpp v53, v21, v21 row_shr:4 row_mask:0xf bank_mask:0xf
	v_add_f32_dpp v54, v22, v22 row_shr:4 row_mask:0xf bank_mask:0xf
	v_add_f32_dpp v55, v23, v23 row_shr:4 row_mask:0xf bank_mask:0xf
	v_add_f32_dpp v56, v24, v24 row_shr:4 row_mask:0xf bank_mask:0xf
	v_add_f32_dpp v57, v25, v25 row_shr:4 row_mask:0xf bank_mask:0xf
	v_add_f32_dpp v58, v26, v26 row_shr:4 row_mask:0xf bank_mask:0xf
	v_add_f32_dpp v59, v27, v27 row_shr:4 row_mask:0xf bank_mask:0xf
	v_add_f32_dpp v60, v28, v28 row_shr:4 row_mask:0xf bank_mask:0xf
	v_add_f32_dpp v61, v29, v29 row_shr:4 row_mask:0xf bank_mask:0xf
	v_add_f32_dpp v62, v30, v30 row_shr:4 row_mask:0xf bank_mask:0xf
	v_add_f32_dpp v63, v31, v31 row_shr:4 row_mask:0xf bank_mask:0xf
	v_add_f32_dpp v64, v32, v32 row_shr:4 row_mask:0xf bank_mask:0xf
	v_add_f32_dpp v65, v33, v33 row_shr:4 row_mask:0xf bank_mask:0xf
	v_add_f32_dpp v50, v50, v50 row_shr:8 row_mask:0xf bank_mask:0xf
	v_add_f32_dpp v51, v51, v51 row_shr:8 row_mask:0xf bank_mask:0xf
	v_add_f32_dpp v52, v52, v52 row_shr:8 row_mask:0xf bank_mask:0xf
	v_add_f32_dpp v53, v53, v53 row_shr:8 row_mask:0xf bank_mask:0xf
	v_add_f32_dpp v54, v54, v54 row_shr:8 row_mask:0xf bank_mask:0xf
	v_add_f32_dpp v55, v55, v55 row_shr:8 row_mask:0xf bank_mask:0xf
	v_add_f32_dpp v56, v56, v56 row_shr:8 row_mask:0xf bank_mask:0xf
	v_add_f32_dpp v57, v57, v57 row_shr:8 row_mask:0xf bank_mask:0xf
	v_add_f32_dpp v58, v58, v58 row_shr:8 row_mask:0xf bank_mask:0xf
	v_add_f32_dpp v59, v59, v59 row_shr:8 row_mask:0xf bank_mask:0xf
	v_add_f32_dpp v60, v60, v60 row_shr:8 row_mask:0xf bank_mask:0xf
	v_add_f32_dpp v61, v61, v61 row_shr:8 row_mask:0xf bank_mask:0xf
	v_add_f32_dpp v62, v62, v62 row_shr:8 row_mask:0xf bank_mask:0xf
	v_add_f32_dpp v63, v63, v63 row_shr:8 row_mask:0xf bank_mask:0xf
	v_add_f32_dpp v64, v64, v64 row_shr:8 row_mask:0xf bank_mask:0xf
	v_add_f32_dpp v65, v65, v65 row_shr:8 row_mask:0xf bank_mask:0xf
	s_lshl_b32 s0, s57, 8
	v_add_u32_e32 v232, s0, v215
	v_cmp_lt_u32_e32 vcc, 11, v98
	s_nop 0
	s_and_saveexec_b64 s[20:21], vcc
	ds_write_b128 v232, v[50:53] offset:0
	ds_write_b128 v232, v[54:57] offset:16
	ds_write_b128 v232, v[58:61] offset:128
	ds_write_b128 v232, v[62:65] offset:144
	s_or_b64 exec, exec, s[20:21]
	v_cvt_pk_bf16_f32 v216, v18, v19
	v_cvt_pk_bf16_f32 v217, v20, v21
	v_cvt_pk_bf16_f32 v218, v22, v23
	v_cvt_pk_bf16_f32 v219, v24, v25
	v_cvt_pk_bf16_f32 v220, v26, v27
	v_cvt_pk_bf16_f32 v221, v28, v29
	v_cvt_pk_bf16_f32 v222, v30, v31
	v_cvt_pk_bf16_f32 v223, v32, v33
	s_add_i32 s1, s57, 1
	s_cmp_lt_i32 s1, s53
	s_cbranch_scc0 .Lcmp_nok_q1p2g
	s_waitcnt lgkmcnt(0)
	s_lshl_b32 s0, s1, 13
	s_add_u32 s70, s66, s0
	s_addc_u32 s71, s67, 0
	global_load_dwordx4 v[50:53], v174, s[70:71] offset:0
	global_load_dwordx4 v[54:57], v174, s[70:71] offset:64
	global_load_dwordx4 v[58:61], v174, s[70:71] offset:512
	global_load_dwordx4 v[62:65], v174, s[70:71] offset:576
	global_load_dwordx4 v[66:69], v175, s[70:71] offset:0
	global_load_dwordx4 v[70:73], v175, s[70:71] offset:64
	global_load_dwordx4 v[74:77], v175, s[70:71] offset:512
	global_load_dwordx4 v[78:81], v175, s[70:71] offset:576
	s_waitcnt vmcnt(8)
	s_branch .Lcmp_kj_q1p2g

; #define LAS __attribute__((address_space(3)))
; __device__ __forceinline__ bf16_t tobf(float x) { return (bf16_t)pk2(x, 0.f); }
; __device__ __forceinline__ void nsa_quad_pre(int bg, int quad, const bf16_t* Q, const bf16_t* KV, const bf16_t* KCMP, const bf16_t* VCMPT, const float* GN, bf16_t* ONSA, ...
;     ...
;     for (int tt = 0; tt < 4; ++tt) {
;         const int tok = t0 + tt, cur = tok >> 6;
;         if (cur < 16) { if (lane < 16) selq[tt * 16 + lane] = lane; }
;         else {
;             unsigned k0 = 0u, k1 = 0u;
;             { const int j = lane; if (j >= 1 && j <= cur - 2) { const LAS float* ps = psum + tt * 512 + 4 * j - 1; const float v = ps[0] + ps[1] + ps[2] + ps[3] + ps[4]; k0 = (__builtin_bit_cast(unsigned, v) & ~127u) | (unsigned)(127 - j); } }
;             { const int j = lane + 64; if (j <= cur - 2) { const LAS float* ps = psum + tt * 512 + 4 * j - 1; const float v = ps[0] + ps[1] + ps[2] + ps[3] + ps[4]; k1 = (__builtin_bit_cast(unsigned, v) & ~127u) | (unsigned)(127 - j); } }
;     ...
; #pragma unroll
;     for (int tt = 0; tt < 4; ++tt) { const float gc = GN[(size_t)(b * SEQ + t0 + tt) * 48 + (g * 4 + q4) * 3];
;         bf16_t* op = ONSA + (size_t)(b * SEQ + t0 + tt) * 1024 + (g * 4 + q4) * 64 + r16;
; #pragma unroll
;         for (int nt = 0; nt < 4; ++nt) op[nt * 16] = tobf(gc * oc[nt][tt]); }
.Lcmp_none_q1:
	s_nop 1
	s_nop 7
	s_nop 3
	v_and_b32_e32 v232, 15, v184
	v_lshrrev_b32_e32 v233, 4, v184
	v_and_b32_e32 v234, 3, v232
	v_lshrrev_b32_e32 v235, 2, v232
	s_add_i32 s0, s47, s97
	v_add_u32_e32 v253, s0, v234
	s_and_b32 s1, s88, 3
	s_lshl_b32 s1, s1, 2
	v_add_u32_e32 v0, s1, v235
	v_lshlrev_b32_e32 v98, 7, v0
	v_lshl_add_u32 v98, v253, 11, v98
	v_lshl_add_u32 v98, v233, 3, v98
	v_mul_u32_u24_e32 v99, 0xc0, v253
	v_mul_u32_u24_e32 v0, 12, v0
	v_add_u32_e32 v99, v99, v0
	s_add_u32 s70, s30, 0x38310000
	s_addc_u32 s71, s31, 0
	s_add_u32 s14, s30, 0xf900000
	s_addc_u32 s15, s31, 0
	global_load_dword v232, v99, s[70:71]
	s_waitcnt vmcnt(0)
	v_mul_f32_e32 v2, v2, v232
	v_mul_f32_e32 v3, v3, v232
	v_mul_f32_e32 v4, v4, v232
	v_mul_f32_e32 v5, v5, v232
	v_mul_f32_e32 v6, v6, v232
	v_mul_f32_e32 v7, v7, v232
	v_mul_f32_e32 v8, v8, v232
	v_mul_f32_e32 v9, v9, v232
	v_mul_f32_e32 v10, v10, v232
	v_mul_f32_e32 v11, v11, v232
	v_mul_f32_e32 v12, v12, v232
	v_mul_f32_e32 v13, v13, v232
	v_mul_f32_e32 v14, v14, v232
	v_mul_f32_e32 v15, v15, v232
	v_mul_f32_e32 v16, v16, v232
	v_mul_f32_e32 v17, v17, v232
	v_cvt_pk_bf16_f32 v216, v2, v3
	v_cvt_pk_bf16_f32 v217, v4, v5
	v_cvt_pk_bf16_f32 v218, v6, v7
	v_cvt_pk_bf16_f32 v219, v8, v9
	v_cvt_pk_bf16_f32 v220, v10, v11
	v_cvt_pk_bf16_f32 v221, v12, v13
	v_cvt_pk_bf16_f32 v222, v14, v15
	v_cvt_pk_bf16_f32 v223, v16, v17
	global_store_dwordx2 v98, v[216:217], s[14:15] offset:0
	global_store_dwordx2 v98, v[218:219], s[14:15] offset:32
	global_store_dwordx2 v98, v[220:221], s[14:15] offset:64
	global_store_dwordx2 v98, v[222:223], s[14:15] offset:96
	s_waitcnt lgkmcnt(0)
	s_cmp_gt_i32 s18, 15
	s_cbranch_scc0 .Ltopk_small_q1
	s_lshl_b32 s19, s80, 10
	s_add_i32 s19, s19, 56384
	v_lshlrev_b32_e32 v96, 4, v184
	v_add_u32_e32 v96, s19, v96
	v_add_u32_e32 v97, 0xfffffffc, v96
	v_sub_u32_e32 v94, 127, v184
	v_sub_u32_e32 v95, 63, v184
	s_mov_b32 s54, 0xffffff80
	s_add_i32 s21, s18, -2
	v_add_u32_e32 v236, 64, v184
	ds_read_b32 v86, v97 offset:0
	ds_read_b128 v[50:53], v96 offset:0
	ds_read_b32 v87, v97 offset:1024
	ds_read_b128 v[54:57], v96 offset:1024
	ds_read_b32 v88, v97 offset:2048
	ds_read_b128 v[58:61], v96 offset:2048
	ds_read_b32 v89, v97 offset:3072
	ds_read_b128 v[62:65], v96 offset:3072
	s_waitcnt lgkmcnt(6)
	v_add_f32_e32 v86, v86, v50
	v_add_f32_e32 v86, v86, v51
	v_add_f32_e32 v86, v86, v52
	v_add_f32_e32 v86, v86, v53
	v_and_or_b32 v18, v86, s54, v94
	s_waitcnt lgkmcnt(4)
	v_add_f32_e32 v87, v87, v54
	v_add_f32_e32 v87, v87, v55
	v_add_f32_e32 v87, v87, v56
	v_add_f32_e32 v87, v87, v57
	v_and_or_b32 v22, v87, s54, v95
	s_waitcnt lgkmcnt(2)
	v_add_f32_e32 v88, v88, v58
	v_add_f32_e32 v88, v88, v59
	v_add_f32_e32 v88, v88, v60
	v_add_f32_e32 v88, v88, v61
	v_and_or_b32 v19, v88, s54, v94
	s_waitcnt lgkmcnt(0)
	v_add_f32_e32 v89, v89, v62
	v_add_f32_e32 v89, v89, v63
	v_add_f32_e32 v89, v89, v64
	v_add_f32_e32 v89, v89, v65
	v_and_or_b32 v23, v89, s54, v95
	ds_read_b32 v90, v97 offset:4096
	ds_read_b128 v[66:69], v96 offset:4096
	ds_read_b32 v91, v97 offset:5120
	ds_read_b128 v[70:73], v96 offset:5120
	ds_read_b32 v92, v97 offset:6144
	ds_read_b128 v[74:77], v96 offset:6144
	ds_read_b32 v93, v97 offset:7168
	ds_read_b128 v[78:81], v96 offset:7168
	s_waitcnt lgkmcnt(6)
	v_add_f32_e32 v90, v90, v66
	v_add_f32_e32 v90, v90, v67
	v_add_f32_e32 v90, v90, v68
	v_add_f32_e32 v90, v90, v69
	v_and_or_b32 v20, v90, s54, v94
	s_waitcnt lgkmcnt(4)
	v_add_f32_e32 v91, v91, v70
	v_add_f32_e32 v91, v91, v71
	v_add_f32_e32 v91, v91, v72
	v_add_f32_e32 v91, v91, v73
	v_and_or_b32 v24, v91, s54, v95
	s_waitcnt lgkmcnt(2)
	v_add_f32_e32 v92, v92, v74
	v_add_f32_e32 v92, v92, v75
	v_add_f32_e32 v92, v92, v76
	v_add_f32_e32 v92, v92, v77
	v_and_or_b32 v21, v92, s54, v94
	s_waitcnt lgkmcnt(0)
	v_add_f32_e32 v93, v93, v78
	v_add_f32_e32 v93, v93, v79
	v_add_f32_e32 v93, v93, v80
	v_add_f32_e32 v93, v93, v81
	v_and_or_b32 v25, v93, s54, v95
	v_cmp_le_i32_e64 s[14:15], v184, s21
	v_cmp_lt_i32_e64 s[34:35], 0, v184
	s_nop 0
	s_and_b64 s[14:15], s[14:15], s[34:35]
	v_cmp_le_i32_e64 s[34:35], v236, s21
	v_cndmask_b32_e64 v18, 0, v18, s[14:15]
	s_nop 0
	v_cndmask_b32_e64 v22, 0, v22, s[34:35]
	v_mov_b32_e32 v82, 0
	v_cndmask_b32_e64 v19, 0, v19, s[14:15]
	v_cndmask_b32_e64 v23, 0, v23, s[34:35]
	v_mov_b32_e32 v83, 0
	v_cndmask_b32_e64 v20, 0, v20, s[14:15]
	v_cndmask_b32_e64 v24, 0, v24, s[34:35]
	v_mov_b32_e32 v84, 0
	v_cndmask_b32_e64 v21, 0, v21, s[14:15]
	v_cndmask_b32_e64 v25, 0, v25, s[34:35]
	v_mov_b32_e32 v85, 0
	v_max_u32_e32 v26, v18, v22
	v_max_u32_e32 v27, v19, v23
	v_max_u32_e32 v28, v20, v24
	v_max_u32_e32 v29, v21, v25
	v_max_u32_dpp v26, v26, v26 quad_perm:[1,0,3,2] row_mask:0xf bank_mask:0xf
	v_max_u32_dpp v27, v27, v27 quad_perm:[1,0,3,2] row_mask:0xf bank_mask:0xf
	v_max_u32_dpp v28, v28, v28 quad_perm:[1,0,3,2] row_mask:0xf bank_mask:0xf
	v_max_u32_dpp v29, v29, v29 quad_perm:[1,0,3,2] row_mask:0xf bank_mask:0xf
	v_max_u32_dpp v26, v26, v26 quad_perm:[2,3,0,1] row_mask:0xf bank_mask:0xf
	v_max_u32_dpp v27, v27, v27 quad_perm:[2,3,0,1] row_mask:0xf bank_mask:0xf
	v_max_u32_dpp v28, v28, v28 quad_perm:[2,3,0,1] row_mask:0xf bank_mask:0xf
	v_max_u32_dpp v29, v29, v29 quad_perm:[2,3,0,1] row_mask:0xf bank_mask:0xf
	v_max_u32_dpp v26, v26, v26 row_half_mirror row_mask:0xf bank_mask:0xf
	v_max_u32_dpp v27, v27, v27 row_half_mirror row_mask:0xf bank_mask:0xf
	v_max_u32_dpp v28, v28, v28 row_half_mirror row_mask:0xf bank_mask:0xf
	v_max_u32_dpp v29, v29, v29 row_half_mirror row_mask:0xf bank_mask:0xf
	v_max_u32_dpp v26, v26, v26 row_mirror row_mask:0xf bank_mask:0xf
	v_max_u32_dpp v27, v27, v27 row_mirror row_mask:0xf bank_mask:0xf
	v_max_u32_dpp v28, v28, v28 row_mirror row_mask:0xf bank_mask:0xf
	v_max_u32_dpp v29, v29, v29 row_mirror row_mask:0xf bank_mask:0xf
	ds_swizzle_b32 v30, v26 offset:0x401f
	ds_swizzle_b32 v31, v27 offset:0x401f
	ds_swizzle_b32 v32, v28 offset:0x401f
	ds_swizzle_b32 v33, v29 offset:0x401f
	s_waitcnt lgkmcnt(3)
; __device__ __forceinline__ void nsa_quad_pre(int bg, int quad, const bf16_t* Q, const bf16_t* KV, const bf16_t* KCMP, const bf16_t* VCMPT, const float* GN, bf16_t* ONSA, ...
;     ...
;             for (int it = 0; it < 13; ++it) {
;                 unsigned m = k0 > k1 ? k0 : k1;
; #pragma unroll
;                 for (int off = 32; off >= 1; off >>= 1) { const unsigned o = (unsigned)__shfl_xor((int)m, off); m = o > m ? o : m; }
;                 if (k0 == m) k0 = 0u; if (k1 == m) k1 = 0u;
;                 if (lane == 0) selq[tt * 16 + it] = 127 - (int)(m & 127u);
	v_max_u32_e32 v26, v26, v30
	s_waitcnt lgkmcnt(2)
	v_max_u32_e32 v27, v27, v31
	s_waitcnt lgkmcnt(1)
	v_max_u32_e32 v28, v28, v32
	s_waitcnt lgkmcnt(0)
	v_max_u32_e32 v29, v29, v33
	v_mov_b32_e32 v30, v26
	v_mov_b32_e32 v31, v27
	v_mov_b32_e32 v32, v28
	v_mov_b32_e32 v33, v29
	v_permlane32_swap_b32_e32 v26, v30
	v_permlane32_swap_b32_e32 v27, v31
	v_permlane32_swap_b32_e32 v28, v32
	v_permlane32_swap_b32_e32 v29, v33
	v_max_u32_e32 v26, v26, v30
	v_max_u32_e32 v27, v27, v31
	v_max_u32_e32 v28, v28, v32
	v_max_u32_e32 v29, v29, v33
	v_cmp_eq_u32_e64 s[0:1], 0, v184
	v_and_b32_e32 v236, 127, v26
	v_sub_u32_e32 v236, 127, v236
	v_and_b32_e32 v237, 127, v27
	v_sub_u32_e32 v237, 127, v237
	v_and_b32_e32 v238, 127, v28
	v_sub_u32_e32 v238, 127, v238
	v_and_b32_e32 v239, 127, v29
	v_sub_u32_e32 v239, 127, v239
	v_cndmask_b32_e64 v82, v82, v236, s[0:1]
	v_cndmask_b32_e64 v83, v83, v237, s[0:1]
	v_cndmask_b32_e64 v84, v84, v238, s[0:1]
	v_cndmask_b32_e64 v85, v85, v239, s[0:1]
	v_cmp_eq_u32_e64 s[14:15], v26, v18
	v_cmp_eq_u32_e64 s[34:35], v26, v22
	v_cmp_eq_u32_e64 s[42:43], v27, v19
	v_cmp_eq_u32_e64 s[66:67], v27, v23
	v_cndmask_b32_e64 v18, v18, 0, s[14:15]
	v_cndmask_b32_e64 v22, v22, 0, s[34:35]
	v_cndmask_b32_e64 v19, v19, 0, s[42:43]
	v_cndmask_b32_e64 v23, v23, 0, s[66:67]
	v_cmp_eq_u32_e64 s[14:15], v28, v20
	v_cmp_eq_u32_e64 s[34:35], v28, v24
	v_cmp_eq_u32_e64 s[42:43], v29, v21
	v_cmp_eq_u32_e64 s[66:67], v29, v25
	v_cndmask_b32_e64 v20, v20, 0, s[14:15]
	v_cndmask_b32_e64 v24, v24, 0, s[34:35]
	v_cndmask_b32_e64 v21, v21, 0, s[42:43]
	v_cndmask_b32_e64 v25, v25, 0, s[66:67]
	v_max_u32_e32 v26, v18, v22
	v_max_u32_e32 v27, v19, v23
	v_max_u32_e32 v28, v20, v24
	v_max_u32_e32 v29, v21, v25
	v_max_u32_dpp v26, v26, v26 quad_perm:[1,0,3,2] row_mask:0xf bank_mask:0xf
	v_max_u32_dpp v27, v27, v27 quad_perm:[1,0,3,2] row_mask:0xf bank_mask:0xf
	v_max_u32_dpp v28, v28, v28 quad_perm:[1,0,3,2] row_mask:0xf bank_mask:0xf
	v_max_u32_dpp v29, v29, v29 quad_perm:[1,0,3,2] row_mask:0xf bank_mask:0xf
	v_max_u32_dpp v26, v26, v26 quad_perm:[2,3,0,1] row_mask:0xf bank_mask:0xf
	v_max_u32_dpp v27, v27, v27 quad_perm:[2,3,0,1] row_mask:0xf bank_mask:0xf
	v_max_u32_dpp v28, v28, v28 quad_perm:[2,3,0,1] row_mask:0xf bank_mask:0xf
	v_max_u32_dpp v29, v29, v29 quad_perm:[2,3,0,1] row_mask:0xf bank_mask:0xf
	v_max_u32_dpp v26, v26, v26 row_half_mirror row_mask:0xf bank_mask:0xf
	v_max_u32_dpp v27, v27, v27 row_half_mirror row_mask:0xf bank_mask:0xf
	v_max_u32_dpp v28, v28, v28 row_half_mirror row_mask:0xf bank_mask:0xf
	v_max_u32_dpp v29, v29, v29 row_half_mirror row_mask:0xf bank_mask:0xf
	v_max_u32_dpp v26, v26, v26 row_mirror row_mask:0xf bank_mask:0xf
	v_max_u32_dpp v27, v27, v27 row_mirror row_mask:0xf bank_mask:0xf
	v_max_u32_dpp v28, v28, v28 row_mirror row_mask:0xf bank_mask:0xf
	v_max_u32_dpp v29, v29, v29 row_mirror row_mask:0xf bank_mask:0xf
	ds_swizzle_b32 v30, v26 offset:0x401f
	ds_swizzle_b32 v31, v27 offset:0x401f
	ds_swizzle_b32 v32, v28 offset:0x401f
	ds_swizzle_b32 v33, v29 offset:0x401f
	s_waitcnt lgkmcnt(3)
	v_max_u32_e32 v26, v26, v30
	s_waitcnt lgkmcnt(2)
	v_max_u32_e32 v27, v27, v31
	s_waitcnt lgkmcnt(1)
	v_max_u32_e32 v28, v28, v32
	s_waitcnt lgkmcnt(0)
	v_max_u32_e32 v29, v29, v33
	v_mov_b32_e32 v30, v26
	v_mov_b32_e32 v31, v27
	v_mov_b32_e32 v32, v28
	v_mov_b32_e32 v33, v29
	v_permlane32_swap_b32_e32 v26, v30
	v_permlane32_swap_b32_e32 v27, v31
	v_permlane32_swap_b32_e32 v28, v32
	v_permlane32_swap_b32_e32 v29, v33
	v_max_u32_e32 v26, v26, v30
	v_max_u32_e32 v27, v27, v31
	v_max_u32_e32 v28, v28, v32
	v_max_u32_e32 v29, v29, v33
	v_cmp_eq_u32_e64 s[0:1], 1, v184
	v_and_b32_e32 v236, 127, v26
	v_sub_u32_e32 v236, 127, v236
	v_and_b32_e32 v237, 127, v27
	v_sub_u32_e32 v237, 127, v237
	v_and_b32_e32 v238, 127, v28
	v_sub_u32_e32 v238, 127, v238
	v_and_b32_e32 v239, 127, v29
	v_sub_u32_e32 v239, 127, v239
	v_cndmask_b32_e64 v82, v82, v236, s[0:1]
	v_cndmask_b32_e64 v83, v83, v237, s[0:1]
	v_cndmask_b32_e64 v84, v84, v238, s[0:1]
	v_cndmask_b32_e64 v85, v85, v239, s[0:1]
	v_cmp_eq_u32_e64 s[14:15], v26, v18
	v_cmp_eq_u32_e64 s[34:35], v26, v22
	v_cmp_eq_u32_e64 s[42:43], v27, v19
	v_cmp_eq_u32_e64 s[66:67], v27, v23
	v_cndmask_b32_e64 v18, v18, 0, s[14:15]
	v_cndmask_b32_e64 v22, v22, 0, s[34:35]
	v_cndmask_b32_e64 v19, v19, 0, s[42:43]
	v_cndmask_b32_e64 v23, v23, 0, s[66:67]
	v_cmp_eq_u32_e64 s[14:15], v28, v20
	v_cmp_eq_u32_e64 s[34:35], v28, v24
	v_cmp_eq_u32_e64 s[42:43], v29, v21
	v_cmp_eq_u32_e64 s[66:67], v29, v25
	v_cndmask_b32_e64 v20, v20, 0, s[14:15]
	v_cndmask_b32_e64 v24, v24, 0, s[34:35]
	v_cndmask_b32_e64 v21, v21, 0, s[42:43]
	v_cndmask_b32_e64 v25, v25, 0, s[66:67]
	v_max_u32_e32 v26, v18, v22
	v_max_u32_e32 v27, v19, v23
	v_max_u32_e32 v28, v20, v24
	v_max_u32_e32 v29, v21, v25
	v_max_u32_dpp v26, v26, v26 quad_perm:[1,0,3,2] row_mask:0xf bank_mask:0xf
	v_max_u32_dpp v27, v27, v27 quad_perm:[1,0,3,2] row_mask:0xf bank_mask:0xf
	v_max_u32_dpp v28, v28, v28 quad_perm:[1,0,3,2] row_mask:0xf bank_mask:0xf
	v_max_u32_dpp v29, v29, v29 quad_perm:[1,0,3,2] row_mask:0xf bank_mask:0xf
	v_max_u32_dpp v26, v26, v26 quad_perm:[2,3,0,1] row_mask:0xf bank_mask:0xf
	v_max_u32_dpp v27, v27, v27 quad_perm:[2,3,0,1] row_mask:0xf bank_mask:0xf
	v_max_u32_dpp v28, v28, v28 quad_perm:[2,3,0,1] row_mask:0xf bank_mask:0xf
	v_max_u32_dpp v29, v29, v29 quad_perm:[2,3,0,1] row_mask:0xf bank_mask:0xf
	v_max_u32_dpp v26, v26, v26 row_half_mirror row_mask:0xf bank_mask:0xf
	v_max_u32_dpp v27, v27, v27 row_half_mirror row_mask:0xf bank_mask:0xf
	v_max_u32_dpp v28, v28, v28 row_half_mirror row_mask:0xf bank_mask:0xf
	v_max_u32_dpp v29, v29, v29 row_half_mirror row_mask:0xf bank_mask:0xf
	v_max_u32_dpp v26, v26, v26 row_mirror row_mask:0xf bank_mask:0xf
	v_max_u32_dpp v27, v27, v27 row_mirror row_mask:0xf bank_mask:0xf
	v_max_u32_dpp v28, v28, v28 row_mirror row_mask:0xf bank_mask:0xf
	v_max_u32_dpp v29, v29, v29 row_mirror row_mask:0xf bank_mask:0xf
	ds_swizzle_b32 v30, v26 offset:0x401f
	ds_swizzle_b32 v31, v27 offset:0x401f
	ds_swizzle_b32 v32, v28 offset:0x401f
	ds_swizzle_b32 v33, v29 offset:0x401f
	s_waitcnt lgkmcnt(3)
; __device__ __forceinline__ void nsa_quad_pre(int bg, int quad, const bf16_t* Q, const bf16_t* KV, const bf16_t* KCMP, const bf16_t* VCMPT, const float* GN, bf16_t* ONSA, ...
;     ...
;             for (int it = 0; it < 13; ++it) {
;                 unsigned m = k0 > k1 ? k0 : k1;
; #pragma unroll
;                 for (int off = 32; off >= 1; off >>= 1) { const unsigned o = (unsigned)__shfl_xor((int)m, off); m = o > m ? o : m; }
;                 if (k0 == m) k0 = 0u; if (k1 == m) k1 = 0u;
;                 if (lane == 0) selq[tt * 16 + it] = 127 - (int)(m & 127u);
	v_max_u32_e32 v26, v26, v30
	s_waitcnt lgkmcnt(2)
	v_max_u32_e32 v27, v27, v31
	s_waitcnt lgkmcnt(1)
	v_max_u32_e32 v28, v28, v32
	s_waitcnt lgkmcnt(0)
	v_max_u32_e32 v29, v29, v33
	v_mov_b32_e32 v30, v26
	v_mov_b32_e32 v31, v27
	v_mov_b32_e32 v32, v28
	v_mov_b32_e32 v33, v29
	v_permlane32_swap_b32_e32 v26, v30
	v_permlane32_swap_b32_e32 v27, v31
	v_permlane32_swap_b32_e32 v28, v32
	v_permlane32_swap_b32_e32 v29, v33
	v_max_u32_e32 v26, v26, v30
	v_max_u32_e32 v27, v27, v31
	v_max_u32_e32 v28, v28, v32
	v_max_u32_e32 v29, v29, v33
	v_cmp_eq_u32_e64 s[0:1], 2, v184
	v_and_b32_e32 v236, 127, v26
	v_sub_u32_e32 v236, 127, v236
	v_and_b32_e32 v237, 127, v27
	v_sub_u32_e32 v237, 127, v237
	v_and_b32_e32 v238, 127, v28
	v_sub_u32_e32 v238, 127, v238
	v_and_b32_e32 v239, 127, v29
	v_sub_u32_e32 v239, 127, v239
	v_cndmask_b32_e64 v82, v82, v236, s[0:1]
	v_cndmask_b32_e64 v83, v83, v237, s[0:1]
	v_cndmask_b32_e64 v84, v84, v238, s[0:1]
	v_cndmask_b32_e64 v85, v85, v239, s[0:1]
	v_cmp_eq_u32_e64 s[14:15], v26, v18
	v_cmp_eq_u32_e64 s[34:35], v26, v22
	v_cmp_eq_u32_e64 s[42:43], v27, v19
	v_cmp_eq_u32_e64 s[66:67], v27, v23
	v_cndmask_b32_e64 v18, v18, 0, s[14:15]
	v_cndmask_b32_e64 v22, v22, 0, s[34:35]
	v_cndmask_b32_e64 v19, v19, 0, s[42:43]
	v_cndmask_b32_e64 v23, v23, 0, s[66:67]
	v_cmp_eq_u32_e64 s[14:15], v28, v20
	v_cmp_eq_u32_e64 s[34:35], v28, v24
	v_cmp_eq_u32_e64 s[42:43], v29, v21
	v_cmp_eq_u32_e64 s[66:67], v29, v25
	v_cndmask_b32_e64 v20, v20, 0, s[14:15]
	v_cndmask_b32_e64 v24, v24, 0, s[34:35]
	v_cndmask_b32_e64 v21, v21, 0, s[42:43]
	v_cndmask_b32_e64 v25, v25, 0, s[66:67]
	v_max_u32_e32 v26, v18, v22
	v_max_u32_e32 v27, v19, v23
	v_max_u32_e32 v28, v20, v24
	v_max_u32_e32 v29, v21, v25
	v_max_u32_dpp v26, v26, v26 quad_perm:[1,0,3,2] row_mask:0xf bank_mask:0xf
	v_max_u32_dpp v27, v27, v27 quad_perm:[1,0,3,2] row_mask:0xf bank_mask:0xf
	v_max_u32_dpp v28, v28, v28 quad_perm:[1,0,3,2] row_mask:0xf bank_mask:0xf
	v_max_u32_dpp v29, v29, v29 quad_perm:[1,0,3,2] row_mask:0xf bank_mask:0xf
	v_max_u32_dpp v26, v26, v26 quad_perm:[2,3,0,1] row_mask:0xf bank_mask:0xf
	v_max_u32_dpp v27, v27, v27 quad_perm:[2,3,0,1] row_mask:0xf bank_mask:0xf
	v_max_u32_dpp v28, v28, v28 quad_perm:[2,3,0,1] row_mask:0xf bank_mask:0xf
	v_max_u32_dpp v29, v29, v29 quad_perm:[2,3,0,1] row_mask:0xf bank_mask:0xf
	v_max_u32_dpp v26, v26, v26 row_half_mirror row_mask:0xf bank_mask:0xf
	v_max_u32_dpp v27, v27, v27 row_half_mirror row_mask:0xf bank_mask:0xf
	v_max_u32_dpp v28, v28, v28 row_half_mirror row_mask:0xf bank_mask:0xf
	v_max_u32_dpp v29, v29, v29 row_half_mirror row_mask:0xf bank_mask:0xf
	v_max_u32_dpp v26, v26, v26 row_mirror row_mask:0xf bank_mask:0xf
	v_max_u32_dpp v27, v27, v27 row_mirror row_mask:0xf bank_mask:0xf
	v_max_u32_dpp v28, v28, v28 row_mirror row_mask:0xf bank_mask:0xf
	v_max_u32_dpp v29, v29, v29 row_mirror row_mask:0xf bank_mask:0xf
	ds_swizzle_b32 v30, v26 offset:0x401f
	ds_swizzle_b32 v31, v27 offset:0x401f
	ds_swizzle_b32 v32, v28 offset:0x401f
	ds_swizzle_b32 v33, v29 offset:0x401f
	s_waitcnt lgkmcnt(3)
	v_max_u32_e32 v26, v26, v30
	s_waitcnt lgkmcnt(2)
	v_max_u32_e32 v27, v27, v31
	s_waitcnt lgkmcnt(1)
	v_max_u32_e32 v28, v28, v32
	s_waitcnt lgkmcnt(0)
	v_max_u32_e32 v29, v29, v33
	v_mov_b32_e32 v30, v26
	v_mov_b32_e32 v31, v27
	v_mov_b32_e32 v32, v28
	v_mov_b32_e32 v33, v29
	v_permlane32_swap_b32_e32 v26, v30
	v_permlane32_swap_b32_e32 v27, v31
	v_permlane32_swap_b32_e32 v28, v32
	v_permlane32_swap_b32_e32 v29, v33
	v_max_u32_e32 v26, v26, v30
	v_max_u32_e32 v27, v27, v31
	v_max_u32_e32 v28, v28, v32
	v_max_u32_e32 v29, v29, v33
	v_cmp_eq_u32_e64 s[0:1], 3, v184
	v_and_b32_e32 v236, 127, v26
	v_sub_u32_e32 v236, 127, v236
	v_and_b32_e32 v237, 127, v27
	v_sub_u32_e32 v237, 127, v237
	v_and_b32_e32 v238, 127, v28
	v_sub_u32_e32 v238, 127, v238
	v_and_b32_e32 v239, 127, v29
	v_sub_u32_e32 v239, 127, v239
	v_cndmask_b32_e64 v82, v82, v236, s[0:1]
	v_cndmask_b32_e64 v83, v83, v237, s[0:1]
	v_cndmask_b32_e64 v84, v84, v238, s[0:1]
	v_cndmask_b32_e64 v85, v85, v239, s[0:1]
	v_cmp_eq_u32_e64 s[14:15], v26, v18
	v_cmp_eq_u32_e64 s[34:35], v26, v22
	v_cmp_eq_u32_e64 s[42:43], v27, v19
	v_cmp_eq_u32_e64 s[66:67], v27, v23
	v_cndmask_b32_e64 v18, v18, 0, s[14:15]
	v_cndmask_b32_e64 v22, v22, 0, s[34:35]
	v_cndmask_b32_e64 v19, v19, 0, s[42:43]
	v_cndmask_b32_e64 v23, v23, 0, s[66:67]
	v_cmp_eq_u32_e64 s[14:15], v28, v20
	v_cmp_eq_u32_e64 s[34:35], v28, v24
	v_cmp_eq_u32_e64 s[42:43], v29, v21
	v_cmp_eq_u32_e64 s[66:67], v29, v25
	v_cndmask_b32_e64 v20, v20, 0, s[14:15]
	v_cndmask_b32_e64 v24, v24, 0, s[34:35]
	v_cndmask_b32_e64 v21, v21, 0, s[42:43]
	v_cndmask_b32_e64 v25, v25, 0, s[66:67]
	v_max_u32_e32 v26, v18, v22
	v_max_u32_e32 v27, v19, v23
	v_max_u32_e32 v28, v20, v24
	v_max_u32_e32 v29, v21, v25
	v_max_u32_dpp v26, v26, v26 quad_perm:[1,0,3,2] row_mask:0xf bank_mask:0xf
	v_max_u32_dpp v27, v27, v27 quad_perm:[1,0,3,2] row_mask:0xf bank_mask:0xf
	v_max_u32_dpp v28, v28, v28 quad_perm:[1,0,3,2] row_mask:0xf bank_mask:0xf
	v_max_u32_dpp v29, v29, v29 quad_perm:[1,0,3,2] row_mask:0xf bank_mask:0xf
	v_max_u32_dpp v26, v26, v26 quad_perm:[2,3,0,1] row_mask:0xf bank_mask:0xf
	v_max_u32_dpp v27, v27, v27 quad_perm:[2,3,0,1] row_mask:0xf bank_mask:0xf
	v_max_u32_dpp v28, v28, v28 quad_perm:[2,3,0,1] row_mask:0xf bank_mask:0xf
	v_max_u32_dpp v29, v29, v29 quad_perm:[2,3,0,1] row_mask:0xf bank_mask:0xf
	v_max_u32_dpp v26, v26, v26 row_half_mirror row_mask:0xf bank_mask:0xf
	v_max_u32_dpp v27, v27, v27 row_half_mirror row_mask:0xf bank_mask:0xf
	v_max_u32_dpp v28, v28, v28 row_half_mirror row_mask:0xf bank_mask:0xf
	v_max_u32_dpp v29, v29, v29 row_half_mirror row_mask:0xf bank_mask:0xf
	v_max_u32_dpp v26, v26, v26 row_mirror row_mask:0xf bank_mask:0xf
	v_max_u32_dpp v27, v27, v27 row_mirror row_mask:0xf bank_mask:0xf
	v_max_u32_dpp v28, v28, v28 row_mirror row_mask:0xf bank_mask:0xf
	v_max_u32_dpp v29, v29, v29 row_mirror row_mask:0xf bank_mask:0xf
	ds_swizzle_b32 v30, v26 offset:0x401f
	ds_swizzle_b32 v31, v27 offset:0x401f
	ds_swizzle_b32 v32, v28 offset:0x401f
	ds_swizzle_b32 v33, v29 offset:0x401f
	s_waitcnt lgkmcnt(3)
; __device__ __forceinline__ void nsa_quad_pre(int bg, int quad, const bf16_t* Q, const bf16_t* KV, const bf16_t* KCMP, const bf16_t* VCMPT, const float* GN, bf16_t* ONSA, ...
;     ...
;             for (int it = 0; it < 13; ++it) {
;                 unsigned m = k0 > k1 ? k0 : k1;
; #pragma unroll
;                 for (int off = 32; off >= 1; off >>= 1) { const unsigned o = (unsigned)__shfl_xor((int)m, off); m = o > m ? o : m; }
;                 if (k0 == m) k0 = 0u; if (k1 == m) k1 = 0u;
;                 if (lane == 0) selq[tt * 16 + it] = 127 - (int)(m & 127u);
	v_max_u32_e32 v26, v26, v30
	s_waitcnt lgkmcnt(2)
	v_max_u32_e32 v27, v27, v31
	s_waitcnt lgkmcnt(1)
	v_max_u32_e32 v28, v28, v32
	s_waitcnt lgkmcnt(0)
	v_max_u32_e32 v29, v29, v33
	v_mov_b32_e32 v30, v26
	v_mov_b32_e32 v31, v27
	v_mov_b32_e32 v32, v28
	v_mov_b32_e32 v33, v29
	v_permlane32_swap_b32_e32 v26, v30
	v_permlane32_swap_b32_e32 v27, v31
	v_permlane32_swap_b32_e32 v28, v32
	v_permlane32_swap_b32_e32 v29, v33
	v_max_u32_e32 v26, v26, v30
	v_max_u32_e32 v27, v27, v31
	v_max_u32_e32 v28, v28, v32
	v_max_u32_e32 v29, v29, v33
	v_cmp_eq_u32_e64 s[0:1], 4, v184
	v_and_b32_e32 v236, 127, v26
	v_sub_u32_e32 v236, 127, v236
	v_and_b32_e32 v237, 127, v27
	v_sub_u32_e32 v237, 127, v237
	v_and_b32_e32 v238, 127, v28
	v_sub_u32_e32 v238, 127, v238
	v_and_b32_e32 v239, 127, v29
	v_sub_u32_e32 v239, 127, v239
	v_cndmask_b32_e64 v82, v82, v236, s[0:1]
	v_cndmask_b32_e64 v83, v83, v237, s[0:1]
	v_cndmask_b32_e64 v84, v84, v238, s[0:1]
	v_cndmask_b32_e64 v85, v85, v239, s[0:1]
	v_cmp_eq_u32_e64 s[14:15], v26, v18
	v_cmp_eq_u32_e64 s[34:35], v26, v22
	v_cmp_eq_u32_e64 s[42:43], v27, v19
	v_cmp_eq_u32_e64 s[66:67], v27, v23
	v_cndmask_b32_e64 v18, v18, 0, s[14:15]
	v_cndmask_b32_e64 v22, v22, 0, s[34:35]
	v_cndmask_b32_e64 v19, v19, 0, s[42:43]
	v_cndmask_b32_e64 v23, v23, 0, s[66:67]
	v_cmp_eq_u32_e64 s[14:15], v28, v20
	v_cmp_eq_u32_e64 s[34:35], v28, v24
	v_cmp_eq_u32_e64 s[42:43], v29, v21
	v_cmp_eq_u32_e64 s[66:67], v29, v25
	v_cndmask_b32_e64 v20, v20, 0, s[14:15]
	v_cndmask_b32_e64 v24, v24, 0, s[34:35]
	v_cndmask_b32_e64 v21, v21, 0, s[42:43]
	v_cndmask_b32_e64 v25, v25, 0, s[66:67]
	v_max_u32_e32 v26, v18, v22
	v_max_u32_e32 v27, v19, v23
	v_max_u32_e32 v28, v20, v24
	v_max_u32_e32 v29, v21, v25
	v_max_u32_dpp v26, v26, v26 quad_perm:[1,0,3,2] row_mask:0xf bank_mask:0xf
	v_max_u32_dpp v27, v27, v27 quad_perm:[1,0,3,2] row_mask:0xf bank_mask:0xf
	v_max_u32_dpp v28, v28, v28 quad_perm:[1,0,3,2] row_mask:0xf bank_mask:0xf
	v_max_u32_dpp v29, v29, v29 quad_perm:[1,0,3,2] row_mask:0xf bank_mask:0xf
	v_max_u32_dpp v26, v26, v26 quad_perm:[2,3,0,1] row_mask:0xf bank_mask:0xf
	v_max_u32_dpp v27, v27, v27 quad_perm:[2,3,0,1] row_mask:0xf bank_mask:0xf
	v_max_u32_dpp v28, v28, v28 quad_perm:[2,3,0,1] row_mask:0xf bank_mask:0xf
	v_max_u32_dpp v29, v29, v29 quad_perm:[2,3,0,1] row_mask:0xf bank_mask:0xf
	v_max_u32_dpp v26, v26, v26 row_half_mirror row_mask:0xf bank_mask:0xf
	v_max_u32_dpp v27, v27, v27 row_half_mirror row_mask:0xf bank_mask:0xf
	v_max_u32_dpp v28, v28, v28 row_half_mirror row_mask:0xf bank_mask:0xf
	v_max_u32_dpp v29, v29, v29 row_half_mirror row_mask:0xf bank_mask:0xf
	v_max_u32_dpp v26, v26, v26 row_mirror row_mask:0xf bank_mask:0xf
	v_max_u32_dpp v27, v27, v27 row_mirror row_mask:0xf bank_mask:0xf
	v_max_u32_dpp v28, v28, v28 row_mirror row_mask:0xf bank_mask:0xf
	v_max_u32_dpp v29, v29, v29 row_mirror row_mask:0xf bank_mask:0xf
	ds_swizzle_b32 v30, v26 offset:0x401f
	ds_swizzle_b32 v31, v27 offset:0x401f
	ds_swizzle_b32 v32, v28 offset:0x401f
	ds_swizzle_b32 v33, v29 offset:0x401f
	s_waitcnt lgkmcnt(3)
	v_max_u32_e32 v26, v26, v30
	s_waitcnt lgkmcnt(2)
	v_max_u32_e32 v27, v27, v31
	s_waitcnt lgkmcnt(1)
	v_max_u32_e32 v28, v28, v32
	s_waitcnt lgkmcnt(0)
	v_max_u32_e32 v29, v29, v33
	v_mov_b32_e32 v30, v26
	v_mov_b32_e32 v31, v27
	v_mov_b32_e32 v32, v28
	v_mov_b32_e32 v33, v29
	v_permlane32_swap_b32_e32 v26, v30
	v_permlane32_swap_b32_e32 v27, v31
	v_permlane32_swap_b32_e32 v28, v32
	v_permlane32_swap_b32_e32 v29, v33
	v_max_u32_e32 v26, v26, v30
	v_max_u32_e32 v27, v27, v31
	v_max_u32_e32 v28, v28, v32
	v_max_u32_e32 v29, v29, v33
	v_cmp_eq_u32_e64 s[0:1], 5, v184
	v_and_b32_e32 v236, 127, v26
	v_sub_u32_e32 v236, 127, v236
	v_and_b32_e32 v237, 127, v27
	v_sub_u32_e32 v237, 127, v237
	v_and_b32_e32 v238, 127, v28
	v_sub_u32_e32 v238, 127, v238
	v_and_b32_e32 v239, 127, v29
	v_sub_u32_e32 v239, 127, v239
	v_cndmask_b32_e64 v82, v82, v236, s[0:1]
	v_cndmask_b32_e64 v83, v83, v237, s[0:1]
	v_cndmask_b32_e64 v84, v84, v238, s[0:1]
	v_cndmask_b32_e64 v85, v85, v239, s[0:1]
	v_cmp_eq_u32_e64 s[14:15], v26, v18
	v_cmp_eq_u32_e64 s[34:35], v26, v22
	v_cmp_eq_u32_e64 s[42:43], v27, v19
	v_cmp_eq_u32_e64 s[66:67], v27, v23
	v_cndmask_b32_e64 v18, v18, 0, s[14:15]
	v_cndmask_b32_e64 v22, v22, 0, s[34:35]
	v_cndmask_b32_e64 v19, v19, 0, s[42:43]
	v_cndmask_b32_e64 v23, v23, 0, s[66:67]
	v_cmp_eq_u32_e64 s[14:15], v28, v20
	v_cmp_eq_u32_e64 s[34:35], v28, v24
	v_cmp_eq_u32_e64 s[42:43], v29, v21
	v_cmp_eq_u32_e64 s[66:67], v29, v25
	v_cndmask_b32_e64 v20, v20, 0, s[14:15]
	v_cndmask_b32_e64 v24, v24, 0, s[34:35]
	v_cndmask_b32_e64 v21, v21, 0, s[42:43]
	v_cndmask_b32_e64 v25, v25, 0, s[66:67]
	v_max_u32_e32 v26, v18, v22
	v_max_u32_e32 v27, v19, v23
	v_max_u32_e32 v28, v20, v24
	v_max_u32_e32 v29, v21, v25
	v_max_u32_dpp v26, v26, v26 quad_perm:[1,0,3,2] row_mask:0xf bank_mask:0xf
	v_max_u32_dpp v27, v27, v27 quad_perm:[1,0,3,2] row_mask:0xf bank_mask:0xf
	v_max_u32_dpp v28, v28, v28 quad_perm:[1,0,3,2] row_mask:0xf bank_mask:0xf
	v_max_u32_dpp v29, v29, v29 quad_perm:[1,0,3,2] row_mask:0xf bank_mask:0xf
	v_max_u32_dpp v26, v26, v26 quad_perm:[2,3,0,1] row_mask:0xf bank_mask:0xf
	v_max_u32_dpp v27, v27, v27 quad_perm:[2,3,0,1] row_mask:0xf bank_mask:0xf
	v_max_u32_dpp v28, v28, v28 quad_perm:[2,3,0,1] row_mask:0xf bank_mask:0xf
	v_max_u32_dpp v29, v29, v29 quad_perm:[2,3,0,1] row_mask:0xf bank_mask:0xf
	v_max_u32_dpp v26, v26, v26 row_half_mirror row_mask:0xf bank_mask:0xf
	v_max_u32_dpp v27, v27, v27 row_half_mirror row_mask:0xf bank_mask:0xf
	v_max_u32_dpp v28, v28, v28 row_half_mirror row_mask:0xf bank_mask:0xf
	v_max_u32_dpp v29, v29, v29 row_half_mirror row_mask:0xf bank_mask:0xf
	v_max_u32_dpp v26, v26, v26 row_mirror row_mask:0xf bank_mask:0xf
	v_max_u32_dpp v27, v27, v27 row_mirror row_mask:0xf bank_mask:0xf
	v_max_u32_dpp v28, v28, v28 row_mirror row_mask:0xf bank_mask:0xf
	v_max_u32_dpp v29, v29, v29 row_mirror row_mask:0xf bank_mask:0xf
	ds_swizzle_b32 v30, v26 offset:0x401f
	ds_swizzle_b32 v31, v27 offset:0x401f
	ds_swizzle_b32 v32, v28 offset:0x401f
	ds_swizzle_b32 v33, v29 offset:0x401f
	s_waitcnt lgkmcnt(3)
; __device__ __forceinline__ void nsa_quad_pre(int bg, int quad, const bf16_t* Q, const bf16_t* KV, const bf16_t* KCMP, const bf16_t* VCMPT, const float* GN, bf16_t* ONSA, ...
;     ...
;             for (int it = 0; it < 13; ++it) {
;                 unsigned m = k0 > k1 ? k0 : k1;
; #pragma unroll
;                 for (int off = 32; off >= 1; off >>= 1) { const unsigned o = (unsigned)__shfl_xor((int)m, off); m = o > m ? o : m; }
;                 if (k0 == m) k0 = 0u; if (k1 == m) k1 = 0u;
;                 if (lane == 0) selq[tt * 16 + it] = 127 - (int)(m & 127u);
	v_max_u32_e32 v26, v26, v30
	s_waitcnt lgkmcnt(2)
	v_max_u32_e32 v27, v27, v31
	s_waitcnt lgkmcnt(1)
	v_max_u32_e32 v28, v28, v32
	s_waitcnt lgkmcnt(0)
	v_max_u32_e32 v29, v29, v33
	v_mov_b32_e32 v30, v26
	v_mov_b32_e32 v31, v27
	v_mov_b32_e32 v32, v28
	v_mov_b32_e32 v33, v29
	v_permlane32_swap_b32_e32 v26, v30
	v_permlane32_swap_b32_e32 v27, v31
	v_permlane32_swap_b32_e32 v28, v32
	v_permlane32_swap_b32_e32 v29, v33
	v_max_u32_e32 v26, v26, v30
	v_max_u32_e32 v27, v27, v31
	v_max_u32_e32 v28, v28, v32
	v_max_u32_e32 v29, v29, v33
	v_cmp_eq_u32_e64 s[0:1], 6, v184
	v_and_b32_e32 v236, 127, v26
	v_sub_u32_e32 v236, 127, v236
	v_and_b32_e32 v237, 127, v27
	v_sub_u32_e32 v237, 127, v237
	v_and_b32_e32 v238, 127, v28
	v_sub_u32_e32 v238, 127, v238
	v_and_b32_e32 v239, 127, v29
	v_sub_u32_e32 v239, 127, v239
	v_cndmask_b32_e64 v82, v82, v236, s[0:1]
	v_cndmask_b32_e64 v83, v83, v237, s[0:1]
	v_cndmask_b32_e64 v84, v84, v238, s[0:1]
	v_cndmask_b32_e64 v85, v85, v239, s[0:1]
	v_cmp_eq_u32_e64 s[14:15], v26, v18
	v_cmp_eq_u32_e64 s[34:35], v26, v22
	v_cmp_eq_u32_e64 s[42:43], v27, v19
	v_cmp_eq_u32_e64 s[66:67], v27, v23
	v_cndmask_b32_e64 v18, v18, 0, s[14:15]
	v_cndmask_b32_e64 v22, v22, 0, s[34:35]
	v_cndmask_b32_e64 v19, v19, 0, s[42:43]
	v_cndmask_b32_e64 v23, v23, 0, s[66:67]
	v_cmp_eq_u32_e64 s[14:15], v28, v20
	v_cmp_eq_u32_e64 s[34:35], v28, v24
	v_cmp_eq_u32_e64 s[42:43], v29, v21
	v_cmp_eq_u32_e64 s[66:67], v29, v25
	v_cndmask_b32_e64 v20, v20, 0, s[14:15]
	v_cndmask_b32_e64 v24, v24, 0, s[34:35]
	v_cndmask_b32_e64 v21, v21, 0, s[42:43]
	v_cndmask_b32_e64 v25, v25, 0, s[66:67]
	v_max_u32_e32 v26, v18, v22
	v_max_u32_e32 v27, v19, v23
	v_max_u32_e32 v28, v20, v24
	v_max_u32_e32 v29, v21, v25
	v_max_u32_dpp v26, v26, v26 quad_perm:[1,0,3,2] row_mask:0xf bank_mask:0xf
	v_max_u32_dpp v27, v27, v27 quad_perm:[1,0,3,2] row_mask:0xf bank_mask:0xf
	v_max_u32_dpp v28, v28, v28 quad_perm:[1,0,3,2] row_mask:0xf bank_mask:0xf
	v_max_u32_dpp v29, v29, v29 quad_perm:[1,0,3,2] row_mask:0xf bank_mask:0xf
	v_max_u32_dpp v26, v26, v26 quad_perm:[2,3,0,1] row_mask:0xf bank_mask:0xf
	v_max_u32_dpp v27, v27, v27 quad_perm:[2,3,0,1] row_mask:0xf bank_mask:0xf
	v_max_u32_dpp v28, v28, v28 quad_perm:[2,3,0,1] row_mask:0xf bank_mask:0xf
	v_max_u32_dpp v29, v29, v29 quad_perm:[2,3,0,1] row_mask:0xf bank_mask:0xf
	v_max_u32_dpp v26, v26, v26 row_half_mirror row_mask:0xf bank_mask:0xf
	v_max_u32_dpp v27, v27, v27 row_half_mirror row_mask:0xf bank_mask:0xf
	v_max_u32_dpp v28, v28, v28 row_half_mirror row_mask:0xf bank_mask:0xf
	v_max_u32_dpp v29, v29, v29 row_half_mirror row_mask:0xf bank_mask:0xf
	v_max_u32_dpp v26, v26, v26 row_mirror row_mask:0xf bank_mask:0xf
	v_max_u32_dpp v27, v27, v27 row_mirror row_mask:0xf bank_mask:0xf
	v_max_u32_dpp v28, v28, v28 row_mirror row_mask:0xf bank_mask:0xf
	v_max_u32_dpp v29, v29, v29 row_mirror row_mask:0xf bank_mask:0xf
	ds_swizzle_b32 v30, v26 offset:0x401f
	ds_swizzle_b32 v31, v27 offset:0x401f
	ds_swizzle_b32 v32, v28 offset:0x401f
	ds_swizzle_b32 v33, v29 offset:0x401f
	s_waitcnt lgkmcnt(3)
	v_max_u32_e32 v26, v26, v30
	s_waitcnt lgkmcnt(2)
	v_max_u32_e32 v27, v27, v31
	s_waitcnt lgkmcnt(1)
	v_max_u32_e32 v28, v28, v32
	s_waitcnt lgkmcnt(0)
	v_max_u32_e32 v29, v29, v33
	v_mov_b32_e32 v30, v26
	v_mov_b32_e32 v31, v27
	v_mov_b32_e32 v32, v28
	v_mov_b32_e32 v33, v29
	v_permlane32_swap_b32_e32 v26, v30
	v_permlane32_swap_b32_e32 v27, v31
	v_permlane32_swap_b32_e32 v28, v32
	v_permlane32_swap_b32_e32 v29, v33
	v_max_u32_e32 v26, v26, v30
	v_max_u32_e32 v27, v27, v31
	v_max_u32_e32 v28, v28, v32
	v_max_u32_e32 v29, v29, v33
	v_cmp_eq_u32_e64 s[0:1], 7, v184
	v_and_b32_e32 v236, 127, v26
	v_sub_u32_e32 v236, 127, v236
	v_and_b32_e32 v237, 127, v27
	v_sub_u32_e32 v237, 127, v237
	v_and_b32_e32 v238, 127, v28
	v_sub_u32_e32 v238, 127, v238
	v_and_b32_e32 v239, 127, v29
	v_sub_u32_e32 v239, 127, v239
	v_cndmask_b32_e64 v82, v82, v236, s[0:1]
	v_cndmask_b32_e64 v83, v83, v237, s[0:1]
	v_cndmask_b32_e64 v84, v84, v238, s[0:1]
	v_cndmask_b32_e64 v85, v85, v239, s[0:1]
	v_cmp_eq_u32_e64 s[14:15], v26, v18
	v_cmp_eq_u32_e64 s[34:35], v26, v22
	v_cmp_eq_u32_e64 s[42:43], v27, v19
	v_cmp_eq_u32_e64 s[66:67], v27, v23
	v_cndmask_b32_e64 v18, v18, 0, s[14:15]
	v_cndmask_b32_e64 v22, v22, 0, s[34:35]
	v_cndmask_b32_e64 v19, v19, 0, s[42:43]
	v_cndmask_b32_e64 v23, v23, 0, s[66:67]
	v_cmp_eq_u32_e64 s[14:15], v28, v20
	v_cmp_eq_u32_e64 s[34:35], v28, v24
	v_cmp_eq_u32_e64 s[42:43], v29, v21
	v_cmp_eq_u32_e64 s[66:67], v29, v25
	v_cndmask_b32_e64 v20, v20, 0, s[14:15]
	v_cndmask_b32_e64 v24, v24, 0, s[34:35]
	v_cndmask_b32_e64 v21, v21, 0, s[42:43]
	v_cndmask_b32_e64 v25, v25, 0, s[66:67]
	v_max_u32_e32 v26, v18, v22
	v_max_u32_e32 v27, v19, v23
	v_max_u32_e32 v28, v20, v24
	v_max_u32_e32 v29, v21, v25
	v_max_u32_dpp v26, v26, v26 quad_perm:[1,0,3,2] row_mask:0xf bank_mask:0xf
	v_max_u32_dpp v27, v27, v27 quad_perm:[1,0,3,2] row_mask:0xf bank_mask:0xf
	v_max_u32_dpp v28, v28, v28 quad_perm:[1,0,3,2] row_mask:0xf bank_mask:0xf
	v_max_u32_dpp v29, v29, v29 quad_perm:[1,0,3,2] row_mask:0xf bank_mask:0xf
	v_max_u32_dpp v26, v26, v26 quad_perm:[2,3,0,1] row_mask:0xf bank_mask:0xf
	v_max_u32_dpp v27, v27, v27 quad_perm:[2,3,0,1] row_mask:0xf bank_mask:0xf
	v_max_u32_dpp v28, v28, v28 quad_perm:[2,3,0,1] row_mask:0xf bank_mask:0xf
	v_max_u32_dpp v29, v29, v29 quad_perm:[2,3,0,1] row_mask:0xf bank_mask:0xf
	v_max_u32_dpp v26, v26, v26 row_half_mirror row_mask:0xf bank_mask:0xf
	v_max_u32_dpp v27, v27, v27 row_half_mirror row_mask:0xf bank_mask:0xf
	v_max_u32_dpp v28, v28, v28 row_half_mirror row_mask:0xf bank_mask:0xf
	v_max_u32_dpp v29, v29, v29 row_half_mirror row_mask:0xf bank_mask:0xf
	v_max_u32_dpp v26, v26, v26 row_mirror row_mask:0xf bank_mask:0xf
	v_max_u32_dpp v27, v27, v27 row_mirror row_mask:0xf bank_mask:0xf
	v_max_u32_dpp v28, v28, v28 row_mirror row_mask:0xf bank_mask:0xf
	v_max_u32_dpp v29, v29, v29 row_mirror row_mask:0xf bank_mask:0xf
	ds_swizzle_b32 v30, v26 offset:0x401f
	ds_swizzle_b32 v31, v27 offset:0x401f
	ds_swizzle_b32 v32, v28 offset:0x401f
	ds_swizzle_b32 v33, v29 offset:0x401f
	s_waitcnt lgkmcnt(3)
; __device__ __forceinline__ void nsa_quad_pre(int bg, int quad, const bf16_t* Q, const bf16_t* KV, const bf16_t* KCMP, const bf16_t* VCMPT, const float* GN, bf16_t* ONSA, ...
;     ...
;             for (int it = 0; it < 13; ++it) {
;                 unsigned m = k0 > k1 ? k0 : k1;
; #pragma unroll
;                 for (int off = 32; off >= 1; off >>= 1) { const unsigned o = (unsigned)__shfl_xor((int)m, off); m = o > m ? o : m; }
;                 if (k0 == m) k0 = 0u; if (k1 == m) k1 = 0u;
;                 if (lane == 0) selq[tt * 16 + it] = 127 - (int)(m & 127u);
	v_max_u32_e32 v26, v26, v30
	s_waitcnt lgkmcnt(2)
	v_max_u32_e32 v27, v27, v31
	s_waitcnt lgkmcnt(1)
	v_max_u32_e32 v28, v28, v32
	s_waitcnt lgkmcnt(0)
	v_max_u32_e32 v29, v29, v33
	v_mov_b32_e32 v30, v26
	v_mov_b32_e32 v31, v27
	v_mov_b32_e32 v32, v28
	v_mov_b32_e32 v33, v29
	v_permlane32_swap_b32_e32 v26, v30
	v_permlane32_swap_b32_e32 v27, v31
	v_permlane32_swap_b32_e32 v28, v32
	v_permlane32_swap_b32_e32 v29, v33
	v_max_u32_e32 v26, v26, v30
	v_max_u32_e32 v27, v27, v31
	v_max_u32_e32 v28, v28, v32
	v_max_u32_e32 v29, v29, v33
	v_cmp_eq_u32_e64 s[0:1], 8, v184
	v_and_b32_e32 v236, 127, v26
	v_sub_u32_e32 v236, 127, v236
	v_and_b32_e32 v237, 127, v27
	v_sub_u32_e32 v237, 127, v237
	v_and_b32_e32 v238, 127, v28
	v_sub_u32_e32 v238, 127, v238
	v_and_b32_e32 v239, 127, v29
	v_sub_u32_e32 v239, 127, v239
	v_cndmask_b32_e64 v82, v82, v236, s[0:1]
	v_cndmask_b32_e64 v83, v83, v237, s[0:1]
	v_cndmask_b32_e64 v84, v84, v238, s[0:1]
	v_cndmask_b32_e64 v85, v85, v239, s[0:1]
	v_cmp_eq_u32_e64 s[14:15], v26, v18
	v_cmp_eq_u32_e64 s[34:35], v26, v22
	v_cmp_eq_u32_e64 s[42:43], v27, v19
	v_cmp_eq_u32_e64 s[66:67], v27, v23
	v_cndmask_b32_e64 v18, v18, 0, s[14:15]
	v_cndmask_b32_e64 v22, v22, 0, s[34:35]
	v_cndmask_b32_e64 v19, v19, 0, s[42:43]
	v_cndmask_b32_e64 v23, v23, 0, s[66:67]
	v_cmp_eq_u32_e64 s[14:15], v28, v20
	v_cmp_eq_u32_e64 s[34:35], v28, v24
	v_cmp_eq_u32_e64 s[42:43], v29, v21
	v_cmp_eq_u32_e64 s[66:67], v29, v25
	v_cndmask_b32_e64 v20, v20, 0, s[14:15]
	v_cndmask_b32_e64 v24, v24, 0, s[34:35]
	v_cndmask_b32_e64 v21, v21, 0, s[42:43]
	v_cndmask_b32_e64 v25, v25, 0, s[66:67]
	v_max_u32_e32 v26, v18, v22
	v_max_u32_e32 v27, v19, v23
	v_max_u32_e32 v28, v20, v24
	v_max_u32_e32 v29, v21, v25
	v_max_u32_dpp v26, v26, v26 quad_perm:[1,0,3,2] row_mask:0xf bank_mask:0xf
	v_max_u32_dpp v27, v27, v27 quad_perm:[1,0,3,2] row_mask:0xf bank_mask:0xf
	v_max_u32_dpp v28, v28, v28 quad_perm:[1,0,3,2] row_mask:0xf bank_mask:0xf
	v_max_u32_dpp v29, v29, v29 quad_perm:[1,0,3,2] row_mask:0xf bank_mask:0xf
	v_max_u32_dpp v26, v26, v26 quad_perm:[2,3,0,1] row_mask:0xf bank_mask:0xf
	v_max_u32_dpp v27, v27, v27 quad_perm:[2,3,0,1] row_mask:0xf bank_mask:0xf
	v_max_u32_dpp v28, v28, v28 quad_perm:[2,3,0,1] row_mask:0xf bank_mask:0xf
	v_max_u32_dpp v29, v29, v29 quad_perm:[2,3,0,1] row_mask:0xf bank_mask:0xf
	v_max_u32_dpp v26, v26, v26 row_half_mirror row_mask:0xf bank_mask:0xf
	v_max_u32_dpp v27, v27, v27 row_half_mirror row_mask:0xf bank_mask:0xf
	v_max_u32_dpp v28, v28, v28 row_half_mirror row_mask:0xf bank_mask:0xf
	v_max_u32_dpp v29, v29, v29 row_half_mirror row_mask:0xf bank_mask:0xf
	v_max_u32_dpp v26, v26, v26 row_mirror row_mask:0xf bank_mask:0xf
	v_max_u32_dpp v27, v27, v27 row_mirror row_mask:0xf bank_mask:0xf
	v_max_u32_dpp v28, v28, v28 row_mirror row_mask:0xf bank_mask:0xf
	v_max_u32_dpp v29, v29, v29 row_mirror row_mask:0xf bank_mask:0xf
	ds_swizzle_b32 v30, v26 offset:0x401f
	ds_swizzle_b32 v31, v27 offset:0x401f
	ds_swizzle_b32 v32, v28 offset:0x401f
	ds_swizzle_b32 v33, v29 offset:0x401f
	s_waitcnt lgkmcnt(3)
	v_max_u32_e32 v26, v26, v30
	s_waitcnt lgkmcnt(2)
	v_max_u32_e32 v27, v27, v31
	s_waitcnt lgkmcnt(1)
	v_max_u32_e32 v28, v28, v32
	s_waitcnt lgkmcnt(0)
	v_max_u32_e32 v29, v29, v33
	v_mov_b32_e32 v30, v26
	v_mov_b32_e32 v31, v27
	v_mov_b32_e32 v32, v28
	v_mov_b32_e32 v33, v29
	v_permlane32_swap_b32_e32 v26, v30
	v_permlane32_swap_b32_e32 v27, v31
	v_permlane32_swap_b32_e32 v28, v32
	v_permlane32_swap_b32_e32 v29, v33
	v_max_u32_e32 v26, v26, v30
	v_max_u32_e32 v27, v27, v31
	v_max_u32_e32 v28, v28, v32
	v_max_u32_e32 v29, v29, v33
	v_cmp_eq_u32_e64 s[0:1], 9, v184
	v_and_b32_e32 v236, 127, v26
	v_sub_u32_e32 v236, 127, v236
	v_and_b32_e32 v237, 127, v27
	v_sub_u32_e32 v237, 127, v237
	v_and_b32_e32 v238, 127, v28
	v_sub_u32_e32 v238, 127, v238
	v_and_b32_e32 v239, 127, v29
	v_sub_u32_e32 v239, 127, v239
	v_cndmask_b32_e64 v82, v82, v236, s[0:1]
	v_cndmask_b32_e64 v83, v83, v237, s[0:1]
	v_cndmask_b32_e64 v84, v84, v238, s[0:1]
	v_cndmask_b32_e64 v85, v85, v239, s[0:1]
	v_cmp_eq_u32_e64 s[14:15], v26, v18
	v_cmp_eq_u32_e64 s[34:35], v26, v22
	v_cmp_eq_u32_e64 s[42:43], v27, v19
	v_cmp_eq_u32_e64 s[66:67], v27, v23
	v_cndmask_b32_e64 v18, v18, 0, s[14:15]
	v_cndmask_b32_e64 v22, v22, 0, s[34:35]
	v_cndmask_b32_e64 v19, v19, 0, s[42:43]
	v_cndmask_b32_e64 v23, v23, 0, s[66:67]
	v_cmp_eq_u32_e64 s[14:15], v28, v20
	v_cmp_eq_u32_e64 s[34:35], v28, v24
	v_cmp_eq_u32_e64 s[42:43], v29, v21
	v_cmp_eq_u32_e64 s[66:67], v29, v25
	v_cndmask_b32_e64 v20, v20, 0, s[14:15]
	v_cndmask_b32_e64 v24, v24, 0, s[34:35]
	v_cndmask_b32_e64 v21, v21, 0, s[42:43]
	v_cndmask_b32_e64 v25, v25, 0, s[66:67]
	v_max_u32_e32 v26, v18, v22
	v_max_u32_e32 v27, v19, v23
	v_max_u32_e32 v28, v20, v24
	v_max_u32_e32 v29, v21, v25
	v_max_u32_dpp v26, v26, v26 quad_perm:[1,0,3,2] row_mask:0xf bank_mask:0xf
	v_max_u32_dpp v27, v27, v27 quad_perm:[1,0,3,2] row_mask:0xf bank_mask:0xf
	v_max_u32_dpp v28, v28, v28 quad_perm:[1,0,3,2] row_mask:0xf bank_mask:0xf
	v_max_u32_dpp v29, v29, v29 quad_perm:[1,0,3,2] row_mask:0xf bank_mask:0xf
	v_max_u32_dpp v26, v26, v26 quad_perm:[2,3,0,1] row_mask:0xf bank_mask:0xf
	v_max_u32_dpp v27, v27, v27 quad_perm:[2,3,0,1] row_mask:0xf bank_mask:0xf
	v_max_u32_dpp v28, v28, v28 quad_perm:[2,3,0,1] row_mask:0xf bank_mask:0xf
	v_max_u32_dpp v29, v29, v29 quad_perm:[2,3,0,1] row_mask:0xf bank_mask:0xf
	v_max_u32_dpp v26, v26, v26 row_half_mirror row_mask:0xf bank_mask:0xf
	v_max_u32_dpp v27, v27, v27 row_half_mirror row_mask:0xf bank_mask:0xf
	v_max_u32_dpp v28, v28, v28 row_half_mirror row_mask:0xf bank_mask:0xf
	v_max_u32_dpp v29, v29, v29 row_half_mirror row_mask:0xf bank_mask:0xf
	v_max_u32_dpp v26, v26, v26 row_mirror row_mask:0xf bank_mask:0xf
	v_max_u32_dpp v27, v27, v27 row_mirror row_mask:0xf bank_mask:0xf
	v_max_u32_dpp v28, v28, v28 row_mirror row_mask:0xf bank_mask:0xf
	v_max_u32_dpp v29, v29, v29 row_mirror row_mask:0xf bank_mask:0xf
	ds_swizzle_b32 v30, v26 offset:0x401f
	ds_swizzle_b32 v31, v27 offset:0x401f
	ds_swizzle_b32 v32, v28 offset:0x401f
	ds_swizzle_b32 v33, v29 offset:0x401f
	s_waitcnt lgkmcnt(3)
; __device__ __forceinline__ void nsa_quad_pre(int bg, int quad, const bf16_t* Q, const bf16_t* KV, const bf16_t* KCMP, const bf16_t* VCMPT, const float* GN, bf16_t* ONSA, ...
;     ...
;             for (int it = 0; it < 13; ++it) {
;                 unsigned m = k0 > k1 ? k0 : k1;
; #pragma unroll
;                 for (int off = 32; off >= 1; off >>= 1) { const unsigned o = (unsigned)__shfl_xor((int)m, off); m = o > m ? o : m; }
;                 if (k0 == m) k0 = 0u; if (k1 == m) k1 = 0u;
;                 if (lane == 0) selq[tt * 16 + it] = 127 - (int)(m & 127u);
	v_max_u32_e32 v26, v26, v30
	s_waitcnt lgkmcnt(2)
	v_max_u32_e32 v27, v27, v31
	s_waitcnt lgkmcnt(1)
	v_max_u32_e32 v28, v28, v32
	s_waitcnt lgkmcnt(0)
	v_max_u32_e32 v29, v29, v33
	v_mov_b32_e32 v30, v26
	v_mov_b32_e32 v31, v27
	v_mov_b32_e32 v32, v28
	v_mov_b32_e32 v33, v29
	v_permlane32_swap_b32_e32 v26, v30
	v_permlane32_swap_b32_e32 v27, v31
	v_permlane32_swap_b32_e32 v28, v32
	v_permlane32_swap_b32_e32 v29, v33
	v_max_u32_e32 v26, v26, v30
	v_max_u32_e32 v27, v27, v31
	v_max_u32_e32 v28, v28, v32
	v_max_u32_e32 v29, v29, v33
	v_cmp_eq_u32_e64 s[0:1], 10, v184
	v_and_b32_e32 v236, 127, v26
	v_sub_u32_e32 v236, 127, v236
	v_and_b32_e32 v237, 127, v27
	v_sub_u32_e32 v237, 127, v237
	v_and_b32_e32 v238, 127, v28
	v_sub_u32_e32 v238, 127, v238
	v_and_b32_e32 v239, 127, v29
	v_sub_u32_e32 v239, 127, v239
	v_cndmask_b32_e64 v82, v82, v236, s[0:1]
	v_cndmask_b32_e64 v83, v83, v237, s[0:1]
	v_cndmask_b32_e64 v84, v84, v238, s[0:1]
	v_cndmask_b32_e64 v85, v85, v239, s[0:1]
	v_cmp_eq_u32_e64 s[14:15], v26, v18
	v_cmp_eq_u32_e64 s[34:35], v26, v22
	v_cmp_eq_u32_e64 s[42:43], v27, v19
	v_cmp_eq_u32_e64 s[66:67], v27, v23
	v_cndmask_b32_e64 v18, v18, 0, s[14:15]
	v_cndmask_b32_e64 v22, v22, 0, s[34:35]
	v_cndmask_b32_e64 v19, v19, 0, s[42:43]
	v_cndmask_b32_e64 v23, v23, 0, s[66:67]
	v_cmp_eq_u32_e64 s[14:15], v28, v20
	v_cmp_eq_u32_e64 s[34:35], v28, v24
	v_cmp_eq_u32_e64 s[42:43], v29, v21
	v_cmp_eq_u32_e64 s[66:67], v29, v25
	v_cndmask_b32_e64 v20, v20, 0, s[14:15]
	v_cndmask_b32_e64 v24, v24, 0, s[34:35]
	v_cndmask_b32_e64 v21, v21, 0, s[42:43]
	v_cndmask_b32_e64 v25, v25, 0, s[66:67]
	v_max_u32_e32 v26, v18, v22
	v_max_u32_e32 v27, v19, v23
	v_max_u32_e32 v28, v20, v24
	v_max_u32_e32 v29, v21, v25
	v_max_u32_dpp v26, v26, v26 quad_perm:[1,0,3,2] row_mask:0xf bank_mask:0xf
	v_max_u32_dpp v27, v27, v27 quad_perm:[1,0,3,2] row_mask:0xf bank_mask:0xf
	v_max_u32_dpp v28, v28, v28 quad_perm:[1,0,3,2] row_mask:0xf bank_mask:0xf
	v_max_u32_dpp v29, v29, v29 quad_perm:[1,0,3,2] row_mask:0xf bank_mask:0xf
	v_max_u32_dpp v26, v26, v26 quad_perm:[2,3,0,1] row_mask:0xf bank_mask:0xf
	v_max_u32_dpp v27, v27, v27 quad_perm:[2,3,0,1] row_mask:0xf bank_mask:0xf
	v_max_u32_dpp v28, v28, v28 quad_perm:[2,3,0,1] row_mask:0xf bank_mask:0xf
	v_max_u32_dpp v29, v29, v29 quad_perm:[2,3,0,1] row_mask:0xf bank_mask:0xf
	v_max_u32_dpp v26, v26, v26 row_half_mirror row_mask:0xf bank_mask:0xf
	v_max_u32_dpp v27, v27, v27 row_half_mirror row_mask:0xf bank_mask:0xf
	v_max_u32_dpp v28, v28, v28 row_half_mirror row_mask:0xf bank_mask:0xf
	v_max_u32_dpp v29, v29, v29 row_half_mirror row_mask:0xf bank_mask:0xf
	v_max_u32_dpp v26, v26, v26 row_mirror row_mask:0xf bank_mask:0xf
	v_max_u32_dpp v27, v27, v27 row_mirror row_mask:0xf bank_mask:0xf
	v_max_u32_dpp v28, v28, v28 row_mirror row_mask:0xf bank_mask:0xf
	v_max_u32_dpp v29, v29, v29 row_mirror row_mask:0xf bank_mask:0xf
	ds_swizzle_b32 v30, v26 offset:0x401f
	ds_swizzle_b32 v31, v27 offset:0x401f
	ds_swizzle_b32 v32, v28 offset:0x401f
	ds_swizzle_b32 v33, v29 offset:0x401f
	s_waitcnt lgkmcnt(3)
	v_max_u32_e32 v26, v26, v30
	s_waitcnt lgkmcnt(2)
	v_max_u32_e32 v27, v27, v31
	s_waitcnt lgkmcnt(1)
	v_max_u32_e32 v28, v28, v32
	s_waitcnt lgkmcnt(0)
; __device__ __forceinline__ void nsa_quad_pre(int bg, int quad, const bf16_t* Q, const bf16_t* KV, const bf16_t* KCMP, const bf16_t* VCMPT, const float* GN, bf16_t* ONSA, ...
;     ...
;             for (int it = 0; it < 13; ++it) {
;                 unsigned m = k0 > k1 ? k0 : k1;
; #pragma unroll
;                 for (int off = 32; off >= 1; off >>= 1) { const unsigned o = (unsigned)__shfl_xor((int)m, off); m = o > m ? o : m; }
;                 if (k0 == m) k0 = 0u; if (k1 == m) k1 = 0u;
;                 if (lane == 0) selq[tt * 16 + it] = 127 - (int)(m & 127u);
;             }
;             if (lane == 0) { selq[tt * 16 + 13] = 0; selq[tt * 16 + 14] = cur - 1; selq[tt * 16 + 15] = cur; }
	v_max_u32_e32 v29, v29, v33
	v_mov_b32_e32 v30, v26
	v_mov_b32_e32 v31, v27
	v_mov_b32_e32 v32, v28
	v_mov_b32_e32 v33, v29
	v_permlane32_swap_b32_e32 v26, v30
	v_permlane32_swap_b32_e32 v27, v31
	v_permlane32_swap_b32_e32 v28, v32
	v_permlane32_swap_b32_e32 v29, v33
	v_max_u32_e32 v26, v26, v30
	v_max_u32_e32 v27, v27, v31
	v_max_u32_e32 v28, v28, v32
	v_max_u32_e32 v29, v29, v33
	v_cmp_eq_u32_e64 s[0:1], 11, v184
	v_and_b32_e32 v236, 127, v26
	v_sub_u32_e32 v236, 127, v236
	v_and_b32_e32 v237, 127, v27
	v_sub_u32_e32 v237, 127, v237
	v_and_b32_e32 v238, 127, v28
	v_sub_u32_e32 v238, 127, v238
	v_and_b32_e32 v239, 127, v29
	v_sub_u32_e32 v239, 127, v239
	v_cndmask_b32_e64 v82, v82, v236, s[0:1]
	v_cndmask_b32_e64 v83, v83, v237, s[0:1]
	v_cndmask_b32_e64 v84, v84, v238, s[0:1]
	v_cndmask_b32_e64 v85, v85, v239, s[0:1]
	v_cmp_eq_u32_e64 s[14:15], v26, v18
	v_cmp_eq_u32_e64 s[34:35], v26, v22
	v_cmp_eq_u32_e64 s[42:43], v27, v19
	v_cmp_eq_u32_e64 s[66:67], v27, v23
	v_cndmask_b32_e64 v18, v18, 0, s[14:15]
	v_cndmask_b32_e64 v22, v22, 0, s[34:35]
	v_cndmask_b32_e64 v19, v19, 0, s[42:43]
	v_cndmask_b32_e64 v23, v23, 0, s[66:67]
	v_cmp_eq_u32_e64 s[14:15], v28, v20
	v_cmp_eq_u32_e64 s[34:35], v28, v24
	v_cmp_eq_u32_e64 s[42:43], v29, v21
	v_cmp_eq_u32_e64 s[66:67], v29, v25
	v_cndmask_b32_e64 v20, v20, 0, s[14:15]
	v_cndmask_b32_e64 v24, v24, 0, s[34:35]
	v_cndmask_b32_e64 v21, v21, 0, s[42:43]
	v_cndmask_b32_e64 v25, v25, 0, s[66:67]
	v_max_u32_e32 v26, v18, v22
	v_max_u32_e32 v27, v19, v23
	v_max_u32_e32 v28, v20, v24
	v_max_u32_e32 v29, v21, v25
	v_max_u32_dpp v26, v26, v26 quad_perm:[1,0,3,2] row_mask:0xf bank_mask:0xf
	v_max_u32_dpp v27, v27, v27 quad_perm:[1,0,3,2] row_mask:0xf bank_mask:0xf
	v_max_u32_dpp v28, v28, v28 quad_perm:[1,0,3,2] row_mask:0xf bank_mask:0xf
	v_max_u32_dpp v29, v29, v29 quad_perm:[1,0,3,2] row_mask:0xf bank_mask:0xf
	v_max_u32_dpp v26, v26, v26 quad_perm:[2,3,0,1] row_mask:0xf bank_mask:0xf
	v_max_u32_dpp v27, v27, v27 quad_perm:[2,3,0,1] row_mask:0xf bank_mask:0xf
	v_max_u32_dpp v28, v28, v28 quad_perm:[2,3,0,1] row_mask:0xf bank_mask:0xf
	v_max_u32_dpp v29, v29, v29 quad_perm:[2,3,0,1] row_mask:0xf bank_mask:0xf
	v_max_u32_dpp v26, v26, v26 row_half_mirror row_mask:0xf bank_mask:0xf
	v_max_u32_dpp v27, v27, v27 row_half_mirror row_mask:0xf bank_mask:0xf
	v_max_u32_dpp v28, v28, v28 row_half_mirror row_mask:0xf bank_mask:0xf
	v_max_u32_dpp v29, v29, v29 row_half_mirror row_mask:0xf bank_mask:0xf
	v_max_u32_dpp v26, v26, v26 row_mirror row_mask:0xf bank_mask:0xf
	v_max_u32_dpp v27, v27, v27 row_mirror row_mask:0xf bank_mask:0xf
	v_max_u32_dpp v28, v28, v28 row_mirror row_mask:0xf bank_mask:0xf
	v_max_u32_dpp v29, v29, v29 row_mirror row_mask:0xf bank_mask:0xf
	ds_swizzle_b32 v30, v26 offset:0x401f
	ds_swizzle_b32 v31, v27 offset:0x401f
	ds_swizzle_b32 v32, v28 offset:0x401f
	ds_swizzle_b32 v33, v29 offset:0x401f
	s_waitcnt lgkmcnt(3)
	v_max_u32_e32 v26, v26, v30
	s_waitcnt lgkmcnt(2)
	v_max_u32_e32 v27, v27, v31
	s_waitcnt lgkmcnt(1)
	v_max_u32_e32 v28, v28, v32
	s_waitcnt lgkmcnt(0)
	v_max_u32_e32 v29, v29, v33
	v_mov_b32_e32 v30, v26
	v_mov_b32_e32 v31, v27
	v_mov_b32_e32 v32, v28
	v_mov_b32_e32 v33, v29
	v_permlane32_swap_b32_e32 v26, v30
	v_permlane32_swap_b32_e32 v27, v31
	v_permlane32_swap_b32_e32 v28, v32
	v_permlane32_swap_b32_e32 v29, v33
	v_max_u32_e32 v26, v26, v30
	v_max_u32_e32 v27, v27, v31
	v_max_u32_e32 v28, v28, v32
	v_max_u32_e32 v29, v29, v33
	v_cmp_eq_u32_e64 s[0:1], 12, v184
	v_and_b32_e32 v236, 127, v26
	v_sub_u32_e32 v236, 127, v236
	v_and_b32_e32 v237, 127, v27
	v_sub_u32_e32 v237, 127, v237
	v_and_b32_e32 v238, 127, v28
	v_sub_u32_e32 v238, 127, v238
	v_and_b32_e32 v239, 127, v29
	v_sub_u32_e32 v239, 127, v239
	v_cndmask_b32_e64 v82, v82, v236, s[0:1]
	v_cndmask_b32_e64 v83, v83, v237, s[0:1]
	v_cndmask_b32_e64 v84, v84, v238, s[0:1]
	v_cndmask_b32_e64 v85, v85, v239, s[0:1]
	s_add_i32 s19, s18, -1
	v_mov_b32_e32 v236, s19
	v_mov_b32_e32 v237, s18
	v_cmp_eq_u32_e64 s[14:15], 14, v184
	v_cmp_eq_u32_e64 s[34:35], 15, v184
	s_nop 0
	v_cndmask_b32_e64 v82, v82, v236, s[14:15]
	v_cndmask_b32_e64 v82, v82, v237, s[34:35]
	v_cndmask_b32_e64 v83, v83, v236, s[14:15]
	v_cndmask_b32_e64 v83, v83, v237, s[34:35]
	v_cndmask_b32_e64 v84, v84, v236, s[14:15]
	v_cndmask_b32_e64 v84, v84, v237, s[34:35]
	v_cndmask_b32_e64 v85, v85, v236, s[14:15]
	v_cndmask_b32_e64 v85, v85, v237, s[34:35]
	s_and_saveexec_b64 s[42:43], s[6:7]
	ds_write_b32 v196, v82 offset:51520
	ds_write_b32 v196, v83 offset:51584
	ds_write_b32 v196, v84 offset:51648
	ds_write_b32 v196, v85 offset:51712
	s_or_b64 exec, exec, s[42:43]
	s_branch .Ltopk_done_q1

; template <int MODE> ...
;     ...
;     if (MODE == 0 && tid < 256) { const int tok = tid >> 2, word = tid & 3; unsigned m = 0u;
;         if (qb < 16) m = word == 0 ? ((2u << qb) - 1u) : 0u;
;         else {
; #pragma unroll
;             for (int n = 0; n < 16; ++n) { const int j = selall[tok * 16 + n]; m |= ((j >> 5) == word) ? (1u << (j & 31)) : 0u; } }
;         masks[tid] = m; }
.Ltopk_done_q1:
	s_nop 0
	s_waitcnt lgkmcnt(0)
	s_waitcnt vmcnt(0) lgkmcnt(0)
	s_barrier
	v_cmp_gt_u32_e32 vcc, 0x100, v183
	s_nop 0
	s_and_saveexec_b64 s[20:21], vcc
	s_cbranch_execz .Lnsa_mskip_3
	v_and_b32_e32 v90, 3, v183
	s_cmp_lt_i32 s18, 16
	s_cbranch_scc1 .Lnsa_msmall_1
	v_lshlrev_b32_e32 v91, 4, v183
	v_and_b32_e32 v91, 0xffffffc0, v91
	ds_read_b128 v[50:53], v91 offset:51264
	ds_read_b128 v[54:57], v91 offset:51280
	ds_read_b128 v[58:61], v91 offset:51296
	ds_read_b128 v[62:65], v91 offset:51312
	v_mov_b32_e32 v89, 0
	s_waitcnt lgkmcnt(3)
	v_ashrrev_i32_e32 v82, 5, v50
	v_lshlrev_b32_e64 v83, v50, 1
	v_cmp_eq_u32_e32 vcc, v82, v90
	s_nop 1
	v_cndmask_b32_e32 v83, 0, v83, vcc
	v_or_b32_e32 v89, v89, v83
	v_ashrrev_i32_e32 v82, 5, v51
	v_lshlrev_b32_e64 v83, v51, 1
	v_cmp_eq_u32_e32 vcc, v82, v90
	s_nop 1
	v_cndmask_b32_e32 v83, 0, v83, vcc
	v_or_b32_e32 v89, v89, v83
	v_ashrrev_i32_e32 v82, 5, v52
	v_lshlrev_b32_e64 v83, v52, 1
	v_cmp_eq_u32_e32 vcc, v82, v90
	s_nop 1
	v_cndmask_b32_e32 v83, 0, v83, vcc
	v_or_b32_e32 v89, v89, v83
	v_ashrrev_i32_e32 v82, 5, v53
	v_lshlrev_b32_e64 v83, v53, 1
	v_cmp_eq_u32_e32 vcc, v82, v90
	s_nop 1
	v_cndmask_b32_e32 v83, 0, v83, vcc
	v_or_b32_e32 v89, v89, v83
	s_waitcnt lgkmcnt(2)
	v_ashrrev_i32_e32 v82, 5, v54
	v_lshlrev_b32_e64 v83, v54, 1
	v_cmp_eq_u32_e32 vcc, v82, v90
	s_nop 1
	v_cndmask_b32_e32 v83, 0, v83, vcc
	v_or_b32_e32 v89, v89, v83
	v_ashrrev_i32_e32 v82, 5, v55
	v_lshlrev_b32_e64 v83, v55, 1
	v_cmp_eq_u32_e32 vcc, v82, v90
	s_nop 1
	v_cndmask_b32_e32 v83, 0, v83, vcc
	v_or_b32_e32 v89, v89, v83
	v_ashrrev_i32_e32 v82, 5, v56
	v_lshlrev_b32_e64 v83, v56, 1
	v_cmp_eq_u32_e32 vcc, v82, v90
	s_nop 1
	v_cndmask_b32_e32 v83, 0, v83, vcc
	v_or_b32_e32 v89, v89, v83
	v_ashrrev_i32_e32 v82, 5, v57
	v_lshlrev_b32_e64 v83, v57, 1
	v_cmp_eq_u32_e32 vcc, v82, v90
	s_nop 1
	v_cndmask_b32_e32 v83, 0, v83, vcc
	v_or_b32_e32 v89, v89, v83
	s_waitcnt lgkmcnt(1)
	v_ashrrev_i32_e32 v82, 5, v58
	v_lshlrev_b32_e64 v83, v58, 1
	v_cmp_eq_u32_e32 vcc, v82, v90
	s_nop 1
	v_cndmask_b32_e32 v83, 0, v83, vcc
	v_or_b32_e32 v89, v89, v83
	v_ashrrev_i32_e32 v82, 5, v59
	v_lshlrev_b32_e64 v83, v59, 1
	v_cmp_eq_u32_e32 vcc, v82, v90
	s_nop 1
	v_cndmask_b32_e32 v83, 0, v83, vcc
	v_or_b32_e32 v89, v89, v83
	v_ashrrev_i32_e32 v82, 5, v60
	v_lshlrev_b32_e64 v83, v60, 1
	v_cmp_eq_u32_e32 vcc, v82, v90
	s_nop 1
	v_cndmask_b32_e32 v83, 0, v83, vcc
	v_or_b32_e32 v89, v89, v83
	v_ashrrev_i32_e32 v82, 5, v61
	v_lshlrev_b32_e64 v83, v61, 1
	v_cmp_eq_u32_e32 vcc, v82, v90
	s_nop 1
	v_cndmask_b32_e32 v83, 0, v83, vcc
	v_or_b32_e32 v89, v89, v83
	s_waitcnt lgkmcnt(0)
	v_ashrrev_i32_e32 v82, 5, v62
	v_lshlrev_b32_e64 v83, v62, 1
	v_cmp_eq_u32_e32 vcc, v82, v90
	s_nop 1
	v_cndmask_b32_e32 v83, 0, v83, vcc
	v_or_b32_e32 v89, v89, v83
	v_ashrrev_i32_e32 v82, 5, v63
	v_lshlrev_b32_e64 v83, v63, 1
	v_cmp_eq_u32_e32 vcc, v82, v90
	s_nop 1
	v_cndmask_b32_e32 v83, 0, v83, vcc
	v_or_b32_e32 v89, v89, v83
	v_ashrrev_i32_e32 v82, 5, v64
	v_lshlrev_b32_e64 v83, v64, 1
	v_cmp_eq_u32_e32 vcc, v82, v90
	s_nop 1
	v_cndmask_b32_e32 v83, 0, v83, vcc
	v_or_b32_e32 v89, v89, v83
	v_ashrrev_i32_e32 v82, 5, v65
	v_lshlrev_b32_e64 v83, v65, 1
	v_cmp_eq_u32_e32 vcc, v82, v90
	s_nop 1
	v_cndmask_b32_e32 v83, 0, v83, vcc
	v_or_b32_e32 v89, v89, v83
	s_branch .Lnsa_mdone_2
.Lnsa_msmall_1:
	s_nop 1
	s_lshl_b32 s0, 2, s18
	s_add_i32 s0, s0, -1
	v_mov_b32_e32 v89, s0
	v_cmp_eq_u32_e32 vcc, 0, v90
	s_nop 1
	v_cndmask_b32_e32 v89, 0, v89, vcc
.Lnsa_mdone_2:
	s_nop 1
	v_lshlrev_b32_e32 v82, 2, v183
	v_add_u32_e32 v82, 0xd840, v82
	ds_write_b32 v82, v89
	v_lshlrev_b32_e32 v83, 2, v90
	v_add_u32_e32 v84, 0x1fc40, v83
	ds_or_b32 v84, v89
	v_lshrrev_b32_e32 v85, 4, v183
	v_lshl_add_u32 v85, v85, 4, v83
	v_add_u32_e32 v86, 0x1fc50, v85
	ds_or_b32 v86, v89
; #define LAS __attribute__((address_space(3)))
; #define NSA_LD1(jj) do { kr = *(const bf16x8*)((const char*)Kt + (size_t)(jj) * 8192 + kgo); vr = *(const bf16x8*)((const char*)Vt + (jj) * 128 + vgo); } while (0)
; #define NSA_ST1(st_, half_) do { LAS bf16_t* nx_ = stage + (st_) * 18432 + (half_) * 9216 + soff; *(LAS bf16x8*)nx_ = kr; *(LAS bf16x8*)(nx_ + 4608) = vr; } while (0)
; template <int MODE> ...
;     const int r16 = lane & 15, q4 = lane >> 4, b = bg >> 2, g = bg & 3;
;     const bf16_t* Kt = KV + (MODE ? 4 : 2) * (size_t)MTOK * 256 + (size_t)bg * SEQ * 64; const bf16_t* Vt = KV + (MODE ? 5 : 3) * (size_t)MTOK * 256 + (size_t)bg * 64 * SEQ;
;     const LAS float* bt = btab + q4 * 1028;
;     const float bfar = bt[1024];
;     const f32x4 z4 = {0.f, 0.f, 0.f, 0.f};
;     const int j0 = MODE ? (qb - 8 > 0 ? qb - 8 : 0) : 0;
;     if (MODE == 0 && tid < 256) { const int tok = tid >> 2, word = tid & 3; unsigned m = 0u;
;         if (qb < 16) m = word == 0 ? ((2u << qb) - 1u) : 0u;
;         else {
; #pragma unroll
;             for (int n = 0; n < 16; ++n) { const int j = selall[tok * 16 + n]; m |= ((j >> 5) == word) ? (1u << (j & 31)) : 0u; } }
;         masks[tid] = m; }
;     bf16x8 aq[2][2];
; #pragma unroll
;     for (int tile = 0; tile < 2; ++tile) { const int t0 = qb * 64 + wave * 8 + tile * 4;
;         const size_t qoff = (size_t)(b * SEQ + t0 + (r16 & 3)) * 1024 + (g * 4 + (r16 >> 2)) * 64 + q4 * 8;
;         aq[tile][0] = *(const bf16x8*)(Q + qoff); aq[tile][1] = *(const bf16x8*)(Q + qoff + 32); }
;     f32x4 os[2][4]; float ls[2][4];
; #pragma unroll
;     for (int tile = 0; tile < 2; ++tile)
; #pragma unroll
;         for (int i = 0; i < 4; ++i) { os[tile][i] = z4; ls[tile][i] = 0.f; }
;     const int srow = tid >> 3, sch = tid & 7, soff = srow * 72 + sch * 8;
;     const unsigned kgo = (unsigned)(srow * 64 + sch * 8) * 2u, vgo = (unsigned)(srow * SEQ + sch * 8) * 2u;
;     ...
;     bf16x8 kr, vr;
;     NSA_LD1(j0); NSA_ST1(0, 0);
;     if (j0 + 1 <= qb) { NSA_LD1(j0 + 1); NSA_ST1(0, 1); }
;     __syncthreads();
.Lnsa_mskip_3:
	s_nop 0
	s_or_b64 exec, exec, s[20:21]
	v_and_b32_e32 v82, 15, v184
	v_lshrrev_b32_e32 v83, 4, v184
	v_and_b32_e32 v84, 3, v82
	v_lshrrev_b32_e32 v85, 2, v82
	v_and_b32_e32 v86, 1, v85
	v_xor_b32_e32 v87, v83, v84
	v_lshlrev_b32_e32 v87, 4, v87
	v_lshl_add_u32 v87, v86, 6, v87
	v_lshl_add_u32 v88, v85, 3, v84
	v_lshl_add_u32 v98, v88, 7, v87
	v_add_u32_e32 v98, 0xdc40, v98
	v_lshl_add_u32 v99, v82, 7, v87
	v_add_u32_e32 v99, 0xfc40, v99
	v_lshlrev_b32_e32 v88, 7, v86
	v_sub_u32_e32 v0, 64, v88
	v_lshrrev_b32_e32 v88, 3, v184
	v_and_b32_e32 v89, 7, v184
	s_lshr_b32 s0, s80, 3
	s_and_b32 s1, s0, 1
	s_lshl_b32 s1, s1, 2
	s_lshl_b32 s14, s0, 10
	v_and_b32_e32 v90, 3, v88
	v_or_b32_e32 v90, s1, v90
	v_xor_b32_e32 v90, v89, v90
	v_add_u32_e32 v91, s80, v88
	v_lshlrev_b32_e32 v174, 7, v91
	v_lshl_add_u32 v174, v90, 4, v174
	v_xor_b32_e32 v90, v89, v88
	v_lshlrev_b32_e32 v175, 14, v91
	v_lshl_add_u32 v175, v90, 4, v175
	v_add_u32_e32 v88, s80, v84
	v_lshlrev_b32_e32 v89, 3, v83
	v_sub_u32_e32 v176, v88, v89
	v_mul_u32_u24_e32 v92, 0x1010, v85
	v_lshl_add_u32 v177, v176, 2, v92
	v_add_u32_e32 v177, 0xffffff64, v177
	ds_read_b32 v225, v92 offset:4096
	v_mov_b32_e32 v252, 0xf149f2ca
	v_min_u32_e32 v82, 39, v184
	v_lshlrev_b32_e32 v82, 2, v82
	v_add_u32_e32 v82, 0x1fd60, v82
	ds_write_b32 v82, v252
	v_mov_b32_e32 v226, 0x1fd60
	s_mov_b32 s54, 0
	s_waitcnt lgkmcnt(0)
	s_barrier
.Lnsa_mode_top:
	s_nop 1
	s_cmp_lg_u32 s54, 0
	s_cbranch_scc1 .Lnsa_pwin_4
	s_add_u32 s66, s30, 0x33900000
	s_addc_u32 s67, s31, 0
	s_add_u32 s68, s30, 0x34900000
	s_addc_u32 s69, s31, 0
	s_mov_b32 s53, 16
	s_mov_b32 s52, 0x80000000
	v_min_u32_e32 v228, 11, v184
	v_lshlrev_b32_e32 v228, 2, v228
	s_lshl_b32 s0, s80, 2
	s_add_i32 s1, s0, 130112
	v_add_u32_e32 v229, s1, v228
	v_add_u32_e32 v228, 0x1fc40, v228
	v_cmp_gt_u32_e32 vcc, 4, v184
	s_nop 1
	v_cndmask_b32_e32 v228, v229, v228, vcc
	ds_read_b32 v179, v228
	v_and_b32_e32 v178, 3, v184
	v_add_u32_e32 v178, s80, v178
	v_lshlrev_b32_e32 v178, 4, v178
	v_add_u32_e32 v178, 0xd840, v178
	s_waitcnt lgkmcnt(0)
	s_branch .Lnsa_pjoin_5
.Lnsa_pwin_4:
	s_nop 1
	s_add_u32 s66, s30, 0x35900000
	s_addc_u32 s67, s31, 0
	s_add_u32 s68, s30, 0x36900000
	s_addc_u32 s69, s31, 0
	s_mov_b32 s53, 8
	s_mov_b32 s52, 512
	s_add_i32 s0, s18, -8
	s_max_i32 s0, s0, 0
	v_and_b32_e32 v228, 3, v184
	v_lshlrev_b32_e32 v228, 5, v228
	v_sub_u32_e32 v229, s0, v228
	v_max_i32_e32 v229, 0, v229
	v_sub_u32_e32 v230, s18, v228
	v_min_i32_e32 v230, 31, v230
	v_sub_u32_e32 v253, v230, v229
	v_add_u32_e32 v253, 1, v253
	v_max_i32_e32 v230, 0, v253
	v_min_i32_e32 v230, 31, v230
	v_bfm_b32 v179, v230, v229
	v_cmp_lt_i32_e32 vcc, 0, v253
	s_nop 1
	v_cndmask_b32_e32 v179, 0, v179, vcc
	v_cmp_gt_u32_e32 vcc, 32, v229
	s_nop 1
	v_cndmask_b32_e32 v179, 0, v179, vcc
	v_mov_b32_e32 v232, -1
	v_mov_b32_e32 v233, -1
.Lnsa_pjoin_5:
	s_nop 1
	s_mov_b32 s21, -1
	s_lshr_b32 s15, s97, 13
	s_lshl_b32 s15, s15, 2
	s_and_b32 s1, s88, 3
	s_or_b32 s15, s15, s1
	s_lshl_b32 s15, s15, 20
	s_add_u32 s66, s66, s15
	s_addc_u32 s67, s67, 0
	s_add_u32 s68, s68, s15
	s_addc_u32 s69, s69, 0
	v_readlane_b32 s72, v179, 0
	v_readlane_b32 s73, v179, 1
	v_readlane_b32 s74, v179, 2
	v_readlane_b32 s75, v179, 3
	s_mov_b32 s92, 0
	s_mov_b32 s57, 0
	v_mov_b32_e32 v2, 0
	v_mov_b32_e32 v3, 0
	v_mov_b32_e32 v4, 0
	v_mov_b32_e32 v5, 0
	v_mov_b32_e32 v6, 0
	v_mov_b32_e32 v7, 0
	v_mov_b32_e32 v8, 0
	v_mov_b32_e32 v9, 0
	v_mov_b32_e32 v10, 0
	v_mov_b32_e32 v11, 0
	v_mov_b32_e32 v12, 0
	v_mov_b32_e32 v13, 0
	v_mov_b32_e32 v14, 0
	v_mov_b32_e32 v15, 0
	v_mov_b32_e32 v16, 0
	v_mov_b32_e32 v17, 0
	v_mov_b32_e32 v215, 0
	v_mov_b32_e32 v18, 0
	v_mov_b32_e32 v19, 0
	v_mov_b32_e32 v20, 0
	v_mov_b32_e32 v21, 0
	v_mov_b32_e32 v22, 0
	v_mov_b32_e32 v23, 0
	v_mov_b32_e32 v24, 0
	v_mov_b32_e32 v25, 0
	v_mov_b32_e32 v26, 0
	v_mov_b32_e32 v27, 0
	v_mov_b32_e32 v28, 0
	v_mov_b32_e32 v29, 0
	v_mov_b32_e32 v30, 0
	v_mov_b32_e32 v31, 0
	v_mov_b32_e32 v32, 0
	v_mov_b32_e32 v33, 0
	v_mov_b32_e32 v224, 0

; #define NSA_LD1(jj) do { kr = *(const bf16x8*)((const char*)Kt + (size_t)(jj) * 8192 + kgo); vr = *(const bf16x8*)((const char*)Vt + (jj) * 128 + vgo); } while (0)
; #define NSA_ST1(st_, half_) do { LAS bf16_t* nx_ = stage + (st_) * 18432 + (half_) * 9216 + soff; *(LAS bf16x8*)nx_ = kr; *(LAS bf16x8*)(nx_ + 4608) = vr; } while (0)
; template <int MODE> ...
;     ...
;     bf16x8 kr, vr;
;     NSA_LD1(j0); NSA_ST1(0, 0);
;     if (j0 + 1 <= qb) { NSA_LD1(j0 + 1); NSA_ST1(0, 1); }
;     __syncthreads();
;     for (int jA = j0, pp = 0; jA <= qb; jA += 2, pp ^= 1) {
;       for (int sub = 0; sub < 2; ++sub) {
;         const int j = jA + sub; if (j > qb) break;
;         const bool pre = j + 2 <= qb;
;         if (pre) NSA_LD1(j + 2);
.Lnsa_nxo_11:
.Lnsa_nx_12:
	s_cmp_lg_u32 s72, 0
	s_cbranch_scc1 .Lnsa_nxh_13
	s_mov_b32 s72, s73
	s_mov_b32 s73, s74
	s_mov_b32 s74, s75
	s_mov_b32 s75, 0
	s_add_i32 s92, s92, 32
	s_mov_b32 s95, -1
	s_cmp_lt_u32 s92, 128
	s_cbranch_scc1 .Lnsa_nx_12
	s_branch .Lnsa_nxo_14

; #define LAS __attribute__((address_space(3)))
; #define MFMA16(a, b, c) __builtin_amdgcn_mfma_f32_16x16x32_bf16(a, b, c, 0, 0, 0)
; #define NSA_LD1(jj) do { kr = *(const bf16x8*)((const char*)Kt + (size_t)(jj) * 8192 + kgo); vr = *(const bf16x8*)((const char*)Vt + (jj) * 128 + vgo); } while (0)
; #define NSA_ST1(st_, half_) do { LAS bf16_t* nx_ = stage + (st_) * 18432 + (half_) * 9216 + soff; *(LAS bf16x8*)nx_ = kr; *(LAS bf16x8*)(nx_ + 4608) = vr; } while (0)
; template <int MODE> ...
;     ...
;     NSA_LD1(j0); NSA_ST1(0, 0);
;     if (j0 + 1 <= qb) { NSA_LD1(j0 + 1); NSA_ST1(0, 1); }
;     __syncthreads();
;     for (int jA = j0, pp = 0; jA <= qb; jA += 2, pp ^= 1) {
;       for (int sub = 0; sub < 2; ++sub) {
;         const int j = jA + sub; if (j > qb) break;
;         const bool pre = j + 2 <= qb;
;         if (pre) NSA_LD1(j + 2);
;         const LAS bf16_t* Ks = stage + pp * 18432 + sub * 9216; const LAS bf16_t* Vs = Ks + 4608;
;         const bool far = MODE == 0 && (qb - j >= 17);
; #pragma unroll
;         for (int tile = 0; tile < 2; ++tile) {
;             const int tl0 = wave * 8 + tile * 4, t0 = qb * 64 + tl0;
;             unsigned mb[4] = {1u, 1u, 1u, 1u};
;             if (MODE == 0) {
; #pragma unroll
;                 for (int i = 0; i < 4; ++i) mb[i] = (masks[(tl0 + i) * 4 + (j >> 5)] >> (j & 31)) & 1u; }
;             if (MODE == 1 || __builtin_amdgcn_readfirstlane((int)(mb[0] | mb[1] | mb[2] | mb[3]))) {
;                 f32x4 sc[4];
; #pragma unroll
;                 for (int cc = 0; cc < 4; ++cc) { const LAS bf16_t* kp = Ks + (cc * 16 + r16) * 72 + q4 * 8;
;                     sc[cc] = MFMA16(aq[tile][0], *(const LAS bf16x8*)kp, z4); sc[cc] = MFMA16(aq[tile][1], *(const LAS bf16x8*)(kp + 32), sc[cc]); }
.Lnsa_nxo_14:
	s_and_b32 s0, s57, 3
	s_lshl_b32 s0, s0, 14
	s_lshl_b32 s1, s80, 7
	s_add_i32 s0, s0, s1
	s_lshl_b32 s1, s93, 13
	s_add_u32 s70, s66, s1
	s_addc_u32 s71, s67, 0
	s_lshl_b32 s1, s93, 7
	s_add_u32 s14, s68, s1
	s_addc_u32 s15, s69, 0
	s_add_i32 s1, s0, 0xfc40
	s_add_i32 m0, s0, 0xdc40
	s_nop 0
	global_load_lds_dwordx4 v174, s[70:71]
	s_mov_b32 m0, s1
	s_nop 0
	global_load_lds_dwordx4 v175, s[14:15]
	s_mov_b32 s19, -1
	s_cmp_lt_i32 s94, 0
	s_cbranch_scc1 .Lnsa_proA_15
	s_add_i32 s14, s57, 1
	s_and_b32 s0, s14, 3
	s_lshl_b32 s0, s0, 14
	s_lshl_b32 s1, s80, 7
	s_add_i32 s0, s0, s1
	s_lshl_b32 s1, s94, 13
	s_add_u32 s70, s66, s1
	s_addc_u32 s71, s67, 0
	s_lshl_b32 s1, s94, 7
	s_add_u32 s14, s68, s1
	s_addc_u32 s15, s69, 0
	s_add_i32 s1, s0, 0xfc40
	s_add_i32 m0, s0, 0xdc40
	s_nop 0
	global_load_lds_dwordx4 v174, s[70:71]
	s_mov_b32 m0, s1
	s_nop 0
	global_load_lds_dwordx4 v175, s[14:15]
	s_cmp_lt_i32 s95, 0
	s_cbranch_scc1 .Lnsa_proB_16
	s_add_i32 s14, s57, 2
	s_and_b32 s0, s14, 3
	s_lshl_b32 s0, s0, 14
	s_lshl_b32 s1, s80, 7
	s_add_i32 s0, s0, s1
	s_lshl_b32 s1, s95, 13
	s_add_u32 s70, s66, s1
	s_addc_u32 s71, s67, 0
	s_lshl_b32 s1, s95, 7
	s_add_u32 s14, s68, s1
	s_addc_u32 s15, s69, 0
	s_add_i32 s1, s0, 0xfc40
	s_add_i32 m0, s0, 0xdc40
	s_nop 0
	global_load_lds_dwordx4 v174, s[70:71]
	s_mov_b32 m0, s1
	s_nop 0
	global_load_lds_dwordx4 v175, s[14:15]
.Lnsa_nx_18:
	s_cmp_lg_u32 s72, 0
	s_cbranch_scc1 .Lnsa_nxh_19
	s_mov_b32 s72, s73
	s_mov_b32 s73, s74
	s_mov_b32 s74, s75
	s_mov_b32 s75, 0
	s_add_i32 s92, s92, 32
	s_mov_b32 s19, -1
	s_cmp_lt_u32 s92, 128
	s_cbranch_scc1 .Lnsa_nx_18
	s_branch .Lnsa_nxo_20
.Lnsa_nxh_19:
	s_ff1_i32_b32 s0, s72
	s_bitset0_b32 s72, s0
	s_add_i32 s19, s92, s0
.Lnsa_nxo_20:
	s_waitcnt vmcnt(4)
	s_branch .Lnsa_proC_17
.Lnsa_proB_16:
	s_waitcnt vmcnt(2)
	s_branch .Lnsa_proC_17
.Lnsa_proA_15:
	s_waitcnt vmcnt(0)
.Lnsa_proC_17:
	s_barrier
.Lnsa_blk_loop:
	s_nop 1
	s_cmp_lt_i32 s19, 0
	s_cbranch_scc1 .Lnsa_nodma_21
	s_add_i32 s14, s57, 3
	s_and_b32 s0, s14, 3
	s_lshl_b32 s0, s0, 14
	s_lshl_b32 s1, s80, 7
	s_add_i32 s0, s0, s1
	s_lshl_b32 s1, s19, 13
	s_add_u32 s70, s66, s1
	s_addc_u32 s71, s67, 0
	s_lshl_b32 s1, s19, 7
	s_add_u32 s14, s68, s1
	s_addc_u32 s15, s69, 0
	s_add_i32 s1, s0, 0xfc40
	s_add_i32 m0, s0, 0xdc40
	s_nop 0
	global_load_lds_dwordx4 v174, s[70:71]
	s_mov_b32 m0, s1
	s_nop 0
	global_load_lds_dwordx4 v175, s[14:15]
.Lnsa_nodma_21:
	s_nop 1
	s_sub_i32 s47, s18, s93
	s_lshr_b32 s46, s93, 5
	s_and_b32 s43, s93, 31
	s_and_b32 s35, s57, 3
	s_lshl_b32 s35, s35, 14
	s_mov_b32 s42, 0
	s_cmp_eq_u32 s47, 0
	s_cselect_b32 s42, 1, s42
	s_cmp_eq_u32 s47, s53
	s_cselect_b32 s42, 1, s42
	s_cmp_gt_i32 s47, 16
	s_cselect_b32 s42, 2, s42
	v_add_u32_e32 v170, s35, v98
	v_add_u32_e32 v171, v170, v0
	v_add_u32_e32 v172, s35, v99
	v_add_u32_e32 v173, v172, v0
	s_lshl_b32 s0, s47, 6
	v_add_u32_e32 v229, s0, v176
	s_lshl_b32 s0, s47, 8
	v_add_u32_e32 v231, s0, v177
	s_cmp_eq_u32 s46, s21
	s_cbranch_scc1 .Lnsa_mwok_22
	s_mov_b32 s21, s46
	s_cmp_lg_u32 s54, 0
	s_cbranch_scc1 .Lnsa_mwok_22
	s_lshl_b32 s15, s46, 2
	v_add_u32_e32 v228, s15, v178
	ds_read_b32 v232, v228
	ds_read_b32 v233, v228 offset:64
	s_waitcnt lgkmcnt(0)
.Lnsa_mwok_22:
	s_nop 1
	v_bfe_i32 v234, v232, s43, 1
	v_bfe_i32 v235, v233, s43, 1
	s_mov_b32 s34, 0
	s_add_i32 s0, s46, 4
	v_readlane_b32 s1, v179, s0
	s_nop 0
	s_lshr_b32 s1, s1, s43
	s_and_b32 s1, s1, 1
	s_lshl_b32 s1, s1, 0
	s_or_b32 s34, s34, s1
	s_add_i32 s0, s46, 8
	v_readlane_b32 s1, v179, s0
	s_nop 0
	s_lshr_b32 s1, s1, s43
	s_and_b32 s1, s1, 1
	s_lshl_b32 s1, s1, 1
	s_or_b32 s34, s34, s1
	s_and_b32 s0, s34, 3
	s_cmp_eq_u32 s0, 3
	s_cbranch_scc0 .Lnsa_nopair_23
	s_cmp_eq_u32 s42, 1
	s_cbranch_scc1 .Lnsa_nopair_23
	s_cmp_eq_u32 s42, 2
	s_cbranch_scc1 .Lnsa_pfar_26
	v_add_u32_e32 v230, 16, v231
	v_bfi_b32 v228, v234, v231, v226
	v_bfi_b32 v230, v235, v230, v226
	ds_read2_b32 v[66:67], v228 offset0:39 offset1:38
	ds_read2_b32 v[68:69], v228 offset0:37 offset1:36
	ds_read2_b32 v[70:71], v228 offset0:35 offset1:34
	ds_read2_b32 v[72:73], v228 offset0:33 offset1:32
	ds_read_b128 v[50:53], v170 offset:0
	ds_read_b128 v[54:57], v171 offset:0
	ds_read2_b32 v[236:237], v230 offset0:39 offset1:38
	ds_read2_b32 v[238:239], v230 offset0:37 offset1:36
	ds_read2_b32 v[240:241], v230 offset0:35 offset1:34
	ds_read2_b32 v[242:243], v230 offset0:33 offset1:32
	ds_read_b128 v[58:61], v170 offset:512
	ds_read_b128 v[62:65], v171 offset:512
	s_waitcnt lgkmcnt(10)
	s_waitcnt lgkmcnt(6)
	v_mfma_f32_16x16x32_bf16 v[66:69], v[50:53], v[34:37], v[66:69]
	v_mfma_f32_16x16x32_bf16 v[66:69], v[54:57], v[38:41], v[66:69]
	ds_read2_b32 v[74:75], v228 offset0:7 offset1:6
	ds_read2_b32 v[76:77], v228 offset0:5 offset1:4
	ds_read2_b32 v[78:79], v228 offset0:3 offset1:2
	ds_read2_b32 v[80:81], v228 offset0:1 offset1:0
	s_waitcnt lgkmcnt(8)
	v_mfma_f32_16x16x32_bf16 v[236:239], v[50:53], v[42:45], v[236:239]
	v_mfma_f32_16x16x32_bf16 v[236:239], v[54:57], v[46:49], v[236:239]
	ds_read_b128 v[50:53], v170 offset:4096
	ds_read_b128 v[54:57], v171 offset:4096
	s_waitcnt lgkmcnt(6)
	v_mfma_f32_16x16x32_bf16 v[70:73], v[58:61], v[34:37], v[70:73]
	v_mfma_f32_16x16x32_bf16 v[70:73], v[62:65], v[38:41], v[70:73]
	ds_read2_b32 v[244:245], v230 offset0:7 offset1:6
	ds_read2_b32 v[246:247], v230 offset0:5 offset1:4
	ds_read2_b32 v[248:249], v230 offset0:3 offset1:2
	ds_read2_b32 v[250:251], v230 offset0:1 offset1:0
	v_mfma_f32_16x16x32_bf16 v[240:243], v[58:61], v[42:45], v[240:243]
	v_mfma_f32_16x16x32_bf16 v[240:243], v[62:65], v[46:49], v[240:243]
	ds_read_b128 v[58:61], v170 offset:4608
	ds_read_b128 v[62:65], v171 offset:4608
	s_waitcnt lgkmcnt(10)
	s_waitcnt lgkmcnt(6)
	v_mfma_f32_16x16x32_bf16 v[74:77], v[50:53], v[34:37], v[74:77]
	v_mfma_f32_16x16x32_bf16 v[74:77], v[54:57], v[38:41], v[74:77]
	s_waitcnt lgkmcnt(4)
	v_mfma_f32_16x16x32_bf16 v[244:247], v[50:53], v[42:45], v[244:247]
	v_mfma_f32_16x16x32_bf16 v[244:247], v[54:57], v[46:49], v[244:247]
	s_waitcnt lgkmcnt(0)
	v_mfma_f32_16x16x32_bf16 v[78:81], v[58:61], v[34:37], v[78:81]
	v_mfma_f32_16x16x32_bf16 v[78:81], v[62:65], v[38:41], v[78:81]
	v_mfma_f32_16x16x32_bf16 v[248:251], v[58:61], v[42:45], v[248:251]
	v_mfma_f32_16x16x32_bf16 v[248:251], v[62:65], v[46:49], v[248:251]
	s_branch .Lnsa_psm_27
; #define LAS __attribute__((address_space(3)))
; #define CBAR() asm volatile("" ::: "memory")
; #define MFMA16(a, b, c) __builtin_amdgcn_mfma_f32_16x16x32_bf16(a, b, c, 0, 0, 0)
; __device__ __forceinline__ bf16_t tobf(float x) { return (bf16_t)pk2(x, 0.f); }
; __device__ __forceinline__ float ex2(float x) { return __builtin_amdgcn_exp2f(x); }
; template <int MODE> ...
;     ...
;                 if (far) {
; #pragma unroll
;                     for (int cc = 0; cc < 4; ++cc)
; #pragma unroll
;                         for (int i = 0; i < 4; ++i) { const float p = mb[i] ? ex2(sc[cc][i] + bfar) : 0.f; ls[tile][i] += p; Pb[(4 * q4 + i) * 72 + cc * 16 + r16] = tobf(p); }
;                 } else {
; #pragma unroll
;                     for (int cc = 0; cc < 4; ++cc) { const int pos = j * 64 + cc * 16 + r16;
; #pragma unroll
;                         for (int i = 0; i < 4; ++i) { const int dist = t0 + i - pos; const bool ok = MODE ? ((unsigned)dist < 512u) : (dist >= 0 && mb[i]);
;                             const float p = ok ? ex2(sc[cc][i] + bt[clampd(dist)]) : 0.f; ls[tile][i] += p; Pb[(4 * q4 + i) * 72 + cc * 16 + r16] = tobf(p); } }
;                 }
;                 CBAR();
; #pragma unroll
;                 for (int ks = 0; ks < 2; ++ks) { const bf16x8 aP = *(const LAS bf16x8*)(Pb + r16 * 72 + ks * 32 + q4 * 8);
; #pragma unroll
;                     for (int nt = 0; nt < 4; ++nt) os[tile][nt] = MFMA16(aP, *(const LAS bf16x8*)(Vs + (nt * 16 + r16) * 72 + ks * 32 + q4 * 8), os[tile][nt]); }
.Lnsa_pfar_26:
	s_nop 1
	ds_read_b128 v[50:53], v170 offset:0
	ds_read_b128 v[54:57], v171 offset:0
	ds_read_b128 v[58:61], v170 offset:512
	ds_read_b128 v[62:65], v171 offset:512
	v_bfi_b32 v216, v234, v225, v252
	v_bfi_b32 v220, v235, v225, v252
	v_mov_b32_e32 v217, v216
	v_mov_b32_e32 v218, v216
	v_mov_b32_e32 v219, v216
	v_mov_b32_e32 v221, v220
	v_mov_b32_e32 v222, v220
	v_mov_b32_e32 v223, v220
	s_waitcnt lgkmcnt(2)
	v_mfma_f32_16x16x32_bf16 v[66:69], v[50:53], v[34:37], v[216:219]
	v_mfma_f32_16x16x32_bf16 v[236:239], v[50:53], v[42:45], v[220:223]
	v_mfma_f32_16x16x32_bf16 v[66:69], v[54:57], v[38:41], v[66:69]
	v_mfma_f32_16x16x32_bf16 v[236:239], v[54:57], v[46:49], v[236:239]
	ds_read_b128 v[50:53], v170 offset:4096
	ds_read_b128 v[54:57], v171 offset:4096
	s_waitcnt lgkmcnt(2)
	v_mfma_f32_16x16x32_bf16 v[70:73], v[58:61], v[34:37], v[216:219]
	v_mfma_f32_16x16x32_bf16 v[240:243], v[58:61], v[42:45], v[220:223]
	v_mfma_f32_16x16x32_bf16 v[70:73], v[62:65], v[38:41], v[70:73]
	v_mfma_f32_16x16x32_bf16 v[240:243], v[62:65], v[46:49], v[240:243]
	ds_read_b128 v[58:61], v170 offset:4608
	ds_read_b128 v[62:65], v171 offset:4608
	s_waitcnt lgkmcnt(2)
	v_mfma_f32_16x16x32_bf16 v[74:77], v[50:53], v[34:37], v[216:219]
	v_mfma_f32_16x16x32_bf16 v[244:247], v[50:53], v[42:45], v[220:223]
	v_mfma_f32_16x16x32_bf16 v[74:77], v[54:57], v[38:41], v[74:77]
	v_mfma_f32_16x16x32_bf16 v[244:247], v[54:57], v[46:49], v[244:247]
	s_waitcnt lgkmcnt(0)
	v_mfma_f32_16x16x32_bf16 v[78:81], v[58:61], v[34:37], v[216:219]
	v_mfma_f32_16x16x32_bf16 v[248:251], v[58:61], v[42:45], v[220:223]
	v_mfma_f32_16x16x32_bf16 v[78:81], v[62:65], v[38:41], v[78:81]
	v_mfma_f32_16x16x32_bf16 v[248:251], v[62:65], v[46:49], v[248:251]
.Lnsa_psm_27:
	s_nop 1
	s_waitcnt lgkmcnt(0)
	ds_read_b128 v[50:53], v172 offset:0
	ds_read_b128 v[54:57], v173 offset:0
	ds_read_b128 v[58:61], v172 offset:2048
	ds_read_b128 v[62:65], v173 offset:2048
	v_exp_f32_e32 v66, v66
	v_exp_f32_e32 v67, v67
	v_exp_f32_e32 v68, v68
	v_exp_f32_e32 v69, v69
	v_exp_f32_e32 v70, v70
	v_exp_f32_e32 v71, v71
	v_exp_f32_e32 v72, v72
	v_exp_f32_e32 v73, v73
	v_exp_f32_e32 v74, v74
	v_exp_f32_e32 v75, v75
	v_exp_f32_e32 v76, v76
	v_exp_f32_e32 v77, v77
	v_exp_f32_e32 v78, v78
	v_exp_f32_e32 v79, v79
	v_exp_f32_e32 v80, v80
	v_exp_f32_e32 v81, v81
	v_exp_f32_e32 v236, v236
	v_exp_f32_e32 v237, v237
	v_exp_f32_e32 v238, v238
	v_exp_f32_e32 v239, v239
	v_exp_f32_e32 v240, v240
	v_exp_f32_e32 v241, v241
	v_exp_f32_e32 v242, v242
	v_exp_f32_e32 v243, v243
	v_exp_f32_e32 v244, v244
	v_exp_f32_e32 v245, v245
	v_exp_f32_e32 v246, v246
	v_exp_f32_e32 v247, v247
	v_exp_f32_e32 v248, v248
	v_exp_f32_e32 v249, v249
	v_exp_f32_e32 v250, v250
	v_exp_f32_e32 v251, v251
	v_add_f32_e32 v215, v215, v66
	v_add_f32_e32 v215, v215, v67
	v_add_f32_e32 v215, v215, v68
	v_add_f32_e32 v215, v215, v69
	v_add_f32_e32 v215, v215, v70
	v_add_f32_e32 v215, v215, v71
	v_add_f32_e32 v215, v215, v72
	v_add_f32_e32 v215, v215, v73
	v_add_f32_e32 v215, v215, v74
	v_add_f32_e32 v215, v215, v75
	v_add_f32_e32 v215, v215, v76
	v_add_f32_e32 v215, v215, v77
	v_add_f32_e32 v215, v215, v78
	v_add_f32_e32 v215, v215, v79
	v_add_f32_e32 v215, v215, v80
	v_add_f32_e32 v215, v215, v81
	v_cvt_pk_bf16_f32 v82, v66, v67
	v_cvt_pk_bf16_f32 v83, v68, v69
	v_cvt_pk_bf16_f32 v84, v70, v71
	v_cvt_pk_bf16_f32 v85, v72, v73
	v_cvt_pk_bf16_f32 v86, v74, v75
	v_cvt_pk_bf16_f32 v87, v76, v77
	v_cvt_pk_bf16_f32 v88, v78, v79
	v_cvt_pk_bf16_f32 v89, v80, v81
	v_add_f32_e32 v224, v224, v236
	v_add_f32_e32 v224, v224, v237
	v_add_f32_e32 v224, v224, v238
	v_add_f32_e32 v224, v224, v239
	v_add_f32_e32 v224, v224, v240
	v_add_f32_e32 v224, v224, v241
	v_add_f32_e32 v224, v224, v242
	v_add_f32_e32 v224, v224, v243
	v_add_f32_e32 v224, v224, v244
	v_add_f32_e32 v224, v224, v245
	v_add_f32_e32 v224, v224, v246
	v_add_f32_e32 v224, v224, v247
	v_add_f32_e32 v224, v224, v248
	v_add_f32_e32 v224, v224, v249
	v_add_f32_e32 v224, v224, v250
	v_add_f32_e32 v224, v224, v251
	v_cvt_pk_bf16_f32 v90, v236, v237
	v_cvt_pk_bf16_f32 v91, v238, v239
	v_cvt_pk_bf16_f32 v92, v240, v241
	v_cvt_pk_bf16_f32 v93, v242, v243
	v_cvt_pk_bf16_f32 v94, v244, v245
	v_cvt_pk_bf16_f32 v95, v246, v247
	v_cvt_pk_bf16_f32 v96, v248, v249
	v_cvt_pk_bf16_f32 v97, v250, v251
	s_waitcnt lgkmcnt(2)
	v_mfma_f32_16x16x32_bf16 v[2:5], v[50:53], v[82:85], v[2:5]
	v_mfma_f32_16x16x32_bf16 v[18:21], v[50:53], v[90:93], v[18:21]
	v_mfma_f32_16x16x32_bf16 v[2:5], v[54:57], v[86:89], v[2:5]
	v_mfma_f32_16x16x32_bf16 v[18:21], v[54:57], v[94:97], v[18:21]
	ds_read_b128 v[50:53], v172 offset:4096
	ds_read_b128 v[54:57], v173 offset:4096
	s_waitcnt lgkmcnt(2)
	v_mfma_f32_16x16x32_bf16 v[6:9], v[58:61], v[82:85], v[6:9]
	v_mfma_f32_16x16x32_bf16 v[22:25], v[58:61], v[90:93], v[22:25]
	v_mfma_f32_16x16x32_bf16 v[6:9], v[62:65], v[86:89], v[6:9]
	v_mfma_f32_16x16x32_bf16 v[22:25], v[62:65], v[94:97], v[22:25]
	ds_read_b128 v[58:61], v172 offset:6144
	ds_read_b128 v[62:65], v173 offset:6144
	s_waitcnt lgkmcnt(2)
	v_mfma_f32_16x16x32_bf16 v[10:13], v[50:53], v[82:85], v[10:13]
	v_mfma_f32_16x16x32_bf16 v[26:29], v[50:53], v[90:93], v[26:29]
	v_mfma_f32_16x16x32_bf16 v[10:13], v[54:57], v[86:89], v[10:13]
	v_mfma_f32_16x16x32_bf16 v[26:29], v[54:57], v[94:97], v[26:29]
	s_waitcnt lgkmcnt(0)
	v_mfma_f32_16x16x32_bf16 v[14:17], v[58:61], v[82:85], v[14:17]
	v_mfma_f32_16x16x32_bf16 v[30:33], v[58:61], v[90:93], v[30:33]
	v_mfma_f32_16x16x32_bf16 v[14:17], v[62:65], v[86:89], v[14:17]
	v_mfma_f32_16x16x32_bf16 v[30:33], v[62:65], v[94:97], v[30:33]
	s_branch .Lnsa_blkend_25
; #define LAS __attribute__((address_space(3)))
; #define MFMA16(a, b, c) __builtin_amdgcn_mfma_f32_16x16x32_bf16(a, b, c, 0, 0, 0)
; __device__ __forceinline__ bf16_t tobf(float x) { return (bf16_t)pk2(x, 0.f); }
; __device__ __forceinline__ float ex2(float x) { return __builtin_amdgcn_exp2f(x); }
; template <int MODE> ...
;     ...
;         for (int tile = 0; tile < 2; ++tile) {
;             const int tl0 = wave * 8 + tile * 4, t0 = qb * 64 + tl0;
;             unsigned mb[4] = {1u, 1u, 1u, 1u};
;             if (MODE == 0) {
; #pragma unroll
;                 for (int i = 0; i < 4; ++i) mb[i] = (masks[(tl0 + i) * 4 + (j >> 5)] >> (j & 31)) & 1u; }
;             if (MODE == 1 || __builtin_amdgcn_readfirstlane((int)(mb[0] | mb[1] | mb[2] | mb[3]))) {
;                 f32x4 sc[4];
; #pragma unroll
;                 for (int cc = 0; cc < 4; ++cc) { const LAS bf16_t* kp = Ks + (cc * 16 + r16) * 72 + q4 * 8;
;                     sc[cc] = MFMA16(aq[tile][0], *(const LAS bf16x8*)kp, z4); sc[cc] = MFMA16(aq[tile][1], *(const LAS bf16x8*)(kp + 32), sc[cc]); }
;                 if (far) {
; #pragma unroll
;                     for (int cc = 0; cc < 4; ++cc)
; #pragma unroll
;                         for (int i = 0; i < 4; ++i) { const float p = mb[i] ? ex2(sc[cc][i] + bfar) : 0.f; ls[tile][i] += p; Pb[(4 * q4 + i) * 72 + cc * 16 + r16] = tobf(p); }
;                 } else {
; #pragma unroll
;                     for (int cc = 0; cc < 4; ++cc) { const int pos = j * 64 + cc * 16 + r16;
; #pragma unroll
;                         for (int i = 0; i < 4; ++i) { const int dist = t0 + i - pos; const bool ok = MODE ? ((unsigned)dist < 512u) : (dist >= 0 && mb[i]);
;                             const float p = ok ? ex2(sc[cc][i] + bt[clampd(dist)]) : 0.f; ls[tile][i] += p; Pb[(4 * q4 + i) * 72 + cc * 16 + r16] = tobf(p); } }
.Lnsa_nopair_23:
	s_nop 1
	s_bitcmp1_b32 s34, 0
	s_cbranch_scc0 .Lnsa_single1_24
	s_cmp_eq_u32 s42, 1
	s_cbranch_scc1 .Lnsa_gen_28
	s_cmp_eq_u32 s42, 2
	s_cbranch_scc1 .Lnsa_far_29
	v_bfi_b32 v230, v234, v231, v226
	ds_read2_b32 v[66:67], v230 offset0:39 offset1:38
	ds_read2_b32 v[68:69], v230 offset0:37 offset1:36
	ds_read2_b32 v[70:71], v230 offset0:35 offset1:34
	ds_read2_b32 v[72:73], v230 offset0:33 offset1:32
	ds_read2_b32 v[74:75], v230 offset0:7 offset1:6
	ds_read2_b32 v[76:77], v230 offset0:5 offset1:4
	ds_read2_b32 v[78:79], v230 offset0:3 offset1:2
	ds_read2_b32 v[80:81], v230 offset0:1 offset1:0
	ds_read_b128 v[50:53], v170 offset:0
	ds_read_b128 v[54:57], v171 offset:0
	ds_read_b128 v[58:61], v170 offset:512
	ds_read_b128 v[62:65], v171 offset:512
	s_waitcnt lgkmcnt(2)
	v_mfma_f32_16x16x32_bf16 v[66:69], v[50:53], v[34:37], v[66:69]
	v_mfma_f32_16x16x32_bf16 v[66:69], v[54:57], v[38:41], v[66:69]
	ds_read_b128 v[50:53], v170 offset:4096
	ds_read_b128 v[54:57], v171 offset:4096
	s_waitcnt lgkmcnt(2)
	v_mfma_f32_16x16x32_bf16 v[70:73], v[58:61], v[34:37], v[70:73]
	v_mfma_f32_16x16x32_bf16 v[70:73], v[62:65], v[38:41], v[70:73]
	ds_read_b128 v[58:61], v170 offset:4608
	ds_read_b128 v[62:65], v171 offset:4608
	s_waitcnt lgkmcnt(2)
	v_mfma_f32_16x16x32_bf16 v[74:77], v[50:53], v[34:37], v[74:77]
	v_mfma_f32_16x16x32_bf16 v[74:77], v[54:57], v[38:41], v[74:77]
	s_waitcnt lgkmcnt(0)
	v_mfma_f32_16x16x32_bf16 v[78:81], v[58:61], v[34:37], v[78:81]
	v_mfma_f32_16x16x32_bf16 v[78:81], v[62:65], v[38:41], v[78:81]
	s_branch .Lnsa_ssm_30
.Lnsa_far_29:
	s_nop 1
	v_bfi_b32 v216, v234, v225, v252
	v_mov_b32_e32 v217, v216
	v_mov_b32_e32 v218, v216
	v_mov_b32_e32 v219, v216
	ds_read_b128 v[50:53], v170 offset:0
	ds_read_b128 v[54:57], v171 offset:0
	ds_read_b128 v[58:61], v170 offset:512
	ds_read_b128 v[62:65], v171 offset:512
	s_waitcnt lgkmcnt(2)
	v_mfma_f32_16x16x32_bf16 v[66:69], v[50:53], v[34:37], v[216:219]
	v_mfma_f32_16x16x32_bf16 v[66:69], v[54:57], v[38:41], v[66:69]
	ds_read_b128 v[50:53], v170 offset:4096
	ds_read_b128 v[54:57], v171 offset:4096
	s_waitcnt lgkmcnt(2)
	v_mfma_f32_16x16x32_bf16 v[70:73], v[58:61], v[34:37], v[216:219]
	v_mfma_f32_16x16x32_bf16 v[70:73], v[62:65], v[38:41], v[70:73]
	ds_read_b128 v[58:61], v170 offset:4608
	ds_read_b128 v[62:65], v171 offset:4608
	s_waitcnt lgkmcnt(2)
	v_mfma_f32_16x16x32_bf16 v[74:77], v[50:53], v[34:37], v[216:219]
	v_mfma_f32_16x16x32_bf16 v[74:77], v[54:57], v[38:41], v[74:77]
	s_waitcnt lgkmcnt(0)
	v_mfma_f32_16x16x32_bf16 v[78:81], v[58:61], v[34:37], v[216:219]
	v_mfma_f32_16x16x32_bf16 v[78:81], v[62:65], v[38:41], v[78:81]
	s_branch .Lnsa_ssm_30
.Lnsa_gen_28:
	s_nop 1
	v_bfi_b32 v216, v234, v1, v252
	v_mov_b32_e32 v217, v216
	v_mov_b32_e32 v218, v216
	v_mov_b32_e32 v219, v216
	v_mov_b32_e32 v227, v229
	ds_read_b128 v[50:53], v170 offset:0
	ds_read_b128 v[54:57], v171 offset:0
	ds_read_b128 v[58:61], v170 offset:512
	ds_read_b128 v[62:65], v171 offset:512
	s_waitcnt lgkmcnt(2)
	v_mfma_f32_16x16x32_bf16 v[66:69], v[50:53], v[34:37], v[216:219]
	v_mfma_f32_16x16x32_bf16 v[66:69], v[54:57], v[38:41], v[66:69]
	ds_read_b128 v[50:53], v170 offset:4096
	ds_read_b128 v[54:57], v171 offset:4096
	s_waitcnt lgkmcnt(2)
	v_mfma_f32_16x16x32_bf16 v[70:73], v[58:61], v[34:37], v[216:219]
	v_mfma_f32_16x16x32_bf16 v[70:73], v[62:65], v[38:41], v[70:73]
	ds_read_b128 v[58:61], v170 offset:4608
	ds_read_b128 v[62:65], v171 offset:4608
	s_waitcnt lgkmcnt(2)
	v_mfma_f32_16x16x32_bf16 v[74:77], v[50:53], v[34:37], v[216:219]
	v_mfma_f32_16x16x32_bf16 v[74:77], v[54:57], v[38:41], v[74:77]
	s_waitcnt lgkmcnt(0)
	v_mfma_f32_16x16x32_bf16 v[78:81], v[58:61], v[34:37], v[216:219]
	v_mfma_f32_16x16x32_bf16 v[78:81], v[62:65], v[38:41], v[78:81]
	v_bfe_u32 v253, v184, 2, 2
	v_mul_u32_u24_e32 v253, 0x1010, v253
	v_add_u32_e32 v230, 0x0, v227
	v_min_u32_e32 v230, 0x400, v230
	v_lshl_add_u32 v230, v230, 2, v253
	ds_read_b32 v82, v230
	v_add_u32_e32 v230, 0xffffffff, v227
	v_min_u32_e32 v230, 0x400, v230
	v_lshl_add_u32 v230, v230, 2, v253
	ds_read_b32 v83, v230
	v_add_u32_e32 v230, 0xfffffffe, v227
	v_min_u32_e32 v230, 0x400, v230
	v_lshl_add_u32 v230, v230, 2, v253
	ds_read_b32 v84, v230
	v_add_u32_e32 v230, 0xfffffffd, v227
	v_min_u32_e32 v230, 0x400, v230
	v_lshl_add_u32 v230, v230, 2, v253
	ds_read_b32 v85, v230
	v_add_u32_e32 v230, 0xfffffffc, v227
	v_min_u32_e32 v230, 0x400, v230
	v_lshl_add_u32 v230, v230, 2, v253
	ds_read_b32 v86, v230
	v_add_u32_e32 v230, 0xfffffffb, v227
	v_min_u32_e32 v230, 0x400, v230
	v_lshl_add_u32 v230, v230, 2, v253
	ds_read_b32 v87, v230
	v_add_u32_e32 v230, 0xfffffffa, v227
	v_min_u32_e32 v230, 0x400, v230
	v_lshl_add_u32 v230, v230, 2, v253
	ds_read_b32 v88, v230
	v_add_u32_e32 v230, 0xfffffff9, v227
	v_min_u32_e32 v230, 0x400, v230
	v_lshl_add_u32 v230, v230, 2, v253
	ds_read_b32 v89, v230
	s_waitcnt lgkmcnt(7)
	v_add_u32_e32 v230, 0x0, v227
	v_cmp_gt_u32_e32 vcc, s52, v230
	s_nop 1
	v_cndmask_b32_e32 v82, v252, v82, vcc
	v_add_f32_e32 v66, v66, v82
	s_waitcnt lgkmcnt(6)
	v_add_u32_e32 v230, 0xffffffff, v227
	v_cmp_gt_u32_e32 vcc, s52, v230
	s_nop 1
	v_cndmask_b32_e32 v83, v252, v83, vcc
	v_add_f32_e32 v67, v67, v83
	s_waitcnt lgkmcnt(5)
	v_add_u32_e32 v230, 0xfffffffe, v227
	v_cmp_gt_u32_e32 vcc, s52, v230
	s_nop 1
	v_cndmask_b32_e32 v84, v252, v84, vcc
	v_add_f32_e32 v68, v68, v84
	s_waitcnt lgkmcnt(4)
	v_add_u32_e32 v230, 0xfffffffd, v227
	v_cmp_gt_u32_e32 vcc, s52, v230
	s_nop 1
	v_cndmask_b32_e32 v85, v252, v85, vcc
	v_add_f32_e32 v69, v69, v85
	s_waitcnt lgkmcnt(3)
	v_add_u32_e32 v230, 0xfffffffc, v227
	v_cmp_gt_u32_e32 vcc, s52, v230
	s_nop 1
	v_cndmask_b32_e32 v86, v252, v86, vcc
	v_add_f32_e32 v70, v70, v86
	s_waitcnt lgkmcnt(2)
; #define LAS __attribute__((address_space(3)))
; #define CBAR() asm volatile("" ::: "memory")
; #define MFMA16(a, b, c) __builtin_amdgcn_mfma_f32_16x16x32_bf16(a, b, c, 0, 0, 0)
; __device__ __forceinline__ bf16_t tobf(float x) { return (bf16_t)pk2(x, 0.f); }
; __device__ __forceinline__ float ex2(float x) { return __builtin_amdgcn_exp2f(x); }
; template <int MODE> ...
;     ...
;                     for (int cc = 0; cc < 4; ++cc) { const int pos = j * 64 + cc * 16 + r16;
; #pragma unroll
;                         for (int i = 0; i < 4; ++i) { const int dist = t0 + i - pos; const bool ok = MODE ? ((unsigned)dist < 512u) : (dist >= 0 && mb[i]);
;                             const float p = ok ? ex2(sc[cc][i] + bt[clampd(dist)]) : 0.f; ls[tile][i] += p; Pb[(4 * q4 + i) * 72 + cc * 16 + r16] = tobf(p); } }
;                 }
;                 CBAR();
; #pragma unroll
;                 for (int ks = 0; ks < 2; ++ks) { const bf16x8 aP = *(const LAS bf16x8*)(Pb + r16 * 72 + ks * 32 + q4 * 8);
; #pragma unroll
;                     for (int nt = 0; nt < 4; ++nt) os[tile][nt] = MFMA16(aP, *(const LAS bf16x8*)(Vs + (nt * 16 + r16) * 72 + ks * 32 + q4 * 8), os[tile][nt]); }
	v_add_u32_e32 v230, 0xfffffffb, v227
	v_cmp_gt_u32_e32 vcc, s52, v230
	s_nop 1
	v_cndmask_b32_e32 v87, v252, v87, vcc
	v_add_f32_e32 v71, v71, v87
	s_waitcnt lgkmcnt(1)
	v_add_u32_e32 v230, 0xfffffffa, v227
	v_cmp_gt_u32_e32 vcc, s52, v230
	s_nop 1
	v_cndmask_b32_e32 v88, v252, v88, vcc
	v_add_f32_e32 v72, v72, v88
	s_waitcnt lgkmcnt(0)
	v_add_u32_e32 v230, 0xfffffff9, v227
	v_cmp_gt_u32_e32 vcc, s52, v230
	s_nop 1
	v_cndmask_b32_e32 v89, v252, v89, vcc
	v_add_f32_e32 v73, v73, v89
	v_add_u32_e32 v230, 0xffffffe0, v227
	v_min_u32_e32 v230, 0x400, v230
	v_lshl_add_u32 v230, v230, 2, v253
	ds_read_b32 v82, v230
	v_add_u32_e32 v230, 0xffffffdf, v227
	v_min_u32_e32 v230, 0x400, v230
	v_lshl_add_u32 v230, v230, 2, v253
	ds_read_b32 v83, v230
	v_add_u32_e32 v230, 0xffffffde, v227
	v_min_u32_e32 v230, 0x400, v230
	v_lshl_add_u32 v230, v230, 2, v253
	ds_read_b32 v84, v230
	v_add_u32_e32 v230, 0xffffffdd, v227
	v_min_u32_e32 v230, 0x400, v230
	v_lshl_add_u32 v230, v230, 2, v253
	ds_read_b32 v85, v230
	v_add_u32_e32 v230, 0xffffffdc, v227
	v_min_u32_e32 v230, 0x400, v230
	v_lshl_add_u32 v230, v230, 2, v253
	ds_read_b32 v86, v230
	v_add_u32_e32 v230, 0xffffffdb, v227
	v_min_u32_e32 v230, 0x400, v230
	v_lshl_add_u32 v230, v230, 2, v253
	ds_read_b32 v87, v230
	v_add_u32_e32 v230, 0xffffffda, v227
	v_min_u32_e32 v230, 0x400, v230
	v_lshl_add_u32 v230, v230, 2, v253
	ds_read_b32 v88, v230
	v_add_u32_e32 v230, 0xffffffd9, v227
	v_min_u32_e32 v230, 0x400, v230
	v_lshl_add_u32 v230, v230, 2, v253
	ds_read_b32 v89, v230
	s_waitcnt lgkmcnt(7)
	v_add_u32_e32 v230, 0xffffffe0, v227
	v_cmp_gt_u32_e32 vcc, s52, v230
	s_nop 1
	v_cndmask_b32_e32 v82, v252, v82, vcc
	v_add_f32_e32 v74, v74, v82
	s_waitcnt lgkmcnt(6)
	v_add_u32_e32 v230, 0xffffffdf, v227
	v_cmp_gt_u32_e32 vcc, s52, v230
	s_nop 1
	v_cndmask_b32_e32 v83, v252, v83, vcc
	v_add_f32_e32 v75, v75, v83
	s_waitcnt lgkmcnt(5)
	v_add_u32_e32 v230, 0xffffffde, v227
	v_cmp_gt_u32_e32 vcc, s52, v230
	s_nop 1
	v_cndmask_b32_e32 v84, v252, v84, vcc
	v_add_f32_e32 v76, v76, v84
	s_waitcnt lgkmcnt(4)
	v_add_u32_e32 v230, 0xffffffdd, v227
	v_cmp_gt_u32_e32 vcc, s52, v230
	s_nop 1
	v_cndmask_b32_e32 v85, v252, v85, vcc
	v_add_f32_e32 v77, v77, v85
	s_waitcnt lgkmcnt(3)
	v_add_u32_e32 v230, 0xffffffdc, v227
	v_cmp_gt_u32_e32 vcc, s52, v230
	s_nop 1
	v_cndmask_b32_e32 v86, v252, v86, vcc
	v_add_f32_e32 v78, v78, v86
	s_waitcnt lgkmcnt(2)
	v_add_u32_e32 v230, 0xffffffdb, v227
	v_cmp_gt_u32_e32 vcc, s52, v230
	s_nop 1
	v_cndmask_b32_e32 v87, v252, v87, vcc
	v_add_f32_e32 v79, v79, v87
	s_waitcnt lgkmcnt(1)
	v_add_u32_e32 v230, 0xffffffda, v227
	v_cmp_gt_u32_e32 vcc, s52, v230
	s_nop 1
	v_cndmask_b32_e32 v88, v252, v88, vcc
	v_add_f32_e32 v80, v80, v88
	s_waitcnt lgkmcnt(0)
	v_add_u32_e32 v230, 0xffffffd9, v227
	v_cmp_gt_u32_e32 vcc, s52, v230
	s_nop 1
	v_cndmask_b32_e32 v89, v252, v89, vcc
	v_add_f32_e32 v81, v81, v89
.Lnsa_ssm_30:
	s_nop 1
	s_waitcnt lgkmcnt(0)
	ds_read_b128 v[50:53], v172 offset:0
	ds_read_b128 v[54:57], v173 offset:0
	ds_read_b128 v[58:61], v172 offset:2048
	ds_read_b128 v[62:65], v173 offset:2048
	v_exp_f32_e32 v66, v66
	v_exp_f32_e32 v67, v67
	v_exp_f32_e32 v68, v68
	v_exp_f32_e32 v69, v69
	v_exp_f32_e32 v70, v70
	v_exp_f32_e32 v71, v71
	v_exp_f32_e32 v72, v72
	v_exp_f32_e32 v73, v73
	v_exp_f32_e32 v74, v74
	v_exp_f32_e32 v75, v75
	v_exp_f32_e32 v76, v76
	v_exp_f32_e32 v77, v77
	v_exp_f32_e32 v78, v78
	v_exp_f32_e32 v79, v79
	v_exp_f32_e32 v80, v80
	v_exp_f32_e32 v81, v81
	v_add_f32_e32 v215, v215, v66
	v_add_f32_e32 v215, v215, v67
	v_add_f32_e32 v215, v215, v68
	v_add_f32_e32 v215, v215, v69
	v_add_f32_e32 v215, v215, v70
	v_add_f32_e32 v215, v215, v71
	v_add_f32_e32 v215, v215, v72
	v_add_f32_e32 v215, v215, v73
	v_add_f32_e32 v215, v215, v74
	v_add_f32_e32 v215, v215, v75
	v_add_f32_e32 v215, v215, v76
	v_add_f32_e32 v215, v215, v77
	v_add_f32_e32 v215, v215, v78
	v_add_f32_e32 v215, v215, v79
	v_add_f32_e32 v215, v215, v80
	v_add_f32_e32 v215, v215, v81
	v_cvt_pk_bf16_f32 v82, v66, v67
	v_cvt_pk_bf16_f32 v83, v68, v69
	v_cvt_pk_bf16_f32 v84, v70, v71
	v_cvt_pk_bf16_f32 v85, v72, v73
	v_cvt_pk_bf16_f32 v86, v74, v75
	v_cvt_pk_bf16_f32 v87, v76, v77
	v_cvt_pk_bf16_f32 v88, v78, v79
	v_cvt_pk_bf16_f32 v89, v80, v81
	s_waitcnt lgkmcnt(2)
	v_mfma_f32_16x16x32_bf16 v[2:5], v[50:53], v[82:85], v[2:5]
	v_mfma_f32_16x16x32_bf16 v[2:5], v[54:57], v[86:89], v[2:5]
	ds_read_b128 v[50:53], v172 offset:4096
	ds_read_b128 v[54:57], v173 offset:4096
	s_waitcnt lgkmcnt(2)
	v_mfma_f32_16x16x32_bf16 v[6:9], v[58:61], v[82:85], v[6:9]
	v_mfma_f32_16x16x32_bf16 v[6:9], v[62:65], v[86:89], v[6:9]
	ds_read_b128 v[58:61], v172 offset:6144
	ds_read_b128 v[62:65], v173 offset:6144
	s_waitcnt lgkmcnt(2)
	v_mfma_f32_16x16x32_bf16 v[10:13], v[50:53], v[82:85], v[10:13]
	v_mfma_f32_16x16x32_bf16 v[10:13], v[54:57], v[86:89], v[10:13]
	s_waitcnt lgkmcnt(0)
	v_mfma_f32_16x16x32_bf16 v[14:17], v[58:61], v[82:85], v[14:17]
	v_mfma_f32_16x16x32_bf16 v[14:17], v[62:65], v[86:89], v[14:17]
; #define LAS __attribute__((address_space(3)))
; #define MFMA16(a, b, c) __builtin_amdgcn_mfma_f32_16x16x32_bf16(a, b, c, 0, 0, 0)
; __device__ __forceinline__ bf16_t tobf(float x) { return (bf16_t)pk2(x, 0.f); }
; __device__ __forceinline__ float ex2(float x) { return __builtin_amdgcn_exp2f(x); }
; template <int MODE> ...
;     ...
;         for (int tile = 0; tile < 2; ++tile) {
;             const int tl0 = wave * 8 + tile * 4, t0 = qb * 64 + tl0;
;             unsigned mb[4] = {1u, 1u, 1u, 1u};
;             if (MODE == 0) {
; #pragma unroll
;                 for (int i = 0; i < 4; ++i) mb[i] = (masks[(tl0 + i) * 4 + (j >> 5)] >> (j & 31)) & 1u; }
;             if (MODE == 1 || __builtin_amdgcn_readfirstlane((int)(mb[0] | mb[1] | mb[2] | mb[3]))) {
;                 f32x4 sc[4];
; #pragma unroll
;                 for (int cc = 0; cc < 4; ++cc) { const LAS bf16_t* kp = Ks + (cc * 16 + r16) * 72 + q4 * 8;
;                     sc[cc] = MFMA16(aq[tile][0], *(const LAS bf16x8*)kp, z4); sc[cc] = MFMA16(aq[tile][1], *(const LAS bf16x8*)(kp + 32), sc[cc]); }
;                 if (far) {
; #pragma unroll
;                     for (int cc = 0; cc < 4; ++cc)
; #pragma unroll
;                         for (int i = 0; i < 4; ++i) { const float p = mb[i] ? ex2(sc[cc][i] + bfar) : 0.f; ls[tile][i] += p; Pb[(4 * q4 + i) * 72 + cc * 16 + r16] = tobf(p); }
;                 } else {
; #pragma unroll
;                     for (int cc = 0; cc < 4; ++cc) { const int pos = j * 64 + cc * 16 + r16;
; #pragma unroll
;                         for (int i = 0; i < 4; ++i) { const int dist = t0 + i - pos; const bool ok = MODE ? ((unsigned)dist < 512u) : (dist >= 0 && mb[i]);
;                             const float p = ok ? ex2(sc[cc][i] + bt[clampd(dist)]) : 0.f; ls[tile][i] += p; Pb[(4 * q4 + i) * 72 + cc * 16 + r16] = tobf(p); } }
.Lnsa_single1_24:
	s_nop 1
	s_bitcmp1_b32 s34, 1
	s_cbranch_scc0 .Lnsa_blkend_25
	s_cmp_eq_u32 s42, 1
	s_cbranch_scc1 .Lnsa_gen_31
	s_cmp_eq_u32 s42, 2
	s_cbranch_scc1 .Lnsa_far_32
	v_add_u32_e32 v230, 16, v231
	v_bfi_b32 v230, v235, v230, v226
	ds_read2_b32 v[66:67], v230 offset0:39 offset1:38
	ds_read2_b32 v[68:69], v230 offset0:37 offset1:36
	ds_read2_b32 v[70:71], v230 offset0:35 offset1:34
	ds_read2_b32 v[72:73], v230 offset0:33 offset1:32
	ds_read2_b32 v[74:75], v230 offset0:7 offset1:6
	ds_read2_b32 v[76:77], v230 offset0:5 offset1:4
	ds_read2_b32 v[78:79], v230 offset0:3 offset1:2
	ds_read2_b32 v[80:81], v230 offset0:1 offset1:0
	ds_read_b128 v[50:53], v170 offset:0
	ds_read_b128 v[54:57], v171 offset:0
	ds_read_b128 v[58:61], v170 offset:512
	ds_read_b128 v[62:65], v171 offset:512
	s_waitcnt lgkmcnt(2)
	v_mfma_f32_16x16x32_bf16 v[66:69], v[50:53], v[42:45], v[66:69]
	v_mfma_f32_16x16x32_bf16 v[66:69], v[54:57], v[46:49], v[66:69]
	ds_read_b128 v[50:53], v170 offset:4096
	ds_read_b128 v[54:57], v171 offset:4096
	s_waitcnt lgkmcnt(2)
	v_mfma_f32_16x16x32_bf16 v[70:73], v[58:61], v[42:45], v[70:73]
	v_mfma_f32_16x16x32_bf16 v[70:73], v[62:65], v[46:49], v[70:73]
	ds_read_b128 v[58:61], v170 offset:4608
	ds_read_b128 v[62:65], v171 offset:4608
	s_waitcnt lgkmcnt(2)
	v_mfma_f32_16x16x32_bf16 v[74:77], v[50:53], v[42:45], v[74:77]
	v_mfma_f32_16x16x32_bf16 v[74:77], v[54:57], v[46:49], v[74:77]
	s_waitcnt lgkmcnt(0)
	v_mfma_f32_16x16x32_bf16 v[78:81], v[58:61], v[42:45], v[78:81]
	v_mfma_f32_16x16x32_bf16 v[78:81], v[62:65], v[46:49], v[78:81]
	s_branch .Lnsa_ssm_33
.Lnsa_far_32:
	s_nop 1
	v_bfi_b32 v216, v235, v225, v252
	v_mov_b32_e32 v217, v216
	v_mov_b32_e32 v218, v216
	v_mov_b32_e32 v219, v216
	ds_read_b128 v[50:53], v170 offset:0
	ds_read_b128 v[54:57], v171 offset:0
	ds_read_b128 v[58:61], v170 offset:512
	ds_read_b128 v[62:65], v171 offset:512
	s_waitcnt lgkmcnt(2)
	v_mfma_f32_16x16x32_bf16 v[66:69], v[50:53], v[42:45], v[216:219]
	v_mfma_f32_16x16x32_bf16 v[66:69], v[54:57], v[46:49], v[66:69]
	ds_read_b128 v[50:53], v170 offset:4096
	ds_read_b128 v[54:57], v171 offset:4096
	s_waitcnt lgkmcnt(2)
	v_mfma_f32_16x16x32_bf16 v[70:73], v[58:61], v[42:45], v[216:219]
	v_mfma_f32_16x16x32_bf16 v[70:73], v[62:65], v[46:49], v[70:73]
	ds_read_b128 v[58:61], v170 offset:4608
	ds_read_b128 v[62:65], v171 offset:4608
	s_waitcnt lgkmcnt(2)
	v_mfma_f32_16x16x32_bf16 v[74:77], v[50:53], v[42:45], v[216:219]
	v_mfma_f32_16x16x32_bf16 v[74:77], v[54:57], v[46:49], v[74:77]
	s_waitcnt lgkmcnt(0)
	v_mfma_f32_16x16x32_bf16 v[78:81], v[58:61], v[42:45], v[216:219]
	v_mfma_f32_16x16x32_bf16 v[78:81], v[62:65], v[46:49], v[78:81]
	s_branch .Lnsa_ssm_33
.Lnsa_gen_31:
	s_nop 1
	v_bfi_b32 v216, v235, v1, v252
	v_mov_b32_e32 v217, v216
	v_mov_b32_e32 v218, v216
	v_mov_b32_e32 v219, v216
	v_add_u32_e32 v227, 4, v229
	ds_read_b128 v[50:53], v170 offset:0
	ds_read_b128 v[54:57], v171 offset:0
	ds_read_b128 v[58:61], v170 offset:512
	ds_read_b128 v[62:65], v171 offset:512
	s_waitcnt lgkmcnt(2)
	v_mfma_f32_16x16x32_bf16 v[66:69], v[50:53], v[42:45], v[216:219]
	v_mfma_f32_16x16x32_bf16 v[66:69], v[54:57], v[46:49], v[66:69]
	ds_read_b128 v[50:53], v170 offset:4096
	ds_read_b128 v[54:57], v171 offset:4096
	s_waitcnt lgkmcnt(2)
	v_mfma_f32_16x16x32_bf16 v[70:73], v[58:61], v[42:45], v[216:219]
	v_mfma_f32_16x16x32_bf16 v[70:73], v[62:65], v[46:49], v[70:73]
	ds_read_b128 v[58:61], v170 offset:4608
	ds_read_b128 v[62:65], v171 offset:4608
	s_waitcnt lgkmcnt(2)
	v_mfma_f32_16x16x32_bf16 v[74:77], v[50:53], v[42:45], v[216:219]
	v_mfma_f32_16x16x32_bf16 v[74:77], v[54:57], v[46:49], v[74:77]
	s_waitcnt lgkmcnt(0)
	v_mfma_f32_16x16x32_bf16 v[78:81], v[58:61], v[42:45], v[216:219]
	v_mfma_f32_16x16x32_bf16 v[78:81], v[62:65], v[46:49], v[78:81]
	v_bfe_u32 v253, v184, 2, 2
	v_mul_u32_u24_e32 v253, 0x1010, v253
	v_add_u32_e32 v230, 0x0, v227
	v_min_u32_e32 v230, 0x400, v230
	v_lshl_add_u32 v230, v230, 2, v253
	ds_read_b32 v82, v230
	v_add_u32_e32 v230, 0xffffffff, v227
	v_min_u32_e32 v230, 0x400, v230
	v_lshl_add_u32 v230, v230, 2, v253
	ds_read_b32 v83, v230
	v_add_u32_e32 v230, 0xfffffffe, v227
	v_min_u32_e32 v230, 0x400, v230
	v_lshl_add_u32 v230, v230, 2, v253
	ds_read_b32 v84, v230
	v_add_u32_e32 v230, 0xfffffffd, v227
	v_min_u32_e32 v230, 0x400, v230
	v_lshl_add_u32 v230, v230, 2, v253
	ds_read_b32 v85, v230
	v_add_u32_e32 v230, 0xfffffffc, v227
	v_min_u32_e32 v230, 0x400, v230
	v_lshl_add_u32 v230, v230, 2, v253
	ds_read_b32 v86, v230
	v_add_u32_e32 v230, 0xfffffffb, v227
	v_min_u32_e32 v230, 0x400, v230
	v_lshl_add_u32 v230, v230, 2, v253
	ds_read_b32 v87, v230
	v_add_u32_e32 v230, 0xfffffffa, v227
	v_min_u32_e32 v230, 0x400, v230
	v_lshl_add_u32 v230, v230, 2, v253
	ds_read_b32 v88, v230
	v_add_u32_e32 v230, 0xfffffff9, v227
	v_min_u32_e32 v230, 0x400, v230
	v_lshl_add_u32 v230, v230, 2, v253
	ds_read_b32 v89, v230
	s_waitcnt lgkmcnt(7)
	v_add_u32_e32 v230, 0x0, v227
	v_cmp_gt_u32_e32 vcc, s52, v230
	s_nop 1
	v_cndmask_b32_e32 v82, v252, v82, vcc
	v_add_f32_e32 v66, v66, v82
	s_waitcnt lgkmcnt(6)
	v_add_u32_e32 v230, 0xffffffff, v227
	v_cmp_gt_u32_e32 vcc, s52, v230
	s_nop 1
	v_cndmask_b32_e32 v83, v252, v83, vcc
	v_add_f32_e32 v67, v67, v83
	s_waitcnt lgkmcnt(5)
	v_add_u32_e32 v230, 0xfffffffe, v227
	v_cmp_gt_u32_e32 vcc, s52, v230
	s_nop 1
	v_cndmask_b32_e32 v84, v252, v84, vcc
	v_add_f32_e32 v68, v68, v84
	s_waitcnt lgkmcnt(4)
	v_add_u32_e32 v230, 0xfffffffd, v227
	v_cmp_gt_u32_e32 vcc, s52, v230
	s_nop 1
	v_cndmask_b32_e32 v85, v252, v85, vcc
	v_add_f32_e32 v69, v69, v85
	s_waitcnt lgkmcnt(3)
; #define LAS __attribute__((address_space(3)))
; #define CBAR() asm volatile("" ::: "memory")
; #define MFMA16(a, b, c) __builtin_amdgcn_mfma_f32_16x16x32_bf16(a, b, c, 0, 0, 0)
; __device__ __forceinline__ bf16_t tobf(float x) { return (bf16_t)pk2(x, 0.f); }
; __device__ __forceinline__ float ex2(float x) { return __builtin_amdgcn_exp2f(x); }
; #define NSA_ST1(st_, half_) do { LAS bf16_t* nx_ = stage + (st_) * 18432 + (half_) * 9216 + soff; *(LAS bf16x8*)nx_ = kr; *(LAS bf16x8*)(nx_ + 4608) = vr; } while (0)
; template <int MODE> ...
;     ...
;                     for (int cc = 0; cc < 4; ++cc) { const int pos = j * 64 + cc * 16 + r16;
; #pragma unroll
;                         for (int i = 0; i < 4; ++i) { const int dist = t0 + i - pos; const bool ok = MODE ? ((unsigned)dist < 512u) : (dist >= 0 && mb[i]);
;                             const float p = ok ? ex2(sc[cc][i] + bt[clampd(dist)]) : 0.f; ls[tile][i] += p; Pb[(4 * q4 + i) * 72 + cc * 16 + r16] = tobf(p); } }
;                 }
;                 CBAR();
; #pragma unroll
;                 for (int ks = 0; ks < 2; ++ks) { const bf16x8 aP = *(const LAS bf16x8*)(Pb + r16 * 72 + ks * 32 + q4 * 8);
; #pragma unroll
;                     for (int nt = 0; nt < 4; ++nt) os[tile][nt] = MFMA16(aP, *(const LAS bf16x8*)(Vs + (nt * 16 + r16) * 72 + ks * 32 + q4 * 8), os[tile][nt]); }
;                 CBAR();
;             }
;         }
;         if (pre) NSA_ST1(pp ^ 1, sub);
;       }
;         __syncthreads();
;     }
	v_add_u32_e32 v230, 0xfffffffc, v227
	v_cmp_gt_u32_e32 vcc, s52, v230
	s_nop 1
	v_cndmask_b32_e32 v86, v252, v86, vcc
	v_add_f32_e32 v70, v70, v86
	s_waitcnt lgkmcnt(2)
	v_add_u32_e32 v230, 0xfffffffb, v227
	v_cmp_gt_u32_e32 vcc, s52, v230
	s_nop 1
	v_cndmask_b32_e32 v87, v252, v87, vcc
	v_add_f32_e32 v71, v71, v87
	s_waitcnt lgkmcnt(1)
	v_add_u32_e32 v230, 0xfffffffa, v227
	v_cmp_gt_u32_e32 vcc, s52, v230
	s_nop 1
	v_cndmask_b32_e32 v88, v252, v88, vcc
	v_add_f32_e32 v72, v72, v88
	s_waitcnt lgkmcnt(0)
	v_add_u32_e32 v230, 0xfffffff9, v227
	v_cmp_gt_u32_e32 vcc, s52, v230
	s_nop 1
	v_cndmask_b32_e32 v89, v252, v89, vcc
	v_add_f32_e32 v73, v73, v89
	v_add_u32_e32 v230, 0xffffffe0, v227
	v_min_u32_e32 v230, 0x400, v230
	v_lshl_add_u32 v230, v230, 2, v253
	ds_read_b32 v82, v230
	v_add_u32_e32 v230, 0xffffffdf, v227
	v_min_u32_e32 v230, 0x400, v230
	v_lshl_add_u32 v230, v230, 2, v253
	ds_read_b32 v83, v230
	v_add_u32_e32 v230, 0xffffffde, v227
	v_min_u32_e32 v230, 0x400, v230
	v_lshl_add_u32 v230, v230, 2, v253
	ds_read_b32 v84, v230
	v_add_u32_e32 v230, 0xffffffdd, v227
	v_min_u32_e32 v230, 0x400, v230
	v_lshl_add_u32 v230, v230, 2, v253
	ds_read_b32 v85, v230
	v_add_u32_e32 v230, 0xffffffdc, v227
	v_min_u32_e32 v230, 0x400, v230
	v_lshl_add_u32 v230, v230, 2, v253
	ds_read_b32 v86, v230
	v_add_u32_e32 v230, 0xffffffdb, v227
	v_min_u32_e32 v230, 0x400, v230
	v_lshl_add_u32 v230, v230, 2, v253
	ds_read_b32 v87, v230
	v_add_u32_e32 v230, 0xffffffda, v227
	v_min_u32_e32 v230, 0x400, v230
	v_lshl_add_u32 v230, v230, 2, v253
	ds_read_b32 v88, v230
	v_add_u32_e32 v230, 0xffffffd9, v227
	v_min_u32_e32 v230, 0x400, v230
	v_lshl_add_u32 v230, v230, 2, v253
	ds_read_b32 v89, v230
	s_waitcnt lgkmcnt(7)
	v_add_u32_e32 v230, 0xffffffe0, v227
	v_cmp_gt_u32_e32 vcc, s52, v230
	s_nop 1
	v_cndmask_b32_e32 v82, v252, v82, vcc
	v_add_f32_e32 v74, v74, v82
	s_waitcnt lgkmcnt(6)
	v_add_u32_e32 v230, 0xffffffdf, v227
	v_cmp_gt_u32_e32 vcc, s52, v230
	s_nop 1
	v_cndmask_b32_e32 v83, v252, v83, vcc
	v_add_f32_e32 v75, v75, v83
	s_waitcnt lgkmcnt(5)
	v_add_u32_e32 v230, 0xffffffde, v227
	v_cmp_gt_u32_e32 vcc, s52, v230
	s_nop 1
	v_cndmask_b32_e32 v84, v252, v84, vcc
	v_add_f32_e32 v76, v76, v84
	s_waitcnt lgkmcnt(4)
	v_add_u32_e32 v230, 0xffffffdd, v227
	v_cmp_gt_u32_e32 vcc, s52, v230
	s_nop 1
	v_cndmask_b32_e32 v85, v252, v85, vcc
	v_add_f32_e32 v77, v77, v85
	s_waitcnt lgkmcnt(3)
	v_add_u32_e32 v230, 0xffffffdc, v227
	v_cmp_gt_u32_e32 vcc, s52, v230
	s_nop 1
	v_cndmask_b32_e32 v86, v252, v86, vcc
	v_add_f32_e32 v78, v78, v86
	s_waitcnt lgkmcnt(2)
	v_add_u32_e32 v230, 0xffffffdb, v227
	v_cmp_gt_u32_e32 vcc, s52, v230
	s_nop 1
	v_cndmask_b32_e32 v87, v252, v87, vcc
	v_add_f32_e32 v79, v79, v87
	s_waitcnt lgkmcnt(1)
	v_add_u32_e32 v230, 0xffffffda, v227
	v_cmp_gt_u32_e32 vcc, s52, v230
	s_nop 1
	v_cndmask_b32_e32 v88, v252, v88, vcc
	v_add_f32_e32 v80, v80, v88
	s_waitcnt lgkmcnt(0)
	v_add_u32_e32 v230, 0xffffffd9, v227
	v_cmp_gt_u32_e32 vcc, s52, v230
	s_nop 1
	v_cndmask_b32_e32 v89, v252, v89, vcc
	v_add_f32_e32 v81, v81, v89
.Lnsa_ssm_33:
	s_nop 1
	s_waitcnt lgkmcnt(0)
	ds_read_b128 v[50:53], v172 offset:0
	ds_read_b128 v[54:57], v173 offset:0
	ds_read_b128 v[58:61], v172 offset:2048
	ds_read_b128 v[62:65], v173 offset:2048
	v_exp_f32_e32 v66, v66
	v_exp_f32_e32 v67, v67
	v_exp_f32_e32 v68, v68
	v_exp_f32_e32 v69, v69
	v_exp_f32_e32 v70, v70
	v_exp_f32_e32 v71, v71
	v_exp_f32_e32 v72, v72
	v_exp_f32_e32 v73, v73
	v_exp_f32_e32 v74, v74
	v_exp_f32_e32 v75, v75
	v_exp_f32_e32 v76, v76
	v_exp_f32_e32 v77, v77
	v_exp_f32_e32 v78, v78
	v_exp_f32_e32 v79, v79
	v_exp_f32_e32 v80, v80
	v_exp_f32_e32 v81, v81
	v_add_f32_e32 v224, v224, v66
	v_add_f32_e32 v224, v224, v67
	v_add_f32_e32 v224, v224, v68
	v_add_f32_e32 v224, v224, v69
	v_add_f32_e32 v224, v224, v70
	v_add_f32_e32 v224, v224, v71
	v_add_f32_e32 v224, v224, v72
	v_add_f32_e32 v224, v224, v73
	v_add_f32_e32 v224, v224, v74
	v_add_f32_e32 v224, v224, v75
	v_add_f32_e32 v224, v224, v76
	v_add_f32_e32 v224, v224, v77
	v_add_f32_e32 v224, v224, v78
	v_add_f32_e32 v224, v224, v79
	v_add_f32_e32 v224, v224, v80
	v_add_f32_e32 v224, v224, v81
	v_cvt_pk_bf16_f32 v82, v66, v67
	v_cvt_pk_bf16_f32 v83, v68, v69
	v_cvt_pk_bf16_f32 v84, v70, v71
	v_cvt_pk_bf16_f32 v85, v72, v73
	v_cvt_pk_bf16_f32 v86, v74, v75
	v_cvt_pk_bf16_f32 v87, v76, v77
	v_cvt_pk_bf16_f32 v88, v78, v79
	v_cvt_pk_bf16_f32 v89, v80, v81
	s_waitcnt lgkmcnt(2)
	v_mfma_f32_16x16x32_bf16 v[18:21], v[50:53], v[82:85], v[18:21]
	v_mfma_f32_16x16x32_bf16 v[18:21], v[54:57], v[86:89], v[18:21]
	ds_read_b128 v[50:53], v172 offset:4096
	ds_read_b128 v[54:57], v173 offset:4096
	s_waitcnt lgkmcnt(2)
	v_mfma_f32_16x16x32_bf16 v[22:25], v[58:61], v[82:85], v[22:25]
	v_mfma_f32_16x16x32_bf16 v[22:25], v[62:65], v[86:89], v[22:25]
	ds_read_b128 v[58:61], v172 offset:6144
	ds_read_b128 v[62:65], v173 offset:6144
	s_waitcnt lgkmcnt(2)
	v_mfma_f32_16x16x32_bf16 v[26:29], v[50:53], v[82:85], v[26:29]
	v_mfma_f32_16x16x32_bf16 v[26:29], v[54:57], v[86:89], v[26:29]
	s_waitcnt lgkmcnt(0)
	v_mfma_f32_16x16x32_bf16 v[30:33], v[58:61], v[82:85], v[30:33]
	v_mfma_f32_16x16x32_bf16 v[30:33], v[62:65], v[86:89], v[30:33]
.Lnsa_blkend_25:
	s_nop 1
	s_mov_b32 s33, -1
	s_cmp_lt_i32 s19, 0
	s_cbranch_scc1 .Lnsa_nonext_34
.Lnsa_nx_38:
	s_cmp_lg_u32 s72, 0
	s_cbranch_scc1 .Lnsa_nxh_39
	s_mov_b32 s72, s73
	s_mov_b32 s73, s74
	s_mov_b32 s74, s75
	s_mov_b32 s75, 0
	s_add_i32 s92, s92, 32
	s_mov_b32 s33, -1
	s_cmp_lt_u32 s92, 128
	s_cbranch_scc1 .Lnsa_nx_38
	s_branch .Lnsa_nxo_40
.Lnsa_nxh_39:
	s_ff1_i32_b32 s0, s72
	s_bitset0_b32 s72, s0
	s_add_i32 s33, s92, s0
.Lnsa_nxo_40:
.Lnsa_nonext_34:
	s_cmp_lt_i32 s19, 0
	s_cbranch_scc1 .Lnsa_w2_35
	s_waitcnt vmcnt(4)
	s_branch .Lnsa_wj_37
.Lnsa_w2_35:
	s_cmp_lt_i32 s95, 0
	s_cbranch_scc1 .Lnsa_w0_36
	s_waitcnt vmcnt(2)
	s_branch .Lnsa_wj_37

; __device__ __forceinline__ bf16_t tobf(float x) { return (bf16_t)pk2(x, 0.f); }
; __device__ __forceinline__ float red16(float v) { v += __shfl_xor(v, 1); v += __shfl_xor(v, 2); v += __shfl_xor(v, 4); v += __shfl_xor(v, 8); return v; }
; #define NSA_ST1(st_, half_) do { LAS bf16_t* nx_ = stage + (st_) * 18432 + (half_) * 9216 + soff; *(LAS bf16x8*)nx_ = kr; *(LAS bf16x8*)(nx_ + 4608) = vr; } while (0)
; template <int MODE> ...
;     ...
;         if (pre) NSA_ST1(pp ^ 1, sub);
;       }
;         __syncthreads();
;     }
;     ...
; #pragma unroll
;     for (int tile = 0; tile < 2; ++tile) { const int t0 = qb * 64 + wave * 8 + tile * 4;
; #pragma unroll
;         for (int tt = 0; tt < 4; ++tt) { const float gs = GN[(size_t)(b * SEQ + t0 + tt) * 48 + (g * 4 + q4) * 3 + (MODE ? 2 : 1)] / red16(ls[tile][tt]);
;             bf16_t* op = ONSA + (size_t)(b * SEQ + t0 + tt) * 1024 + (g * 4 + q4) * 64 + r16;
; #pragma unroll
;             for (int nt = 0; nt < 4; ++nt) op[nt * 16] = tobf(bflo((unsigned)op[nt * 16]) + gs * os[tile][nt][tt]); } }
.Lnsa_wj_37:
	s_waitcnt lgkmcnt(0)
	s_barrier
	s_mov_b32 s93, s94
	s_mov_b32 s94, s95
	s_mov_b32 s95, s19
	s_mov_b32 s19, s33
	s_add_i32 s57, s57, 1
	s_cmp_ge_i32 s93, 0
	s_cbranch_scc1 .Lnsa_blk_loop
.Lnsa_blk_done:
	s_nop 7
	s_nop 7
	v_and_b32_e32 v66, 15, v184
	v_lshrrev_b32_e32 v67, 4, v184
	v_and_b32_e32 v68, 3, v66
	v_lshrrev_b32_e32 v69, 2, v66
	s_lshl_b32 s0, s18, 6
	s_add_i32 s0, s0, s97
	s_add_i32 s0, s0, s80
	v_add_u32_e32 v70, s0, v68
	s_and_b32 s1, s88, 3
	s_lshl_b32 s1, s1, 2
	v_add_u32_e32 v71, s1, v69
	v_lshlrev_b32_e32 v72, 7, v71
	v_lshl_add_u32 v72, v70, 11, v72
	v_lshl_add_u32 v72, v67, 3, v72
	v_add_u32_e32 v73, 0x2000, v72
	v_mul_u32_u24_e32 v74, 0xc0, v70
	v_mul_u32_u24_e32 v75, 12, v71
	s_lshl_b32 s0, s54, 2
	s_add_i32 s0, s0, 4
	v_add3_u32 v74, v74, v75, s0
	s_add_u32 s70, s30, 0x38310000
	s_addc_u32 s71, s31, 0
	s_add_u32 s14, s30, 0xf900000
	s_addc_u32 s15, s31, 0
	global_load_dword v76, v74, s[70:71] offset:0
	global_load_dword v77, v74, s[70:71] offset:768
	global_load_dwordx2 v[50:51], v72, s[14:15] offset:0
	global_load_dwordx2 v[52:53], v72, s[14:15] offset:32
	global_load_dwordx2 v[54:55], v72, s[14:15] offset:64
	global_load_dwordx2 v[56:57], v72, s[14:15] offset:96
	global_load_dwordx2 v[58:59], v73, s[14:15] offset:0
	global_load_dwordx2 v[60:61], v73, s[14:15] offset:32
	global_load_dwordx2 v[62:63], v73, s[14:15] offset:64
	global_load_dwordx2 v[64:65], v73, s[14:15] offset:96
	v_xor_b32_e32 v78, 16, v184
	v_lshlrev_b32_e32 v78, 2, v78
	v_xor_b32_e32 v79, 32, v184
	v_lshlrev_b32_e32 v79, 2, v79
	ds_bpermute_b32 v237, v78, v215
	s_waitcnt lgkmcnt(0)
	v_add_f32_e32 v236, v215, v237
	ds_bpermute_b32 v237, v79, v236
	s_waitcnt lgkmcnt(0)
	v_add_f32_e32 v236, v236, v237
	ds_bpermute_b32 v245, v78, v224
	s_waitcnt lgkmcnt(0)
	v_add_f32_e32 v244, v224, v245
	ds_bpermute_b32 v245, v79, v244
	s_waitcnt lgkmcnt(0)
	v_add_f32_e32 v244, v244, v245
	s_waitcnt vmcnt(9)
	v_div_scale_f32 v237, s[20:21], v236, v236, v76
	v_rcp_f32_e32 v238, v237
	v_div_scale_f32 v239, vcc, v76, v236, v76
	v_fma_f32 v240, -v237, v238, 1.0
	v_fmac_f32_e32 v238, v240, v238
	v_mul_f32_e32 v240, v239, v238
	v_fma_f32 v241, -v237, v240, v239
	v_fmac_f32_e32 v240, v241, v238
	v_fma_f32 v237, -v237, v240, v239
	s_nop 1
	v_div_fmas_f32 v237, v237, v238, v240
	v_div_fixup_f32 v239, v237, v236, v76
	s_waitcnt vmcnt(8)
	v_div_scale_f32 v245, s[20:21], v244, v244, v77
	v_rcp_f32_e32 v246, v245
	v_div_scale_f32 v247, vcc, v77, v244, v77
	v_fma_f32 v248, -v245, v246, 1.0
	v_fmac_f32_e32 v246, v248, v246
	v_mul_f32_e32 v248, v247, v246
	v_fma_f32 v249, -v245, v248, v247
	v_fmac_f32_e32 v248, v249, v246
	v_fma_f32 v245, -v245, v248, v247
	s_nop 1
	v_div_fmas_f32 v245, v245, v246, v248
	v_div_fixup_f32 v247, v245, v244, v77
	s_waitcnt vmcnt(7)
	v_lshlrev_b32_e32 v242, 16, v50
	v_and_b32_e32 v243, 0xffff0000, v50
	v_fmac_f32_e32 v242, v239, v2
	v_fmac_f32_e32 v243, v239, v3
	v_cvt_pk_bf16_f32 v82, v242, v243
	v_lshlrev_b32_e32 v242, 16, v51
	v_and_b32_e32 v243, 0xffff0000, v51
	v_fmac_f32_e32 v242, v239, v4
	v_fmac_f32_e32 v243, v239, v5
	v_cvt_pk_bf16_f32 v83, v242, v243
	s_waitcnt vmcnt(6)
	v_lshlrev_b32_e32 v242, 16, v52
	v_and_b32_e32 v243, 0xffff0000, v52
	v_fmac_f32_e32 v242, v239, v6
	v_fmac_f32_e32 v243, v239, v7
	v_cvt_pk_bf16_f32 v84, v242, v243
	v_lshlrev_b32_e32 v242, 16, v53
	v_and_b32_e32 v243, 0xffff0000, v53
	v_fmac_f32_e32 v242, v239, v8
	v_fmac_f32_e32 v243, v239, v9
	v_cvt_pk_bf16_f32 v85, v242, v243
	s_waitcnt vmcnt(5)
	v_lshlrev_b32_e32 v242, 16, v54
	v_and_b32_e32 v243, 0xffff0000, v54
	v_fmac_f32_e32 v242, v239, v10
	v_fmac_f32_e32 v243, v239, v11
	v_cvt_pk_bf16_f32 v86, v242, v243
	v_lshlrev_b32_e32 v242, 16, v55
	v_and_b32_e32 v243, 0xffff0000, v55
	v_fmac_f32_e32 v242, v239, v12
	v_fmac_f32_e32 v243, v239, v13
	v_cvt_pk_bf16_f32 v87, v242, v243
	s_waitcnt vmcnt(4)
	v_lshlrev_b32_e32 v242, 16, v56
	v_and_b32_e32 v243, 0xffff0000, v56
	v_fmac_f32_e32 v242, v239, v14
	v_fmac_f32_e32 v243, v239, v15
	v_cvt_pk_bf16_f32 v88, v242, v243
	v_lshlrev_b32_e32 v242, 16, v57
	v_and_b32_e32 v243, 0xffff0000, v57
	v_fmac_f32_e32 v242, v239, v16
	v_fmac_f32_e32 v243, v239, v17
	v_cvt_pk_bf16_f32 v89, v242, v243
	s_waitcnt vmcnt(3)
	v_lshlrev_b32_e32 v250, 16, v58
	v_and_b32_e32 v251, 0xffff0000, v58
	v_fmac_f32_e32 v250, v247, v18
	v_fmac_f32_e32 v251, v247, v19
	v_cvt_pk_bf16_f32 v90, v250, v251
	v_lshlrev_b32_e32 v250, 16, v59
	v_and_b32_e32 v251, 0xffff0000, v59
	v_fmac_f32_e32 v250, v247, v20
	v_fmac_f32_e32 v251, v247, v21
	v_cvt_pk_bf16_f32 v91, v250, v251
	s_waitcnt vmcnt(2)
	v_lshlrev_b32_e32 v250, 16, v60
	v_and_b32_e32 v251, 0xffff0000, v60
	v_fmac_f32_e32 v250, v247, v22
	v_fmac_f32_e32 v251, v247, v23
	v_cvt_pk_bf16_f32 v92, v250, v251
	v_lshlrev_b32_e32 v250, 16, v61
	v_and_b32_e32 v251, 0xffff0000, v61
	v_fmac_f32_e32 v250, v247, v24
	v_fmac_f32_e32 v251, v247, v25
	v_cvt_pk_bf16_f32 v93, v250, v251
	s_waitcnt vmcnt(1)
	v_lshlrev_b32_e32 v250, 16, v62
	v_and_b32_e32 v251, 0xffff0000, v62
	v_fmac_f32_e32 v250, v247, v26
	v_fmac_f32_e32 v251, v247, v27
	v_cvt_pk_bf16_f32 v94, v250, v251
	v_lshlrev_b32_e32 v250, 16, v63
	v_and_b32_e32 v251, 0xffff0000, v63
	v_fmac_f32_e32 v250, v247, v28
	v_fmac_f32_e32 v251, v247, v29
	v_cvt_pk_bf16_f32 v95, v250, v251
	s_waitcnt vmcnt(0)
	v_lshlrev_b32_e32 v250, 16, v64
	v_and_b32_e32 v251, 0xffff0000, v64
	v_fmac_f32_e32 v250, v247, v30
	v_fmac_f32_e32 v251, v247, v31
	v_cvt_pk_bf16_f32 v96, v250, v251
	v_lshlrev_b32_e32 v250, 16, v65
	v_and_b32_e32 v251, 0xffff0000, v65
	v_fmac_f32_e32 v250, v247, v32
	v_fmac_f32_e32 v251, v247, v33
	v_cvt_pk_bf16_f32 v97, v250, v251
	global_store_dwordx2 v72, v[82:83], s[14:15] offset:0
	global_store_dwordx2 v72, v[84:85], s[14:15] offset:32
	global_store_dwordx2 v72, v[86:87], s[14:15] offset:64
	global_store_dwordx2 v72, v[88:89], s[14:15] offset:96
	global_store_dwordx2 v73, v[90:91], s[14:15] offset:0
	global_store_dwordx2 v73, v[92:93], s[14:15] offset:32
	global_store_dwordx2 v73, v[94:95], s[14:15] offset:64
	global_store_dwordx2 v73, v[96:97], s[14:15] offset:96
	s_waitcnt vmcnt(0)
	s_add_i32 s54, s54, 1
	s_cmp_eq_u32 s54, 1
	s_cbranch_scc1 .Lnsa_mode_top
	v_cmp_gt_u32_e32 vcc, 0x44, v183
	s_nop 0
	s_and_saveexec_b64 s[20:21], vcc
	s_cbranch_execz .Lnsa_zskip_41
	v_lshlrev_b32_e32 v50, 2, v183
	v_add_u32_e32 v50, 0x1fc40, v50
	ds_write_b32 v50, v1
